# one rendezvous per phase in GEMM K-loops (leading half keeps post-MFMA barriers, trailing half pre-MFMA barriers), ALIGN barriers dropped
# baseline (speedup 1.0000x reference)
; #define LAS __attribute__((address_space(3)))
; __global__ void __launch_bounds__(512) mega_fwd(Args a_unused) {
;     ...
;     const int tid = threadIdx.x, lane = tid & 63, wave = __builtin_amdgcn_readfirstlane(tid >> 6), G = gridDim.x, bid = blockIdx.x;
;     KArgP kp = (KArgP)__builtin_amdgcn_kernarg_segment_ptr();
;     (void)a_unused;
;     volatile LAS unsigned* bst = (volatile LAS unsigned*)(lds + P_OFF + 8192);
;     if (tid == 0) { bst[0] = 0u; bst[1] = 0u; }
;     if (bid == 0) { unsigned* bw = (unsigned*)(kp->ws + S_BAR); for (int i = tid; i < XCD_BAR_WORDS; i += 512) __hip_atomic_store(bw + i, 0u, RLX_AGENT); }
.LBB0_2:
	s_or_b64 exec, exec, s[4:5]
	s_lshr_b32 s98, s2, 8
	s_cmp_lg_u32 s3, 0
	s_cbranch_scc1 .LBB0_6
	s_load_dwordx2 s[4:5], s[0:1], 0xe8
	v_lshlrev_b32_e32 v2, 2, v232
	v_mov_b32_e32 v3, 0
	v_add_u32_e32 v1, 0xfffffe00, v232
	s_mov_b64 s[6:7], 0x800
	s_waitcnt lgkmcnt(0)
	v_lshl_add_u64 v[4:5], s[4:5], 0, v[2:3]
	s_mov_b64 s[4:5], 0x2700000
	v_lshl_add_u64 v[4:5], v[4:5], 0, s[4:5]
	s_mov_b64 s[4:5], 0
	s_movk_i32 s8, 0xb7f

; #define PG8_STAGE(bufoff, gbase, voff) do { _Pragma("unroll") for (int _i = 0; _i < 2; ++_i) \
;         __builtin_amdgcn_global_load_lds((const unsigned*)((const char*)(gbase) + (voff)[_i]), (PG8_LAS unsigned*)(lds + (bufoff) + ldsw + _i * 8192), 16, 0, 0); } while (0)
; #define PG8_WAIT_V(n) asm volatile("s_waitcnt vmcnt(" #n ")" ::: "memory")
; #define PG8_BAR __builtin_amdgcn_s_barrier()
;     ...
;     for (int i = 0; i < 2; ++i) { int R, C; stage_rc(tid * 16 + i * 8192, R, C); const int Rb = Epi::PERM ? ((R & ~31) + perm32(R & 31)) : R;
;         voffA[i] = (unsigned)(R * lda_ + C) * 2u; voffB[i] = (unsigned)(Rb * K + C) * 2u; }
;     const size_t kstep = (size_t)(BK * 2);
;     const size_t hstepA = (size_t)HALF * lda_ * 2, hstepB = (size_t)HALF * K * 2;
;     const size_t tstepA = 2 * hstepA, tstepB = 2 * hstepB;
;     const unsigned ldsw = (unsigned)wid * 1024u;
;     const int aoff = lds_byte(wr * 64 + fr, fq * 8), boff = lds_byte(wc * 32 + fr, fq * 8);
;     ...
;         PG8_STAGE(PG8_SB(1, 0), cB + kstep, voffB); PG8_STAGE(PG8_SA(1, 0), cA + kstep, voffA); PG8_STAGE(PG8_SB(1, 1), cB + hstepB + kstep, voffB);
;         PG8_WAIT_V(6); PG8_BAR;
.LBB0_216:
	s_add_u32 s18, s8, 0x2800000
	s_addc_u32 s19, s9, 0
	s_add_u32 s20, s8, 0x2900000
	s_addc_u32 s21, s9, 0
	s_add_u32 s70, s8, 0x2c00000
	s_addc_u32 s71, s9, 0
	s_add_u32 s22, s8, 0x3200000
	s_addc_u32 s23, s9, 0
	s_add_u32 s24, s8, 0x1a800000
	s_addc_u32 s25, s9, 0
	s_add_u32 s72, s8, 0x1e800000
	s_mov_b64 s[26:27], 0x80
	s_addc_u32 s73, s9, 0
	s_and_b32 s40, s4, 3
	s_add_i32 m0, s61, 0x18000
	v_lshl_add_u64 v[6:7], v[6:7], 0, s[26:27]
	s_lshl_b32 s74, s5, 6
	s_lshl_b32 s37, s5, 13
	s_lshl_b32 s75, s40, 5
	s_lshl_b32 s38, s40, 12
	s_waitcnt vmcnt(2)
	s_barrier
	global_load_lds_dwordx4 v[6:7], off
	v_lshl_add_u64 v[4:5], v[4:5], 0, s[26:27]
	s_add_i32 m0, s61, 0x1a000
	s_add_i32 s76, s61, 0x8000
	s_add_i32 s77, s61, 0xa000
	global_load_lds_dwordx4 v[4:5], off
	v_lshl_add_u64 v[0:1], v[0:1], 0, s[26:27]
	s_mov_b32 m0, s76
	s_add_u32 s4, s34, 0x40080
	global_load_lds_dwordx4 v[0:1], off
	v_lshl_add_u64 v[0:1], v[2:3], 0, s[26:27]
	s_mov_b32 m0, s77
	s_addc_u32 s5, s35, 0
	global_load_lds_dwordx4 v[0:1], off
	s_add_i32 m0, s61, 0x1c000
	v_lshl_add_u64 v[0:1], s[4:5], 0, v[176:177]
	global_load_lds_dwordx4 v[0:1], off
	v_lshl_add_u64 v[0:1], s[4:5], 0, v[180:181]
	s_add_i32 m0, s61, 0x1e000
	s_movk_i32 s4, 0x3c0
	global_load_lds_dwordx4 v[0:1], off
	v_and_b32_e32 v0, 48, v8
	v_lshlrev_b32_e32 v1, 6, v8
	v_and_or_b32 v0, v1, s4, v0
	v_lshlrev_b32_e32 v1, 2, v8
	v_and_b32_e32 v1, 32, v1
	v_bitop3_b32 v2, v0, s37, v1 bitop3:0xde
	v_bitop3_b32 v199, v0, s38, v1 bitop3:0xde
	v_lshlrev_b32_e32 v0, 14, v9
	v_and_b32_e32 v0, 0xffff8000, v0
	v_lshl_add_u32 v0, v10, 11, v0
	v_and_b32_e32 v1, 1, v9
	v_lshl_or_b32 v0, v1, 6, v0
	s_cmpk_lt_u32 s36, 0x100
	v_lshl_add_u32 v184, v11, 1, v0
	v_lshlrev_b32_e32 v0, 14, v12
	s_cselect_b64 s[36:37], -1, 0
	s_cmp_lt_u32 s40, 2
	v_and_b32_e32 v0, 0xffff8000, v0
	s_cselect_b64 s[4:5], -1, 0
	s_add_u32 s38, s8, 0x1a800200
	v_lshl_add_u32 v0, v13, 11, v0
	v_and_b32_e32 v1, 1, v12
	s_waitcnt vmcnt(6)
	s_addc_u32 s39, s9, 0
	s_lshl_b32 s40, s40, 2
	v_lshl_or_b32 v0, v1, 6, v0
	s_add_i32 s78, s40, 0
	v_lshl_add_u32 v186, v14, 1, v0
	v_cndmask_b32_e64 v0, 0, 1, s[6:7]
	s_add_i32 s79, 0, 0x10000
	s_add_i32 s80, 0, 0x14000
	s_add_i32 s78, s78, 0x20000
	v_mov_b32_e32 v185, v183
	v_mov_b32_e32 v187, v183
	v_cmp_ne_u32_e64 s[6:7], 1, v0
	v_add_u32_e32 v201, s79, v199
	v_add_u32_e32 v205, s80, v199
	v_add_u32_e32 v207, 0, v2
	s_movk_i32 s81, 0x1800
	v_mov_b32_e32 v209, 0x358637bd
	s_mov_b32 s46, 0x3e0293ee
	s_mov_b64 s[48:49], 0x2c000
	s_mov_b32 s82, 0x2c000
	s_mov_b32 s84, 0x4800000
	v_mov_b64_e32 v[188:189], 0x1500
	s_cmp_lg_u32 s98, 0
	s_cbranch_scc1 .Lpg_x2_9
	s_barrier
.Lpg_x2_9:
	s_branch .LBB0_219
.LBB0_217:
	s_mov_b64 s[28:29], 0

; #define PG8_STAGE(bufoff, gbase, voff) do { _Pragma("unroll") for (int _i = 0; _i < 2; ++_i) \
;         __builtin_amdgcn_global_load_lds((const unsigned*)((const char*)(gbase) + (voff)[_i]), (PG8_LAS unsigned*)(lds + (bufoff) + ldsw + _i * 8192), 16, 0, 0); } while (0)
; #define PG8_LDA(dst, b, h) do { _Pragma("unroll") for (int m = 0; m < 4; ++m) _Pragma("unroll") for (int k = 0; k < 2; ++k) dst[m][k] = *(const PG8_LAS bf16x8*)(lds + PG8_SA(b, h) + aoff + m * 2048 + k * 1024); } while (0)
; #define PG8_LDB(dst, b, h) do { _Pragma("unroll") for (int n = 0; n < 2; ++n) _Pragma("unroll") for (int k = 0; k < 2; ++k) dst[n][k] = *(const PG8_LAS bf16x8*)(lds + PG8_SB(b, h) + boff + n * 2048 + k * 1024); } while (0)
; #define PG8_MMA(ai, bj, At, Bt) do { __builtin_amdgcn_s_setprio(1); _Pragma("unroll") for (int m = 0; m < 4; ++m) _Pragma("unroll") for (int n = 0; n < 2; ++n) _Pragma("unroll") for (int k = 0; k < 2; ++k) \
;         acc[ai][bj][m][n] = __builtin_amdgcn_mfma_f32_16x16x32_bf16(Bt[n][k], At[m][k], acc[ai][bj][m][n], 0, 0, 0); __builtin_amdgcn_s_setprio(0); } while (0)
; #define PG8_WAIT_V(n) asm volatile("s_waitcnt vmcnt(" #n ")" ::: "memory")
; #define PG8_WAIT_L(n) asm volatile("s_waitcnt lgkmcnt(" #n ")" ::: "memory")
; #define PG8_BAR __builtin_amdgcn_s_barrier()
; #define PG8_SCHED __builtin_amdgcn_sched_barrier(0)
;     ...
;             PG8_LDB(B0, 0, 0); PG8_LDB(B1, 0, 1); PG8_SCHED; PG8_LDA(At, 0, 0); PG8_STAGE(PG8_SA(1, 1), a1 + hstepA, voffA);
;             PG8_WAIT_V(8); PG8_WAIT_L(0); PG8_BAR; PG8_MMA(0, 0, At, B0); PG8_MMA(0, 1, At, B1); PG8_BAR; PG8_SCHED;
.LBB0_228:
	ds_read_b128 v[128:131], v201
	ds_read_b128 v[132:135], v201 offset:1024
	ds_read_b128 v[136:139], v201 offset:2048
	ds_read_b128 v[140:143], v201 offset:3072
	ds_read_b128 v[144:147], v205
	ds_read_b128 v[148:151], v205 offset:1024
	ds_read_b128 v[152:155], v205 offset:2048
	ds_read_b128 v[156:159], v205 offset:3072
	s_add_u32 s34, s28, 0xfffc0080
	s_addc_u32 s35, s29, -1
	s_cmp_eq_u32 s63, 12
	s_cselect_b32 s41, s42, s35
	s_cselect_b32 s40, s43, s34
	s_cselect_b32 s35, s44, s53
	s_cselect_b32 s34, s45, s51
	v_lshl_add_u64 v[192:193], s[28:29], 0, v[184:185]
	s_add_i32 m0, s61, 0xc000
	ds_read_b128 v[160:163], v207
	ds_read_b128 v[164:167], v207 offset:1024
	ds_read_b128 v[210:213], v207 offset:2048
	ds_read_b128 v[214:217], v207 offset:3072
	ds_read_b128 v[218:221], v207 offset:4096
	ds_read_b128 v[222:225], v207 offset:5120
	ds_read_b128 v[226:229], v207 offset:6144
	ds_read_b128 v[234:237], v207 offset:7168
	global_load_lds_dwordx4 v[192:193], off
	v_lshl_add_u64 v[192:193], s[28:29], 0, v[186:187]
	s_add_i32 m0, s61, 0xe000
	s_nop 0
	global_load_lds_dwordx4 v[192:193], off
	s_waitcnt vmcnt(8)
	s_waitcnt lgkmcnt(0)
	s_setprio 1
	s_cmp_lg_u32 s98, 0
	s_cbranch_scc0 .Lpg_b1_1
	s_barrier
	s_setprio 2
.Lpg_b1_1:
	s_waitcnt lgkmcnt(0)
	v_mfma_f32_16x16x32_bf16 v[124:127], v[128:131], v[160:163], v[124:127]
	v_mfma_f32_16x16x32_bf16 v[120:123], v[136:139], v[160:163], v[120:123]
	v_mfma_f32_16x16x32_bf16 v[108:111], v[128:131], v[210:213], v[108:111]
	v_mfma_f32_16x16x32_bf16 v[104:107], v[136:139], v[210:213], v[104:107]
	v_mfma_f32_16x16x32_bf16 v[92:95], v[128:131], v[218:221], v[92:95]
	v_mfma_f32_16x16x32_bf16 v[88:91], v[136:139], v[218:221], v[88:91]
	v_mfma_f32_16x16x32_bf16 v[76:79], v[128:131], v[226:229], v[76:79]
	v_mfma_f32_16x16x32_bf16 v[72:75], v[136:139], v[226:229], v[72:75]
	v_mfma_f32_16x16x32_bf16 v[124:127], v[132:135], v[164:167], v[124:127]
	v_mfma_f32_16x16x32_bf16 v[120:123], v[140:143], v[164:167], v[120:123]
	v_mfma_f32_16x16x32_bf16 v[108:111], v[132:135], v[214:217], v[108:111]
	v_mfma_f32_16x16x32_bf16 v[104:107], v[140:143], v[214:217], v[104:107]
	v_mfma_f32_16x16x32_bf16 v[92:95], v[132:135], v[222:225], v[92:95]
	v_mfma_f32_16x16x32_bf16 v[88:91], v[140:143], v[222:225], v[88:91]
	v_mfma_f32_16x16x32_bf16 v[76:79], v[132:135], v[234:237], v[76:79]
	v_mfma_f32_16x16x32_bf16 v[72:75], v[140:143], v[234:237], v[72:75]
	v_mfma_f32_16x16x32_bf16 v[116:119], v[144:147], v[160:163], v[116:119]
	v_mfma_f32_16x16x32_bf16 v[112:115], v[152:155], v[160:163], v[112:115]
	v_mfma_f32_16x16x32_bf16 v[100:103], v[144:147], v[210:213], v[100:103]
	v_mfma_f32_16x16x32_bf16 v[96:99], v[152:155], v[210:213], v[96:99]
	v_mfma_f32_16x16x32_bf16 v[84:87], v[144:147], v[218:221], v[84:87]
	v_mfma_f32_16x16x32_bf16 v[80:83], v[152:155], v[218:221], v[80:83]
	v_mfma_f32_16x16x32_bf16 v[68:71], v[144:147], v[226:229], v[68:71]
	v_mfma_f32_16x16x32_bf16 v[64:67], v[152:155], v[226:229], v[64:67]
	v_mfma_f32_16x16x32_bf16 v[116:119], v[148:151], v[164:167], v[116:119]
	v_mfma_f32_16x16x32_bf16 v[112:115], v[156:159], v[164:167], v[112:115]
	v_mfma_f32_16x16x32_bf16 v[100:103], v[148:151], v[214:217], v[100:103]
	v_mfma_f32_16x16x32_bf16 v[96:99], v[156:159], v[214:217], v[96:99]
	v_mfma_f32_16x16x32_bf16 v[84:87], v[148:151], v[222:225], v[84:87]
	v_mfma_f32_16x16x32_bf16 v[80:83], v[156:159], v[222:225], v[80:83]
	v_mfma_f32_16x16x32_bf16 v[68:71], v[148:151], v[234:237], v[68:71]
	v_mfma_f32_16x16x32_bf16 v[64:67], v[156:159], v[234:237], v[64:67]
	s_setprio 0
	s_cmp_lg_u32 s98, 0
	s_cbranch_scc1 .Lpg_b2_2
	s_barrier
; #define PG8_STAGE(bufoff, gbase, voff) do { _Pragma("unroll") for (int _i = 0; _i < 2; ++_i) \
;         __builtin_amdgcn_global_load_lds((const unsigned*)((const char*)(gbase) + (voff)[_i]), (PG8_LAS unsigned*)(lds + (bufoff) + ldsw + _i * 8192), 16, 0, 0); } while (0)
; #define PG8_LDA(dst, b, h) do { _Pragma("unroll") for (int m = 0; m < 4; ++m) _Pragma("unroll") for (int k = 0; k < 2; ++k) dst[m][k] = *(const PG8_LAS bf16x8*)(lds + PG8_SA(b, h) + aoff + m * 2048 + k * 1024); } while (0)
; #define PG8_LDB(dst, b, h) do { _Pragma("unroll") for (int n = 0; n < 2; ++n) _Pragma("unroll") for (int k = 0; k < 2; ++k) dst[n][k] = *(const PG8_LAS bf16x8*)(lds + PG8_SB(b, h) + boff + n * 2048 + k * 1024); } while (0)
; #define PG8_MMA(ai, bj, At, Bt) do { __builtin_amdgcn_s_setprio(1); _Pragma("unroll") for (int m = 0; m < 4; ++m) _Pragma("unroll") for (int n = 0; n < 2; ++n) _Pragma("unroll") for (int k = 0; k < 2; ++k) \
;         acc[ai][bj][m][n] = __builtin_amdgcn_mfma_f32_16x16x32_bf16(Bt[n][k], At[m][k], acc[ai][bj][m][n], 0, 0, 0); __builtin_amdgcn_s_setprio(0); } while (0)
; #define PG8_WAIT_V(n) asm volatile("s_waitcnt vmcnt(" #n ")" ::: "memory")
; #define PG8_WAIT_L(n) asm volatile("s_waitcnt lgkmcnt(" #n ")" ::: "memory")
; #define PG8_BAR __builtin_amdgcn_s_barrier()
; #define PG8_SCHED __builtin_amdgcn_sched_barrier(0)
;     ...
;             PG8_LDA(At, 0, 1); PG8_STAGE(PG8_SB(0, 0), b2, voffB); PG8_STAGE(PG8_SB(0, 1), b2 + hstepB, voffB); PG8_STAGE(PG8_SA(0, 0), a2, voffA);
;             PG8_WAIT_V(8); PG8_WAIT_L(0); PG8_BAR; PG8_MMA(1, 0, At, B0); PG8_MMA(1, 1, At, B1); PG8_BAR; PG8_SCHED;
;             PG8_LDB(B0, 1, 0); PG8_LDB(B1, 1, 1); PG8_SCHED; PG8_LDA(At, 1, 0); PG8_STAGE(PG8_SA(0, 1), a2 + hstepA, voffA);
;             PG8_WAIT_V(8); PG8_WAIT_L(0); PG8_BAR; PG8_MMA(0, 0, At, B0); PG8_MMA(0, 1, At, B1); PG8_BAR; PG8_SCHED;
.Lpg_b2_2:
	s_add_i32 s85, s79, s65
	v_lshl_add_u64 v[192:193], s[34:35], 0, v[176:177]
	s_mov_b32 m0, s85
	ds_read_b128 v[160:163], v207 offset:16384
	ds_read_b128 v[164:167], v207 offset:17408
	ds_read_b128 v[210:213], v207 offset:18432
	ds_read_b128 v[214:217], v207 offset:19456
	ds_read_b128 v[218:221], v207 offset:20480
	ds_read_b128 v[222:225], v207 offset:21504
	ds_read_b128 v[226:229], v207 offset:22528
	ds_read_b128 v[234:237], v207 offset:23552
	global_load_lds_dwordx4 v[192:193], off
	s_add_i32 m0, s85, 0x2000
	s_add_u32 s86, s34, 0x40000
	v_lshl_add_u64 v[202:203], s[34:35], 0, v[180:181]
	s_addc_u32 s87, s35, 0
	s_add_i32 s85, s80, s65
	global_load_lds_dwordx4 v[202:203], off
	v_lshl_add_u64 v[230:231], s[86:87], 0, v[176:177]
	s_mov_b32 m0, s85
	v_lshl_add_u64 v[238:239], s[40:41], 0, v[178:179]
	global_load_lds_dwordx4 v[230:231], off
	v_lshl_add_u64 v[230:231], s[86:87], 0, v[180:181]
	s_add_i32 m0, s85, 0x2000
	s_nop 0
	global_load_lds_dwordx4 v[230:231], off
	v_lshl_add_u64 v[230:231], s[40:41], 0, v[174:175]
	s_mov_b32 m0, s61
	s_nop 0
	global_load_lds_dwordx4 v[230:231], off
	s_mov_b32 m0, s66
	s_nop 0
	global_load_lds_dwordx4 v[238:239], off
	s_waitcnt vmcnt(8)
	s_waitcnt lgkmcnt(0)
	s_setprio 1
	s_cmp_lg_u32 s98, 0
	s_cbranch_scc0 .Lpg_b1_3
	s_barrier
	s_setprio 2
.Lpg_b1_3:
	s_waitcnt lgkmcnt(0)
	v_mfma_f32_16x16x32_bf16 v[60:63], v[128:131], v[160:163], v[60:63]
	v_mfma_f32_16x16x32_bf16 v[56:59], v[136:139], v[160:163], v[56:59]
	v_mfma_f32_16x16x32_bf16 v[44:47], v[128:131], v[210:213], v[44:47]
	v_mfma_f32_16x16x32_bf16 v[40:43], v[136:139], v[210:213], v[40:43]
	v_mfma_f32_16x16x32_bf16 v[28:31], v[128:131], v[218:221], v[28:31]
	v_mfma_f32_16x16x32_bf16 v[24:27], v[136:139], v[218:221], v[24:27]
	v_mfma_f32_16x16x32_bf16 v[12:15], v[128:131], v[226:229], v[12:15]
	v_mfma_f32_16x16x32_bf16 v[8:11], v[136:139], v[226:229], v[8:11]
	v_mfma_f32_16x16x32_bf16 v[60:63], v[132:135], v[164:167], v[60:63]
	v_mfma_f32_16x16x32_bf16 v[56:59], v[140:143], v[164:167], v[56:59]
	v_mfma_f32_16x16x32_bf16 v[44:47], v[132:135], v[214:217], v[44:47]
	v_mfma_f32_16x16x32_bf16 v[40:43], v[140:143], v[214:217], v[40:43]
	v_mfma_f32_16x16x32_bf16 v[28:31], v[132:135], v[222:225], v[28:31]
	v_mfma_f32_16x16x32_bf16 v[24:27], v[140:143], v[222:225], v[24:27]
	v_mfma_f32_16x16x32_bf16 v[12:15], v[132:135], v[234:237], v[12:15]
	v_mfma_f32_16x16x32_bf16 v[8:11], v[140:143], v[234:237], v[8:11]
	v_mfma_f32_16x16x32_bf16 v[52:55], v[144:147], v[160:163], v[52:55]
	v_mfma_f32_16x16x32_bf16 v[48:51], v[152:155], v[160:163], v[48:51]
	v_mfma_f32_16x16x32_bf16 v[36:39], v[144:147], v[210:213], v[36:39]
	v_mfma_f32_16x16x32_bf16 v[32:35], v[152:155], v[210:213], v[32:35]
	v_mfma_f32_16x16x32_bf16 v[20:23], v[144:147], v[218:221], v[20:23]
	v_mfma_f32_16x16x32_bf16 v[16:19], v[152:155], v[218:221], v[16:19]
	v_mfma_f32_16x16x32_bf16 v[4:7], v[144:147], v[226:229], v[4:7]
	v_mfma_f32_16x16x32_bf16 v[0:3], v[152:155], v[226:229], v[0:3]
	v_mfma_f32_16x16x32_bf16 v[52:55], v[148:151], v[164:167], v[52:55]
	v_mfma_f32_16x16x32_bf16 v[48:51], v[156:159], v[164:167], v[48:51]
	v_mfma_f32_16x16x32_bf16 v[36:39], v[148:151], v[214:217], v[36:39]
	v_mfma_f32_16x16x32_bf16 v[32:35], v[156:159], v[214:217], v[32:35]
	v_mfma_f32_16x16x32_bf16 v[20:23], v[148:151], v[222:225], v[20:23]
	v_mfma_f32_16x16x32_bf16 v[16:19], v[156:159], v[222:225], v[16:19]
	v_mfma_f32_16x16x32_bf16 v[4:7], v[148:151], v[234:237], v[4:7]
	v_mfma_f32_16x16x32_bf16 v[0:3], v[156:159], v[234:237], v[0:3]
	s_setprio 0
	s_cmp_lg_u32 s98, 0
	s_cbranch_scc1 .Lpg_b2_4
	s_barrier
.Lpg_b2_4:
	s_add_i32 s85, 0, 0x18000
	s_add_i32 s86, 0, 0x1c000
	v_add_u32_e32 v140, s85, v199
	v_add_u32_e32 v156, s86, v199
	ds_read_b128 v[128:131], v140
	ds_read_b128 v[132:135], v140 offset:1024
	ds_read_b128 v[136:139], v140 offset:2048
	ds_read_b128 v[140:143], v140 offset:3072
	ds_read_b128 v[144:147], v156
	ds_read_b128 v[148:151], v156 offset:1024
	ds_read_b128 v[152:155], v156 offset:2048
	ds_read_b128 v[156:159], v156 offset:3072
	s_add_u32 s40, s40, 0x40000
	s_addc_u32 s41, s41, 0
	s_mov_b32 m0, s67
	v_lshl_add_u64 v[240:241], s[40:41], 0, v[174:175]
	ds_read_b128 v[160:163], v207 offset:32768
	ds_read_b128 v[164:167], v207 offset:33792
	ds_read_b128 v[210:213], v207 offset:34816
	ds_read_b128 v[214:217], v207 offset:35840
	ds_read_b128 v[218:221], v207 offset:36864
	ds_read_b128 v[222:225], v207 offset:37888
	ds_read_b128 v[226:229], v207 offset:38912
	ds_read_b128 v[234:237], v207 offset:39936
	global_load_lds_dwordx4 v[240:241], off
	v_lshl_add_u64 v[240:241], s[40:41], 0, v[178:179]
	s_mov_b32 m0, s68
	s_nop 0
	global_load_lds_dwordx4 v[240:241], off
	s_waitcnt vmcnt(8)
	s_waitcnt lgkmcnt(0)
	s_setprio 1
	s_cmp_lg_u32 s98, 0
	s_cbranch_scc0 .Lpg_b1_5
	s_barrier
	s_setprio 2

; #define PG8_STAGE(bufoff, gbase, voff) do { _Pragma("unroll") for (int _i = 0; _i < 2; ++_i) \
;         __builtin_amdgcn_global_load_lds((const unsigned*)((const char*)(gbase) + (voff)[_i]), (PG8_LAS unsigned*)(lds + (bufoff) + ldsw + _i * 8192), 16, 0, 0); } while (0)
; #define PG8_LDA(dst, b, h) do { _Pragma("unroll") for (int m = 0; m < 4; ++m) _Pragma("unroll") for (int k = 0; k < 2; ++k) dst[m][k] = *(const PG8_LAS bf16x8*)(lds + PG8_SA(b, h) + aoff + m * 2048 + k * 1024); } while (0)
; #define PG8_MMA(ai, bj, At, Bt) do { __builtin_amdgcn_s_setprio(1); _Pragma("unroll") for (int m = 0; m < 4; ++m) _Pragma("unroll") for (int n = 0; n < 2; ++n) _Pragma("unroll") for (int k = 0; k < 2; ++k) \
;         acc[ai][bj][m][n] = __builtin_amdgcn_mfma_f32_16x16x32_bf16(Bt[n][k], At[m][k], acc[ai][bj][m][n], 0, 0, 0); __builtin_amdgcn_s_setprio(0); } while (0)
; #define PG8_WAIT_V(n) asm volatile("s_waitcnt vmcnt(" #n ")" ::: "memory")
; #define PG8_WAIT_L(n) asm volatile("s_waitcnt lgkmcnt(" #n ")" ::: "memory")
; #define PG8_BAR __builtin_amdgcn_s_barrier()
; #define PG8_SCHED __builtin_amdgcn_sched_barrier(0)
;     ...
;             PG8_LDA(At, 1, 1); PG8_STAGE(PG8_SB(1, 0), b3, voffB); PG8_STAGE(PG8_SB(1, 1), b3 + hstepB, voffB); PG8_STAGE(PG8_SA(1, 0), a3, voffA);
;             PG8_WAIT_V(8); PG8_WAIT_L(0); PG8_BAR; PG8_MMA(1, 0, At, B0); PG8_MMA(1, 1, At, B1); PG8_BAR; PG8_SCHED;
.Lpg_b2_6:
	s_add_i32 s40, s85, s65
	v_lshl_add_u64 v[192:193], v[192:193], 0, s[26:27]
	s_mov_b32 m0, s40
	ds_read_b128 v[160:163], v207 offset:49152
	ds_read_b128 v[164:167], v207 offset:50176
	ds_read_b128 v[210:213], v207 offset:51200
	ds_read_b128 v[214:217], v207 offset:52224
	ds_read_b128 v[218:221], v207 offset:53248
	ds_read_b128 v[222:225], v207 offset:54272
	ds_read_b128 v[226:229], v207 offset:55296
	ds_read_b128 v[234:237], v207 offset:56320
	global_load_lds_dwordx4 v[192:193], off
	s_add_i32 m0, s40, 0x2000
	s_add_u32 s34, s34, 0x40080
	v_lshl_add_u64 v[192:193], v[202:203], 0, s[26:27]
	s_addc_u32 s35, s35, 0
	s_add_i32 s40, s86, s65
	global_load_lds_dwordx4 v[192:193], off
	v_lshl_add_u64 v[192:193], s[34:35], 0, v[176:177]
	s_mov_b32 m0, s40
	s_nop 0
	global_load_lds_dwordx4 v[192:193], off
	v_lshl_add_u64 v[192:193], s[34:35], 0, v[180:181]
	s_add_i32 m0, s40, 0x2000
	s_nop 0
	global_load_lds_dwordx4 v[192:193], off
	v_lshl_add_u64 v[192:193], v[230:231], 0, s[26:27]
	s_mov_b32 m0, s76
	s_nop 0
	global_load_lds_dwordx4 v[192:193], off
	v_lshl_add_u64 v[192:193], v[238:239], 0, s[26:27]
	s_mov_b32 m0, s77
	s_nop 0
	global_load_lds_dwordx4 v[192:193], off
	s_waitcnt vmcnt(8)
	s_waitcnt lgkmcnt(0)
	s_setprio 1
	s_cmp_lg_u32 s98, 0
	s_cbranch_scc0 .Lpg_b1_7
	s_barrier
	s_setprio 2

; #define PG8_BAR __builtin_amdgcn_s_barrier()
;     ...
;         for (int t = 0; t < nt; t += 2) {
;             const bool last = (t == nt - 2);
;     ...
;         }
;         if constexpr (ALIGN_EPI) { if (wr == 0) PG8_BAR; }
.Lpg_b2_8:
	s_add_i32 s63, s63, 2
	s_add_u32 s28, s28, 0x100
	s_addc_u32 s29, s29, 0
	s_add_u32 s51, s51, 0x100
	s_addc_u32 s53, s53, 0
	s_cmp_gt_u32 s63, 13
	s_cbranch_scc0 .LBB0_228
	s_and_b64 vcc, exec, s[36:37]
	s_cbranch_vccz .LBB0_231

; #define PG8_BAR __builtin_amdgcn_s_barrier()
;     ...
;         if constexpr (!Epi::AFTER_DRAIN) { E(acc, cur, wr, wc, fr, fq); S.done(cur); }
;         if (!has_next) break;
; #pragma unroll
;         for (int a = 0; a < 2; ++a)
; #pragma unroll
;             for (int b = 0; b < 2; ++b)
; #pragma unroll
;                 for (int m = 0; m < 4; ++m)
; #pragma unroll
;                     for (int n = 0; n < 2; ++n) acc[a][b][m][n] = (f32x4){0.f, 0.f, 0.f, 0.f};
;         cur = nxt; cA = nA; cB = nB; ++ui;
;         if constexpr (ALIGN_EPI) { if (wr == 1) PG8_BAR; }
.LBB0_329:
	s_andn2_b64 vcc, exec, s[16:17]
	s_cbranch_vccnz .LBB0_217
	s_branch .LBB0_217

; #define PG8_STAGE(bufoff, gbase, voff) do { _Pragma("unroll") for (int _i = 0; _i < 2; ++_i) \
;         __builtin_amdgcn_global_load_lds((const unsigned*)((const char*)(gbase) + (voff)[_i]), (PG8_LAS unsigned*)(lds + (bufoff) + ldsw + _i * 8192), 16, 0, 0); } while (0)
; #define PG8_WAIT_V(n) asm volatile("s_waitcnt vmcnt(" #n ")" ::: "memory")
; #define PG8_BAR __builtin_amdgcn_s_barrier()
;     ...
;     for (int i = 0; i < 2; ++i) { int R, C; stage_rc(tid * 16 + i * 8192, R, C); const int Rb = Epi::PERM ? ((R & ~31) + perm32(R & 31)) : R;
;         voffA[i] = (unsigned)(R * lda_ + C) * 2u; voffB[i] = (unsigned)(Rb * K + C) * 2u; }
;     const size_t kstep = (size_t)(BK * 2);
;     const size_t hstepA = (size_t)HALF * lda_ * 2, hstepB = (size_t)HALF * K * 2;
;     const size_t tstepA = 2 * hstepA, tstepB = 2 * hstepB;
;     const unsigned ldsw = (unsigned)wid * 1024u;
;     const int aoff = lds_byte(wr * 64 + fr, fq * 8), boff = lds_byte(wc * 32 + fr, fq * 8);
;     ...
;         PG8_STAGE(PG8_SB(1, 0), cB + kstep, voffB); PG8_STAGE(PG8_SA(1, 0), cA + kstep, voffA); PG8_STAGE(PG8_SB(1, 1), cB + hstepB + kstep, voffB);
;         PG8_WAIT_V(6); PG8_BAR;
.LBB0_386:
	s_add_u32 s12, s4, 0x2840000
	s_addc_u32 s13, s5, 0
	s_add_u32 s14, s4, 0xd800000
	s_addc_u32 s15, s5, 0
	s_and_b32 s20, s16, 3
	s_lshl_b32 s56, s17, 6
	s_lshl_b32 s19, s17, 13
	s_mov_b64 s[16:17], 0x80
	s_add_i32 m0, s49, 0x18000
	v_lshl_add_u64 v[6:7], v[6:7], 0, s[16:17]
	s_lshl_b32 s57, s20, 5
	s_lshl_b32 s21, s20, 12
	s_waitcnt vmcnt(2)
	s_barrier
	global_load_lds_dwordx4 v[6:7], off
	v_lshl_add_u64 v[2:3], v[2:3], 0, s[16:17]
	s_add_i32 m0, s49, 0x1a000
	s_add_i32 s58, s49, 0x8000
	s_add_i32 s59, s49, 0xa000
	global_load_lds_dwordx4 v[2:3], off
	v_lshl_add_u64 v[0:1], v[0:1], 0, s[16:17]
	s_mov_b32 m0, s58
	s_add_u32 s4, s34, 0x40080
	global_load_lds_dwordx4 v[0:1], off
	v_lshl_add_u64 v[0:1], v[4:5], 0, s[16:17]
	s_mov_b32 m0, s59
	s_addc_u32 s5, s35, 0
	global_load_lds_dwordx4 v[0:1], off
	s_add_i32 m0, s49, 0x1c000
	v_lshl_add_u64 v[0:1], s[4:5], 0, v[138:139]
	global_load_lds_dwordx4 v[0:1], off
	v_lshl_add_u64 v[0:1], s[4:5], 0, v[142:143]
	s_add_i32 m0, s49, 0x1e000
	s_movk_i32 s4, 0x3c0
	global_load_lds_dwordx4 v[0:1], off
	v_and_b32_e32 v0, 48, v8
	v_lshlrev_b32_e32 v1, 6, v8
	v_and_or_b32 v0, v1, s4, v0
	v_lshlrev_b32_e32 v1, 2, v8
	v_and_b32_e32 v1, 32, v1
	v_bitop3_b32 v2, v0, s19, v1 bitop3:0xde
	v_bitop3_b32 v162, v0, s21, v1 bitop3:0xde
	v_lshlrev_b32_e32 v0, 14, v9
	v_and_b32_e32 v0, 0xffff8000, v0
	v_lshl_add_u32 v0, v10, 11, v0
	v_and_b32_e32 v1, 1, v9
	v_lshl_or_b32 v0, v1, 6, v0
	v_lshl_add_u32 v144, v11, 1, v0
	v_lshlrev_b32_e32 v0, 14, v12
	s_cmpk_lt_u32 s18, 0x100
	v_and_b32_e32 v0, 0xffff8000, v0
	s_waitcnt vmcnt(6)
	s_cselect_b64 s[18:19], -1, 0
	s_lshl_b32 s4, s20, 2
	v_lshl_add_u32 v0, v13, 11, v0
	v_and_b32_e32 v1, 1, v12
	s_add_i32 s61, s4, 0
	v_lshl_or_b32 v0, v1, 6, v0
	s_add_i32 s62, 0, 0x10000
	s_add_i32 s63, 0, 0x14000
	s_ashr_i32 s60, s42, 31
	s_add_i32 s61, s61, 0x20000
	v_mov_b32_e32 v145, v139
	v_lshl_add_u32 v146, v14, 1, v0
	v_mov_b32_e32 v147, v139
	v_mov_b64_e32 v[148:149], 0x80
	v_mov_b64_e32 v[150:151], 0x7f
	v_add_u32_e32 v163, s62, v162
	v_add_u32_e32 v164, s63, v162
	v_add_u32_e32 v165, 0, v2
	s_mov_b32 s64, 0x40000
	v_mov_b32_e32 v166, 0x358637bd
	s_mov_b64 s[20:21], 0x48000
	s_mov_b32 s65, 0x48000
	s_mov_b64 s[22:23], 0x50000
	s_mov_b32 s66, 0x50000
	s_mov_b64 s[24:25], 0x58000
	s_mov_b32 s67, 0x58000
	s_cmp_lg_u32 s98, 0
	s_cbranch_scc1 .Lpg_x2_18
	s_barrier
.Lpg_x2_18:
	s_branch .LBB0_389
.LBB0_387:
	s_mov_b64 s[4:5], 0

; #define PG8_STAGE(bufoff, gbase, voff) do { _Pragma("unroll") for (int _i = 0; _i < 2; ++_i) \
;         __builtin_amdgcn_global_load_lds((const unsigned*)((const char*)(gbase) + (voff)[_i]), (PG8_LAS unsigned*)(lds + (bufoff) + ldsw + _i * 8192), 16, 0, 0); } while (0)
; #define PG8_LDA(dst, b, h) do { _Pragma("unroll") for (int m = 0; m < 4; ++m) _Pragma("unroll") for (int k = 0; k < 2; ++k) dst[m][k] = *(const PG8_LAS bf16x8*)(lds + PG8_SA(b, h) + aoff + m * 2048 + k * 1024); } while (0)
; #define PG8_LDB(dst, b, h) do { _Pragma("unroll") for (int n = 0; n < 2; ++n) _Pragma("unroll") for (int k = 0; k < 2; ++k) dst[n][k] = *(const PG8_LAS bf16x8*)(lds + PG8_SB(b, h) + boff + n * 2048 + k * 1024); } while (0)
; #define PG8_MMA(ai, bj, At, Bt) do { __builtin_amdgcn_s_setprio(1); _Pragma("unroll") for (int m = 0; m < 4; ++m) _Pragma("unroll") for (int n = 0; n < 2; ++n) _Pragma("unroll") for (int k = 0; k < 2; ++k) \
;         acc[ai][bj][m][n] = __builtin_amdgcn_mfma_f32_16x16x32_bf16(Bt[n][k], At[m][k], acc[ai][bj][m][n], 0, 0, 0); __builtin_amdgcn_s_setprio(0); } while (0)
; #define PG8_WAIT_V(n) asm volatile("s_waitcnt vmcnt(" #n ")" ::: "memory")
; #define PG8_WAIT_L(n) asm volatile("s_waitcnt lgkmcnt(" #n ")" ::: "memory")
; #define PG8_BAR __builtin_amdgcn_s_barrier()
; #define PG8_SCHED __builtin_amdgcn_sched_barrier(0)
;     ...
;             PG8_LDB(B0, 0, 0); PG8_LDB(B1, 0, 1); PG8_SCHED; PG8_LDA(At, 0, 0); PG8_STAGE(PG8_SA(1, 1), a1 + hstepA, voffA);
;             PG8_WAIT_V(8); PG8_WAIT_L(0); PG8_BAR; PG8_MMA(0, 0, At, B0); PG8_MMA(0, 1, At, B1); PG8_BAR; PG8_SCHED;
.LBB0_396:
	ds_read_b128 v[128:131], v163
	ds_read_b128 v[132:135], v163 offset:1024
	ds_read_b128 v[152:155], v163 offset:2048
	ds_read_b128 v[156:159], v163 offset:3072
	ds_read_b128 v[168:171], v164
	ds_read_b128 v[172:175], v164 offset:1024
	ds_read_b128 v[176:179], v164 offset:2048
	ds_read_b128 v[180:183], v164 offset:3072
	s_add_u32 s34, s28, 0xfffc0080
	s_addc_u32 s35, s29, -1
	s_cmp_eq_u32 s72, 12
	s_cselect_b32 s41, s37, s35
	s_cselect_b32 s40, s68, s34
	s_cselect_b32 s35, s27, s71
	s_cselect_b32 s34, s69, s70
	v_lshl_add_u64 v[160:161], s[28:29], 0, v[144:145]
	s_add_i32 m0, s49, 0xc000
	ds_read_b128 v[184:187], v165
	ds_read_b128 v[188:191], v165 offset:1024
	ds_read_b128 v[192:195], v165 offset:2048
	ds_read_b128 v[196:199], v165 offset:3072
	ds_read_b128 v[200:203], v165 offset:4096
	ds_read_b128 v[204:207], v165 offset:5120
	ds_read_b128 v[208:211], v165 offset:6144
	ds_read_b128 v[212:215], v165 offset:7168
	global_load_lds_dwordx4 v[160:161], off
	v_lshl_add_u64 v[160:161], s[28:29], 0, v[146:147]
	s_add_i32 m0, s49, 0xe000
	s_nop 0
	global_load_lds_dwordx4 v[160:161], off
	s_waitcnt vmcnt(8)
	s_waitcnt lgkmcnt(0)
	s_setprio 1
	s_cmp_lg_u32 s98, 0
	s_cbranch_scc0 .Lpg_b1_10
	s_barrier
	s_setprio 2
.Lpg_b1_10:
	s_waitcnt lgkmcnt(0)
	v_mfma_f32_16x16x32_bf16 v[124:127], v[128:131], v[184:187], v[124:127]
	v_mfma_f32_16x16x32_bf16 v[120:123], v[152:155], v[184:187], v[120:123]
	v_mfma_f32_16x16x32_bf16 v[108:111], v[128:131], v[192:195], v[108:111]
	v_mfma_f32_16x16x32_bf16 v[104:107], v[152:155], v[192:195], v[104:107]
	v_mfma_f32_16x16x32_bf16 v[92:95], v[128:131], v[200:203], v[92:95]
	v_mfma_f32_16x16x32_bf16 v[88:91], v[152:155], v[200:203], v[88:91]
	v_mfma_f32_16x16x32_bf16 v[76:79], v[128:131], v[208:211], v[76:79]
	v_mfma_f32_16x16x32_bf16 v[72:75], v[152:155], v[208:211], v[72:75]
	v_mfma_f32_16x16x32_bf16 v[124:127], v[132:135], v[188:191], v[124:127]
	v_mfma_f32_16x16x32_bf16 v[120:123], v[156:159], v[188:191], v[120:123]
	v_mfma_f32_16x16x32_bf16 v[108:111], v[132:135], v[196:199], v[108:111]
	v_mfma_f32_16x16x32_bf16 v[104:107], v[156:159], v[196:199], v[104:107]
	v_mfma_f32_16x16x32_bf16 v[92:95], v[132:135], v[204:207], v[92:95]
	v_mfma_f32_16x16x32_bf16 v[88:91], v[156:159], v[204:207], v[88:91]
	v_mfma_f32_16x16x32_bf16 v[76:79], v[132:135], v[212:215], v[76:79]
	v_mfma_f32_16x16x32_bf16 v[72:75], v[156:159], v[212:215], v[72:75]
	v_mfma_f32_16x16x32_bf16 v[116:119], v[168:171], v[184:187], v[116:119]
	v_mfma_f32_16x16x32_bf16 v[112:115], v[176:179], v[184:187], v[112:115]
	v_mfma_f32_16x16x32_bf16 v[100:103], v[168:171], v[192:195], v[100:103]
	v_mfma_f32_16x16x32_bf16 v[96:99], v[176:179], v[192:195], v[96:99]
	v_mfma_f32_16x16x32_bf16 v[84:87], v[168:171], v[200:203], v[84:87]
	v_mfma_f32_16x16x32_bf16 v[80:83], v[176:179], v[200:203], v[80:83]
	v_mfma_f32_16x16x32_bf16 v[68:71], v[168:171], v[208:211], v[68:71]
	v_mfma_f32_16x16x32_bf16 v[64:67], v[176:179], v[208:211], v[64:67]
	v_mfma_f32_16x16x32_bf16 v[116:119], v[172:175], v[188:191], v[116:119]
	v_mfma_f32_16x16x32_bf16 v[112:115], v[180:183], v[188:191], v[112:115]
	v_mfma_f32_16x16x32_bf16 v[100:103], v[172:175], v[196:199], v[100:103]
	v_mfma_f32_16x16x32_bf16 v[96:99], v[180:183], v[196:199], v[96:99]
	v_mfma_f32_16x16x32_bf16 v[84:87], v[172:175], v[204:207], v[84:87]
	v_mfma_f32_16x16x32_bf16 v[80:83], v[180:183], v[204:207], v[80:83]
	v_mfma_f32_16x16x32_bf16 v[68:71], v[172:175], v[212:215], v[68:71]
	v_mfma_f32_16x16x32_bf16 v[64:67], v[180:183], v[212:215], v[64:67]
	s_setprio 0
	s_cmp_lg_u32 s98, 0
	s_cbranch_scc1 .Lpg_b2_11
	s_barrier
; #define PG8_STAGE(bufoff, gbase, voff) do { _Pragma("unroll") for (int _i = 0; _i < 2; ++_i) \
;         __builtin_amdgcn_global_load_lds((const unsigned*)((const char*)(gbase) + (voff)[_i]), (PG8_LAS unsigned*)(lds + (bufoff) + ldsw + _i * 8192), 16, 0, 0); } while (0)
; #define PG8_LDA(dst, b, h) do { _Pragma("unroll") for (int m = 0; m < 4; ++m) _Pragma("unroll") for (int k = 0; k < 2; ++k) dst[m][k] = *(const PG8_LAS bf16x8*)(lds + PG8_SA(b, h) + aoff + m * 2048 + k * 1024); } while (0)
; #define PG8_LDB(dst, b, h) do { _Pragma("unroll") for (int n = 0; n < 2; ++n) _Pragma("unroll") for (int k = 0; k < 2; ++k) dst[n][k] = *(const PG8_LAS bf16x8*)(lds + PG8_SB(b, h) + boff + n * 2048 + k * 1024); } while (0)
; #define PG8_MMA(ai, bj, At, Bt) do { __builtin_amdgcn_s_setprio(1); _Pragma("unroll") for (int m = 0; m < 4; ++m) _Pragma("unroll") for (int n = 0; n < 2; ++n) _Pragma("unroll") for (int k = 0; k < 2; ++k) \
;         acc[ai][bj][m][n] = __builtin_amdgcn_mfma_f32_16x16x32_bf16(Bt[n][k], At[m][k], acc[ai][bj][m][n], 0, 0, 0); __builtin_amdgcn_s_setprio(0); } while (0)
; #define PG8_WAIT_V(n) asm volatile("s_waitcnt vmcnt(" #n ")" ::: "memory")
; #define PG8_WAIT_L(n) asm volatile("s_waitcnt lgkmcnt(" #n ")" ::: "memory")
; #define PG8_BAR __builtin_amdgcn_s_barrier()
; #define PG8_SCHED __builtin_amdgcn_sched_barrier(0)
;     ...
;             PG8_LDA(At, 0, 1); PG8_STAGE(PG8_SB(0, 0), b2, voffB); PG8_STAGE(PG8_SB(0, 1), b2 + hstepB, voffB); PG8_STAGE(PG8_SA(0, 0), a2, voffA);
;             PG8_WAIT_V(8); PG8_WAIT_L(0); PG8_BAR; PG8_MMA(1, 0, At, B0); PG8_MMA(1, 1, At, B1); PG8_BAR; PG8_SCHED;
;             PG8_LDB(B0, 1, 0); PG8_LDB(B1, 1, 1); PG8_SCHED; PG8_LDA(At, 1, 0); PG8_STAGE(PG8_SA(0, 1), a2 + hstepA, voffA);
;             PG8_WAIT_V(8); PG8_WAIT_L(0); PG8_BAR; PG8_MMA(0, 0, At, B0); PG8_MMA(0, 1, At, B1); PG8_BAR; PG8_SCHED;
.Lpg_b2_11:
	s_add_i32 s73, s62, s52
	v_lshl_add_u64 v[160:161], s[34:35], 0, v[138:139]
	s_mov_b32 m0, s73
	ds_read_b128 v[184:187], v165 offset:16384
	ds_read_b128 v[188:191], v165 offset:17408
	ds_read_b128 v[192:195], v165 offset:18432
	ds_read_b128 v[196:199], v165 offset:19456
	ds_read_b128 v[200:203], v165 offset:20480
	ds_read_b128 v[204:207], v165 offset:21504
	ds_read_b128 v[208:211], v165 offset:22528
	ds_read_b128 v[212:215], v165 offset:23552
	global_load_lds_dwordx4 v[160:161], off
	s_add_i32 m0, s73, 0x2000
	s_add_u32 s74, s34, 0x40000
	v_lshl_add_u64 v[216:217], s[34:35], 0, v[142:143]
	s_addc_u32 s75, s35, 0
	s_add_i32 s73, s63, s52
	global_load_lds_dwordx4 v[216:217], off
	v_lshl_add_u64 v[218:219], s[74:75], 0, v[138:139]
	s_mov_b32 m0, s73
	v_lshl_add_u64 v[220:221], s[40:41], 0, v[140:141]
	global_load_lds_dwordx4 v[218:219], off
	v_lshl_add_u64 v[218:219], s[74:75], 0, v[142:143]
	s_add_i32 m0, s73, 0x2000
	s_nop 0
	global_load_lds_dwordx4 v[218:219], off
	v_lshl_add_u64 v[218:219], s[40:41], 0, v[136:137]
	s_mov_b32 m0, s49
	s_nop 0
	global_load_lds_dwordx4 v[218:219], off
	s_mov_b32 m0, s51
	s_nop 0
	global_load_lds_dwordx4 v[220:221], off
	s_waitcnt vmcnt(8)
	s_waitcnt lgkmcnt(0)
	s_setprio 1
	s_cmp_lg_u32 s98, 0
	s_cbranch_scc0 .Lpg_b1_12
	s_barrier
	s_setprio 2
.Lpg_b1_12:
	s_waitcnt lgkmcnt(0)
	v_mfma_f32_16x16x32_bf16 v[60:63], v[128:131], v[184:187], v[60:63]
	v_mfma_f32_16x16x32_bf16 v[56:59], v[152:155], v[184:187], v[56:59]
	v_mfma_f32_16x16x32_bf16 v[44:47], v[128:131], v[192:195], v[44:47]
	v_mfma_f32_16x16x32_bf16 v[40:43], v[152:155], v[192:195], v[40:43]
	v_mfma_f32_16x16x32_bf16 v[28:31], v[128:131], v[200:203], v[28:31]
	v_mfma_f32_16x16x32_bf16 v[24:27], v[152:155], v[200:203], v[24:27]
	v_mfma_f32_16x16x32_bf16 v[12:15], v[128:131], v[208:211], v[12:15]
	v_mfma_f32_16x16x32_bf16 v[8:11], v[152:155], v[208:211], v[8:11]
	v_mfma_f32_16x16x32_bf16 v[60:63], v[132:135], v[188:191], v[60:63]
	v_mfma_f32_16x16x32_bf16 v[56:59], v[156:159], v[188:191], v[56:59]
	v_mfma_f32_16x16x32_bf16 v[44:47], v[132:135], v[196:199], v[44:47]
	v_mfma_f32_16x16x32_bf16 v[40:43], v[156:159], v[196:199], v[40:43]
	v_mfma_f32_16x16x32_bf16 v[28:31], v[132:135], v[204:207], v[28:31]
	v_mfma_f32_16x16x32_bf16 v[24:27], v[156:159], v[204:207], v[24:27]
	v_mfma_f32_16x16x32_bf16 v[12:15], v[132:135], v[212:215], v[12:15]
	v_mfma_f32_16x16x32_bf16 v[8:11], v[156:159], v[212:215], v[8:11]
	v_mfma_f32_16x16x32_bf16 v[52:55], v[168:171], v[184:187], v[52:55]
	v_mfma_f32_16x16x32_bf16 v[48:51], v[176:179], v[184:187], v[48:51]
	v_mfma_f32_16x16x32_bf16 v[36:39], v[168:171], v[192:195], v[36:39]
	v_mfma_f32_16x16x32_bf16 v[32:35], v[176:179], v[192:195], v[32:35]
	v_mfma_f32_16x16x32_bf16 v[20:23], v[168:171], v[200:203], v[20:23]
	v_mfma_f32_16x16x32_bf16 v[16:19], v[176:179], v[200:203], v[16:19]
	v_mfma_f32_16x16x32_bf16 v[4:7], v[168:171], v[208:211], v[4:7]
	v_mfma_f32_16x16x32_bf16 v[0:3], v[176:179], v[208:211], v[0:3]
	v_mfma_f32_16x16x32_bf16 v[52:55], v[172:175], v[188:191], v[52:55]
	v_mfma_f32_16x16x32_bf16 v[48:51], v[180:183], v[188:191], v[48:51]
	v_mfma_f32_16x16x32_bf16 v[36:39], v[172:175], v[196:199], v[36:39]
	v_mfma_f32_16x16x32_bf16 v[32:35], v[180:183], v[196:199], v[32:35]
	v_mfma_f32_16x16x32_bf16 v[20:23], v[172:175], v[204:207], v[20:23]
	v_mfma_f32_16x16x32_bf16 v[16:19], v[180:183], v[204:207], v[16:19]
	v_mfma_f32_16x16x32_bf16 v[4:7], v[172:175], v[212:215], v[4:7]
	v_mfma_f32_16x16x32_bf16 v[0:3], v[180:183], v[212:215], v[0:3]
	s_setprio 0
	s_cmp_lg_u32 s98, 0
	s_cbranch_scc1 .Lpg_b2_13
	s_barrier
.Lpg_b2_13:
	s_add_i32 s73, 0, 0x18000
	s_add_i32 s74, 0, 0x1c000
	v_add_u32_e32 v156, s73, v162
	v_add_u32_e32 v167, s74, v162
	ds_read_b128 v[128:131], v156
	ds_read_b128 v[132:135], v156 offset:1024
	ds_read_b128 v[152:155], v156 offset:2048
	ds_read_b128 v[156:159], v156 offset:3072
	ds_read_b128 v[168:171], v167
	ds_read_b128 v[172:175], v167 offset:1024
	ds_read_b128 v[176:179], v167 offset:2048
	ds_read_b128 v[180:183], v167 offset:3072
	s_add_u32 s40, s40, 0x40000
	s_addc_u32 s41, s41, 0
	s_mov_b32 m0, s53
	v_lshl_add_u64 v[222:223], s[40:41], 0, v[136:137]
	ds_read_b128 v[184:187], v165 offset:32768
	ds_read_b128 v[188:191], v165 offset:33792
	ds_read_b128 v[192:195], v165 offset:34816
	ds_read_b128 v[196:199], v165 offset:35840
	ds_read_b128 v[200:203], v165 offset:36864
	ds_read_b128 v[204:207], v165 offset:37888
	ds_read_b128 v[208:211], v165 offset:38912
	ds_read_b128 v[212:215], v165 offset:39936
	global_load_lds_dwordx4 v[222:223], off
	v_lshl_add_u64 v[222:223], s[40:41], 0, v[140:141]
	s_mov_b32 m0, s54
	s_nop 0
	global_load_lds_dwordx4 v[222:223], off
	s_waitcnt vmcnt(8)
	s_waitcnt lgkmcnt(0)
	s_setprio 1
	s_cmp_lg_u32 s98, 0
	s_cbranch_scc0 .Lpg_b1_14
	s_barrier
	s_setprio 2

; #define PG8_STAGE(bufoff, gbase, voff) do { _Pragma("unroll") for (int _i = 0; _i < 2; ++_i) \
;         __builtin_amdgcn_global_load_lds((const unsigned*)((const char*)(gbase) + (voff)[_i]), (PG8_LAS unsigned*)(lds + (bufoff) + ldsw + _i * 8192), 16, 0, 0); } while (0)
; #define PG8_LDA(dst, b, h) do { _Pragma("unroll") for (int m = 0; m < 4; ++m) _Pragma("unroll") for (int k = 0; k < 2; ++k) dst[m][k] = *(const PG8_LAS bf16x8*)(lds + PG8_SA(b, h) + aoff + m * 2048 + k * 1024); } while (0)
; #define PG8_MMA(ai, bj, At, Bt) do { __builtin_amdgcn_s_setprio(1); _Pragma("unroll") for (int m = 0; m < 4; ++m) _Pragma("unroll") for (int n = 0; n < 2; ++n) _Pragma("unroll") for (int k = 0; k < 2; ++k) \
;         acc[ai][bj][m][n] = __builtin_amdgcn_mfma_f32_16x16x32_bf16(Bt[n][k], At[m][k], acc[ai][bj][m][n], 0, 0, 0); __builtin_amdgcn_s_setprio(0); } while (0)
; #define PG8_WAIT_V(n) asm volatile("s_waitcnt vmcnt(" #n ")" ::: "memory")
; #define PG8_WAIT_L(n) asm volatile("s_waitcnt lgkmcnt(" #n ")" ::: "memory")
; #define PG8_BAR __builtin_amdgcn_s_barrier()
; #define PG8_SCHED __builtin_amdgcn_sched_barrier(0)
;     ...
;             PG8_LDA(At, 1, 1); PG8_STAGE(PG8_SB(1, 0), b3, voffB); PG8_STAGE(PG8_SB(1, 1), b3 + hstepB, voffB); PG8_STAGE(PG8_SA(1, 0), a3, voffA);
;             PG8_WAIT_V(8); PG8_WAIT_L(0); PG8_BAR; PG8_MMA(1, 0, At, B0); PG8_MMA(1, 1, At, B1); PG8_BAR; PG8_SCHED;
.Lpg_b2_15:
	s_add_i32 s40, s73, s52
	v_lshl_add_u64 v[160:161], v[160:161], 0, s[16:17]
	s_mov_b32 m0, s40
	ds_read_b128 v[184:187], v165 offset:49152
	ds_read_b128 v[188:191], v165 offset:50176
	ds_read_b128 v[192:195], v165 offset:51200
	ds_read_b128 v[196:199], v165 offset:52224
	ds_read_b128 v[200:203], v165 offset:53248
	ds_read_b128 v[204:207], v165 offset:54272
	ds_read_b128 v[208:211], v165 offset:55296
	ds_read_b128 v[212:215], v165 offset:56320
	global_load_lds_dwordx4 v[160:161], off
	s_add_i32 m0, s40, 0x2000
	s_add_u32 s34, s34, 0x40080
	v_lshl_add_u64 v[160:161], v[216:217], 0, s[16:17]
	s_addc_u32 s35, s35, 0
	s_add_i32 s40, s74, s52
	global_load_lds_dwordx4 v[160:161], off
	v_lshl_add_u64 v[160:161], s[34:35], 0, v[138:139]
	s_mov_b32 m0, s40
	s_nop 0
	global_load_lds_dwordx4 v[160:161], off
	v_lshl_add_u64 v[160:161], s[34:35], 0, v[142:143]
	s_add_i32 m0, s40, 0x2000
	s_nop 0
	global_load_lds_dwordx4 v[160:161], off
	v_lshl_add_u64 v[160:161], v[218:219], 0, s[16:17]
	s_mov_b32 m0, s58
	s_nop 0
	global_load_lds_dwordx4 v[160:161], off
	v_lshl_add_u64 v[160:161], v[220:221], 0, s[16:17]
	s_mov_b32 m0, s59
	s_nop 0
	global_load_lds_dwordx4 v[160:161], off
	s_waitcnt vmcnt(8)
	s_waitcnt lgkmcnt(0)
	s_setprio 1
	s_cmp_lg_u32 s98, 0
	s_cbranch_scc0 .Lpg_b1_16
	s_barrier
	s_setprio 2

; #define PG8_BAR __builtin_amdgcn_s_barrier()
;     ...
;         for (int t = 0; t < nt; t += 2) {
;             const bool last = (t == nt - 2);
;     ...
;         }
;         if constexpr (ALIGN_EPI) { if (wr == 0) PG8_BAR; }
.Lpg_b2_17:
	s_add_i32 s72, s72, 2
	s_add_u32 s28, s28, 0x100
	s_addc_u32 s29, s29, 0
	s_add_u32 s70, s70, 0x100
	s_addc_u32 s71, s71, 0
	s_cmp_gt_u32 s72, 13
	s_cbranch_scc0 .LBB0_396
	s_and_b64 vcc, exec, s[18:19]
	s_cbranch_vccz .LBB0_399

; #define PG8_BAR __builtin_amdgcn_s_barrier()
;     ...
;         if constexpr (!Epi::AFTER_DRAIN) { E(acc, cur, wr, wc, fr, fq); S.done(cur); }
;         if (!has_next) break;
; #pragma unroll
;         for (int a = 0; a < 2; ++a)
; #pragma unroll
;             for (int b = 0; b < 2; ++b)
; #pragma unroll
;                 for (int m = 0; m < 4; ++m)
; #pragma unroll
;                     for (int n = 0; n < 2; ++n) acc[a][b][m][n] = (f32x4){0.f, 0.f, 0.f, 0.f};
;         cur = nxt; cA = nA; cB = nB; ++ui;
;         if constexpr (ALIGN_EPI) { if (wr == 1) PG8_BAR; }
.LBB0_436:
	s_andn2_b64 vcc, exec, s[10:11]
	s_cbranch_vccnz .LBB0_387
	s_branch .LBB0_387

; #define PG8_STAGE(bufoff, gbase, voff) do { _Pragma("unroll") for (int _i = 0; _i < 2; ++_i) \
;         __builtin_amdgcn_global_load_lds((const unsigned*)((const char*)(gbase) + (voff)[_i]), (PG8_LAS unsigned*)(lds + (bufoff) + ldsw + _i * 8192), 16, 0, 0); } while (0)
; #define PG8_WAIT_V(n) asm volatile("s_waitcnt vmcnt(" #n ")" ::: "memory")
; #define PG8_BAR __builtin_amdgcn_s_barrier()
;     ...
;     for (int i = 0; i < 2; ++i) { int R, C; stage_rc(tid * 16 + i * 8192, R, C); const int Rb = Epi::PERM ? ((R & ~31) + perm32(R & 31)) : R;
;         voffA[i] = (unsigned)(R * lda_ + C) * 2u; voffB[i] = (unsigned)(Rb * K + C) * 2u; }
;     const size_t kstep = (size_t)(BK * 2);
;     const size_t hstepA = (size_t)HALF * lda_ * 2, hstepB = (size_t)HALF * K * 2;
;     const size_t tstepA = 2 * hstepA, tstepB = 2 * hstepB;
;     const unsigned ldsw = (unsigned)wid * 1024u;
;     const int aoff = lds_byte(wr * 64 + fr, fq * 8), boff = lds_byte(wc * 32 + fr, fq * 8);
;     ...
;         PG8_STAGE(PG8_SB(1, 0), cB + kstep, voffB); PG8_STAGE(PG8_SA(1, 0), cA + kstep, voffA); PG8_STAGE(PG8_SB(1, 1), cB + hstepB + kstep, voffB);
;         PG8_WAIT_V(6); PG8_BAR;
.LBB0_624:
	s_add_u32 s16, s0, 0x2900000
	s_addc_u32 s17, s1, 0
	s_add_u32 s18, s0, 0x3200000
	s_addc_u32 s19, s1, 0
	s_add_u32 s47, s0, 0xe800000
	s_addc_u32 s52, s1, 0
	v_and_b32_e32 v16, 48, v1
	v_lshlrev_b32_e32 v17, 6, v1
	s_movk_i32 s1, 0x3c0
	v_lshlrev_b32_e32 v1, 2, v1
	s_and_b32 s7, s7, 3
	s_lshl_b32 s0, s6, 13
	v_and_or_b32 v16, v17, s1, v16
	v_and_b32_e32 v1, 32, v1
	s_add_i32 m0, s43, 0x18000
	v_lshl_add_u64 v[8:9], v[8:9], 0, s[66:67]
	s_lshl_b32 s53, s6, 6
	v_bitop3_b32 v17, v16, s0, v1 bitop3:0xde
	s_lshl_b32 s54, s7, 5
	s_lshl_b32 s0, s7, 12
	s_waitcnt vmcnt(2)
	s_barrier
	global_load_lds_dwordx4 v[8:9], off
	v_lshl_add_u64 v[6:7], v[6:7], 0, s[66:67]
	s_add_i32 m0, s43, 0x1a000
	s_add_i32 s55, s43, 0x8000
	s_add_i32 s56, s43, 0xa000
	v_bitop3_b32 v1, v16, s0, v1 bitop3:0xde
	global_load_lds_dwordx4 v[6:7], off
	v_lshl_add_u64 v[2:3], v[2:3], 0, s[66:67]
	s_mov_b32 m0, s55
	s_add_u32 s0, s28, 0x18080
	global_load_lds_dwordx4 v[2:3], off
	v_lshl_add_u64 v[2:3], v[4:5], 0, s[66:67]
	s_mov_b32 m0, s56
	s_addc_u32 s1, s29, 0
	global_load_lds_dwordx4 v[2:3], off
	s_add_i32 m0, s43, 0x1c000
	v_lshl_add_u64 v[2:3], s[0:1], 0, v[166:167]
	global_load_lds_dwordx4 v[2:3], off
	v_lshl_add_u64 v[2:3], s[0:1], 0, v[162:163]
	s_add_i32 m0, s43, 0x1e000
	s_cmpk_lt_u32 s2, 0x100
	global_load_lds_dwordx4 v[2:3], off
	v_lshlrev_b32_e32 v2, 13, v14
	v_and_b32_e32 v2, 0xffffc000, v2
	v_lshl_add_u32 v2, v13, 10, v2
	v_and_b32_e32 v3, 1, v14
	v_lshl_or_b32 v2, v3, 6, v2
	v_lshl_add_u32 v170, v15, 1, v2
	v_lshlrev_b32_e32 v2, 13, v10
	s_cselect_b64 s[20:21], -1, 0
	s_cmp_lt_u32 s7, 2
	v_and_b32_e32 v2, 0xffffc000, v2
	s_waitcnt vmcnt(6)
	s_cselect_b64 s[0:1], -1, 0
	s_lshl_b32 s2, s7, 2
	v_lshl_add_u32 v2, v11, 10, v2
	v_and_b32_e32 v3, 1, v10
	s_add_i32 s57, s2, 0
	v_lshl_or_b32 v2, v3, 6, v2
	v_readlane_b32 s6, v253, 25
	s_add_i32 s57, s57, 0x20000
	v_mov_b32_e32 v171, v0
	v_lshl_add_u32 v172, v12, 1, v2
	v_mov_b32_e32 v173, v0
	s_mov_b32 s58, 0
	v_add_u32_e32 v190, 0, v17
	v_readlane_b32 s2, v253, 23
	s_mov_b32 s36, s6
	s_cmp_lg_u32 s98, 0
	s_cbranch_scc1 .Lpg_x2_27
	s_barrier
.Lpg_x2_27:
	v_readlane_b32 s7, v253, 26
	s_branch .LBB0_627

; #define PG8_STAGE(bufoff, gbase, voff) do { _Pragma("unroll") for (int _i = 0; _i < 2; ++_i) \
;         __builtin_amdgcn_global_load_lds((const unsigned*)((const char*)(gbase) + (voff)[_i]), (PG8_LAS unsigned*)(lds + (bufoff) + ldsw + _i * 8192), 16, 0, 0); } while (0)
; #define PG8_LDA(dst, b, h) do { _Pragma("unroll") for (int m = 0; m < 4; ++m) _Pragma("unroll") for (int k = 0; k < 2; ++k) dst[m][k] = *(const PG8_LAS bf16x8*)(lds + PG8_SA(b, h) + aoff + m * 2048 + k * 1024); } while (0)
; #define PG8_LDB(dst, b, h) do { _Pragma("unroll") for (int n = 0; n < 2; ++n) _Pragma("unroll") for (int k = 0; k < 2; ++k) dst[n][k] = *(const PG8_LAS bf16x8*)(lds + PG8_SB(b, h) + boff + n * 2048 + k * 1024); } while (0)
; #define PG8_MMA(ai, bj, At, Bt) do { __builtin_amdgcn_s_setprio(1); _Pragma("unroll") for (int m = 0; m < 4; ++m) _Pragma("unroll") for (int n = 0; n < 2; ++n) _Pragma("unroll") for (int k = 0; k < 2; ++k) \
;         acc[ai][bj][m][n] = __builtin_amdgcn_mfma_f32_16x16x32_bf16(Bt[n][k], At[m][k], acc[ai][bj][m][n], 0, 0, 0); __builtin_amdgcn_s_setprio(0); } while (0)
; #define PG8_WAIT_V(n) asm volatile("s_waitcnt vmcnt(" #n ")" ::: "memory")
; #define PG8_WAIT_L(n) asm volatile("s_waitcnt lgkmcnt(" #n ")" ::: "memory")
; #define PG8_BAR __builtin_amdgcn_s_barrier()
; #define PG8_SCHED __builtin_amdgcn_sched_barrier(0)
;     ...
;             const bool last = (t == nt - 2);
;             const char* a1 = cA + (size_t)(t + 1) * kstep;
;             const char* a2 = last ? nA : cA + (size_t)(t + 2) * kstep; const char* b2 = last ? nB : cB + (size_t)(t + 2) * kstep;
;             const char* a3 = a2 + kstep; const char* b3 = b2 + kstep;
;             if (last && has_next) S.a_ready(nxt);
;             if constexpr (SP2) {
;             PG8_LDB(B0, 0, 0); PG8_LDB(B1, 0, 1); PG8_SCHED; PG8_LDA(At, 0, 0); PG8_STAGE(PG8_SA(1, 1), a1 + hstepA, voffA);
;             PG8_WAIT_V(8); PG8_WAIT_L(0); PG8_BAR; PG8_MMA(0, 0, At, B0); PG8_MMA(0, 1, At, B1); PG8_BAR; PG8_SCHED;
.LBB0_632:
	s_add_u32 s28, s8, 0xfffe0080
	s_addc_u32 s29, s9, -1
	s_add_i32 s48, 0, 0x10000
	s_cmp_eq_u32 s86, 2
	s_cselect_b32 s35, s23, s29
	s_cselect_b32 s34, s37, s28
	s_cselect_b32 s29, s25, s85
	s_cselect_b32 s28, s24, s69
	s_add_i32 s61, 0, 0x14000
	v_add_u32_e32 v142, s48, v1
	v_add_u32_e32 v158, s61, v1
	ds_read_b128 v[130:133], v142
	ds_read_b128 v[134:137], v142 offset:1024
	ds_read_b128 v[138:141], v142 offset:2048
	ds_read_b128 v[142:145], v142 offset:3072
	ds_read_b128 v[146:149], v158
	ds_read_b128 v[150:153], v158 offset:1024
	ds_read_b128 v[154:157], v158 offset:2048
	ds_read_b128 v[158:161], v158 offset:3072
	v_lshl_add_u64 v[188:189], s[8:9], 0, v[170:171]
	s_add_i32 m0, s43, 0xc000
	ds_read_b128 v[174:177], v190
	ds_read_b128 v[180:183], v190 offset:1024
	ds_read_b128 v[184:187], v190 offset:2048
	ds_read_b128 v[192:195], v190 offset:3072
	ds_read_b128 v[196:199], v190 offset:4096
	ds_read_b128 v[200:203], v190 offset:5120
	ds_read_b128 v[204:207], v190 offset:6144
	ds_read_b128 v[210:213], v190 offset:7168
	global_load_lds_dwordx4 v[188:189], off
	v_lshl_add_u64 v[188:189], s[8:9], 0, v[172:173]
	s_add_i32 m0, s43, 0xe000
	s_nop 0
	global_load_lds_dwordx4 v[188:189], off
	s_waitcnt vmcnt(8)
	s_waitcnt lgkmcnt(0)
	s_setprio 1
	s_cmp_lg_u32 s98, 0
	s_cbranch_scc0 .Lpg_b1_19
	s_barrier
	s_setprio 2
.Lpg_b1_19:
	s_waitcnt lgkmcnt(0)
	v_mfma_f32_16x16x32_bf16 v[126:129], v[130:133], v[174:177], v[126:129]
	v_mfma_f32_16x16x32_bf16 v[122:125], v[138:141], v[174:177], v[122:125]
	v_mfma_f32_16x16x32_bf16 v[110:113], v[130:133], v[184:187], v[110:113]
	v_mfma_f32_16x16x32_bf16 v[106:109], v[138:141], v[184:187], v[106:109]
	v_mfma_f32_16x16x32_bf16 v[94:97], v[130:133], v[196:199], v[94:97]
	v_mfma_f32_16x16x32_bf16 v[90:93], v[138:141], v[196:199], v[90:93]
	v_mfma_f32_16x16x32_bf16 v[78:81], v[130:133], v[204:207], v[78:81]
	v_mfma_f32_16x16x32_bf16 v[74:77], v[138:141], v[204:207], v[74:77]
	v_mfma_f32_16x16x32_bf16 v[126:129], v[134:137], v[180:183], v[126:129]
	v_mfma_f32_16x16x32_bf16 v[122:125], v[142:145], v[180:183], v[122:125]
	v_mfma_f32_16x16x32_bf16 v[110:113], v[134:137], v[192:195], v[110:113]
	v_mfma_f32_16x16x32_bf16 v[106:109], v[142:145], v[192:195], v[106:109]
	v_mfma_f32_16x16x32_bf16 v[94:97], v[134:137], v[200:203], v[94:97]
	v_mfma_f32_16x16x32_bf16 v[90:93], v[142:145], v[200:203], v[90:93]
	v_mfma_f32_16x16x32_bf16 v[78:81], v[134:137], v[210:213], v[78:81]
	v_mfma_f32_16x16x32_bf16 v[74:77], v[142:145], v[210:213], v[74:77]
	v_mfma_f32_16x16x32_bf16 v[118:121], v[146:149], v[174:177], v[118:121]
	v_mfma_f32_16x16x32_bf16 v[114:117], v[154:157], v[174:177], v[114:117]
	v_mfma_f32_16x16x32_bf16 v[102:105], v[146:149], v[184:187], v[102:105]
	v_mfma_f32_16x16x32_bf16 v[98:101], v[154:157], v[184:187], v[98:101]
	v_mfma_f32_16x16x32_bf16 v[86:89], v[146:149], v[196:199], v[86:89]
	v_mfma_f32_16x16x32_bf16 v[82:85], v[154:157], v[196:199], v[82:85]
	v_mfma_f32_16x16x32_bf16 v[70:73], v[146:149], v[204:207], v[70:73]
	v_mfma_f32_16x16x32_bf16 v[66:69], v[154:157], v[204:207], v[66:69]
	v_mfma_f32_16x16x32_bf16 v[118:121], v[150:153], v[180:183], v[118:121]
	v_mfma_f32_16x16x32_bf16 v[114:117], v[158:161], v[180:183], v[114:117]
	v_mfma_f32_16x16x32_bf16 v[102:105], v[150:153], v[192:195], v[102:105]
	v_mfma_f32_16x16x32_bf16 v[98:101], v[158:161], v[192:195], v[98:101]
	v_mfma_f32_16x16x32_bf16 v[86:89], v[150:153], v[200:203], v[86:89]
	v_mfma_f32_16x16x32_bf16 v[82:85], v[158:161], v[200:203], v[82:85]
	v_mfma_f32_16x16x32_bf16 v[70:73], v[150:153], v[210:213], v[70:73]
	v_mfma_f32_16x16x32_bf16 v[66:69], v[158:161], v[210:213], v[66:69]
	s_setprio 0
	s_cmp_lg_u32 s98, 0
	s_cbranch_scc1 .Lpg_b2_20
	s_barrier
; #define PG8_STAGE(bufoff, gbase, voff) do { _Pragma("unroll") for (int _i = 0; _i < 2; ++_i) \
;         __builtin_amdgcn_global_load_lds((const unsigned*)((const char*)(gbase) + (voff)[_i]), (PG8_LAS unsigned*)(lds + (bufoff) + ldsw + _i * 8192), 16, 0, 0); } while (0)
; #define PG8_LDA(dst, b, h) do { _Pragma("unroll") for (int m = 0; m < 4; ++m) _Pragma("unroll") for (int k = 0; k < 2; ++k) dst[m][k] = *(const PG8_LAS bf16x8*)(lds + PG8_SA(b, h) + aoff + m * 2048 + k * 1024); } while (0)
; #define PG8_LDB(dst, b, h) do { _Pragma("unroll") for (int n = 0; n < 2; ++n) _Pragma("unroll") for (int k = 0; k < 2; ++k) dst[n][k] = *(const PG8_LAS bf16x8*)(lds + PG8_SB(b, h) + boff + n * 2048 + k * 1024); } while (0)
; #define PG8_MMA(ai, bj, At, Bt) do { __builtin_amdgcn_s_setprio(1); _Pragma("unroll") for (int m = 0; m < 4; ++m) _Pragma("unroll") for (int n = 0; n < 2; ++n) _Pragma("unroll") for (int k = 0; k < 2; ++k) \
;         acc[ai][bj][m][n] = __builtin_amdgcn_mfma_f32_16x16x32_bf16(Bt[n][k], At[m][k], acc[ai][bj][m][n], 0, 0, 0); __builtin_amdgcn_s_setprio(0); } while (0)
; #define PG8_WAIT_V(n) asm volatile("s_waitcnt vmcnt(" #n ")" ::: "memory")
; #define PG8_WAIT_L(n) asm volatile("s_waitcnt lgkmcnt(" #n ")" ::: "memory")
; #define PG8_BAR __builtin_amdgcn_s_barrier()
; #define PG8_SCHED __builtin_amdgcn_sched_barrier(0)
;     ...
;             PG8_LDA(At, 0, 1); PG8_STAGE(PG8_SB(0, 0), b2, voffB); PG8_STAGE(PG8_SB(0, 1), b2 + hstepB, voffB); PG8_STAGE(PG8_SA(0, 0), a2, voffA);
;             PG8_WAIT_V(8); PG8_WAIT_L(0); PG8_BAR; PG8_MMA(1, 0, At, B0); PG8_MMA(1, 1, At, B1); PG8_BAR; PG8_SCHED;
;             PG8_LDB(B0, 1, 0); PG8_LDB(B1, 1, 1); PG8_SCHED; PG8_LDA(At, 1, 0); PG8_STAGE(PG8_SA(0, 1), a2 + hstepA, voffA);
;             PG8_WAIT_V(8); PG8_WAIT_L(0); PG8_BAR; PG8_MMA(0, 0, At, B0); PG8_MMA(0, 1, At, B1); PG8_BAR; PG8_SCHED;
.Lpg_b2_20:
	s_add_i32 s48, s48, s42
	v_lshl_add_u64 v[188:189], s[28:29], 0, v[166:167]
	s_mov_b32 m0, s48
	ds_read_b128 v[174:177], v190 offset:16384
	ds_read_b128 v[180:183], v190 offset:17408
	ds_read_b128 v[184:187], v190 offset:18432
	ds_read_b128 v[192:195], v190 offset:19456
	ds_read_b128 v[196:199], v190 offset:20480
	ds_read_b128 v[200:203], v190 offset:21504
	ds_read_b128 v[204:207], v190 offset:22528
	ds_read_b128 v[210:213], v190 offset:23552
	global_load_lds_dwordx4 v[188:189], off
	s_add_i32 m0, s48, 0x2000
	s_add_u32 s48, s28, 0x18000
	v_lshl_add_u64 v[214:215], s[28:29], 0, v[162:163]
	s_addc_u32 s49, s29, 0
	s_add_i32 s61, s61, s42
	global_load_lds_dwordx4 v[214:215], off
	v_lshl_add_u64 v[216:217], s[48:49], 0, v[166:167]
	s_mov_b32 m0, s61
	v_lshl_add_u64 v[218:219], s[34:35], 0, v[164:165]
	global_load_lds_dwordx4 v[216:217], off
	v_lshl_add_u64 v[216:217], s[48:49], 0, v[162:163]
	s_add_i32 m0, s61, 0x2000
	s_nop 0
	global_load_lds_dwordx4 v[216:217], off
	v_lshl_add_u64 v[216:217], s[34:35], 0, v[168:169]
	s_mov_b32 m0, s43
	s_nop 0
	global_load_lds_dwordx4 v[216:217], off
	s_mov_b32 m0, s44
	s_nop 0
	global_load_lds_dwordx4 v[218:219], off
	s_waitcnt vmcnt(8)
	s_waitcnt lgkmcnt(0)
	s_setprio 1
	s_cmp_lg_u32 s98, 0
	s_cbranch_scc0 .Lpg_b1_21
	s_barrier
	s_setprio 2
.Lpg_b1_21:
	s_waitcnt lgkmcnt(0)
	v_mfma_f32_16x16x32_bf16 v[62:65], v[130:133], v[174:177], v[62:65]
	v_mfma_f32_16x16x32_bf16 v[58:61], v[138:141], v[174:177], v[58:61]
	v_mfma_f32_16x16x32_bf16 v[46:49], v[130:133], v[184:187], v[46:49]
	v_mfma_f32_16x16x32_bf16 v[42:45], v[138:141], v[184:187], v[42:45]
	v_mfma_f32_16x16x32_bf16 v[30:33], v[130:133], v[196:199], v[30:33]
	v_mfma_f32_16x16x32_bf16 v[26:29], v[138:141], v[196:199], v[26:29]
	v_mfma_f32_16x16x32_bf16 v[14:17], v[130:133], v[204:207], v[14:17]
	v_mfma_f32_16x16x32_bf16 v[10:13], v[138:141], v[204:207], v[10:13]
	v_mfma_f32_16x16x32_bf16 v[62:65], v[134:137], v[180:183], v[62:65]
	v_mfma_f32_16x16x32_bf16 v[58:61], v[142:145], v[180:183], v[58:61]
	v_mfma_f32_16x16x32_bf16 v[46:49], v[134:137], v[192:195], v[46:49]
	v_mfma_f32_16x16x32_bf16 v[42:45], v[142:145], v[192:195], v[42:45]
	v_mfma_f32_16x16x32_bf16 v[30:33], v[134:137], v[200:203], v[30:33]
	v_mfma_f32_16x16x32_bf16 v[26:29], v[142:145], v[200:203], v[26:29]
	v_mfma_f32_16x16x32_bf16 v[14:17], v[134:137], v[210:213], v[14:17]
	v_mfma_f32_16x16x32_bf16 v[10:13], v[142:145], v[210:213], v[10:13]
	v_mfma_f32_16x16x32_bf16 v[54:57], v[146:149], v[174:177], v[54:57]
	v_mfma_f32_16x16x32_bf16 v[50:53], v[154:157], v[174:177], v[50:53]
	v_mfma_f32_16x16x32_bf16 v[38:41], v[146:149], v[184:187], v[38:41]
	v_mfma_f32_16x16x32_bf16 v[34:37], v[154:157], v[184:187], v[34:37]
	v_mfma_f32_16x16x32_bf16 v[22:25], v[146:149], v[196:199], v[22:25]
	v_mfma_f32_16x16x32_bf16 v[18:21], v[154:157], v[196:199], v[18:21]
	v_mfma_f32_16x16x32_bf16 v[6:9], v[146:149], v[204:207], v[6:9]
	v_mfma_f32_16x16x32_bf16 v[2:5], v[154:157], v[204:207], v[2:5]
	v_mfma_f32_16x16x32_bf16 v[54:57], v[150:153], v[180:183], v[54:57]
	v_mfma_f32_16x16x32_bf16 v[50:53], v[158:161], v[180:183], v[50:53]
	v_mfma_f32_16x16x32_bf16 v[38:41], v[150:153], v[192:195], v[38:41]
	v_mfma_f32_16x16x32_bf16 v[34:37], v[158:161], v[192:195], v[34:37]
	v_mfma_f32_16x16x32_bf16 v[22:25], v[150:153], v[200:203], v[22:25]
	v_mfma_f32_16x16x32_bf16 v[18:21], v[158:161], v[200:203], v[18:21]
	v_mfma_f32_16x16x32_bf16 v[6:9], v[150:153], v[210:213], v[6:9]
	v_mfma_f32_16x16x32_bf16 v[2:5], v[158:161], v[210:213], v[2:5]
	s_setprio 0
	s_cmp_lg_u32 s98, 0
	s_cbranch_scc1 .Lpg_b2_22
	s_barrier
.Lpg_b2_22:
	s_add_i32 s48, 0, 0x18000
	s_add_i32 s49, 0, 0x1c000
	v_add_u32_e32 v142, s48, v1
	v_add_u32_e32 v158, s49, v1
	ds_read_b128 v[130:133], v142
	ds_read_b128 v[134:137], v142 offset:1024
	ds_read_b128 v[138:141], v142 offset:2048
	ds_read_b128 v[142:145], v142 offset:3072
	ds_read_b128 v[146:149], v158
	ds_read_b128 v[150:153], v158 offset:1024
	ds_read_b128 v[154:157], v158 offset:2048
	ds_read_b128 v[158:161], v158 offset:3072
	s_add_u32 s34, s34, 0x20000
	s_addc_u32 s35, s35, 0
	s_mov_b32 m0, s45
	v_lshl_add_u64 v[222:223], s[34:35], 0, v[168:169]
	ds_read_b128 v[174:177], v190 offset:32768
	ds_read_b128 v[180:183], v190 offset:33792
	ds_read_b128 v[184:187], v190 offset:34816
	ds_read_b128 v[192:195], v190 offset:35840
	ds_read_b128 v[196:199], v190 offset:36864
	ds_read_b128 v[200:203], v190 offset:37888
	ds_read_b128 v[204:207], v190 offset:38912
	ds_read_b128 v[210:213], v190 offset:39936
	global_load_lds_dwordx4 v[222:223], off
	v_lshl_add_u64 v[222:223], s[34:35], 0, v[164:165]
	s_mov_b32 m0, s46
	s_nop 0
	global_load_lds_dwordx4 v[222:223], off
	s_waitcnt vmcnt(8)
	s_waitcnt lgkmcnt(0)
	s_setprio 1
	s_cmp_lg_u32 s98, 0
	s_cbranch_scc0 .Lpg_b1_23
	s_barrier
	s_setprio 2

; #define PG8_STAGE(bufoff, gbase, voff) do { _Pragma("unroll") for (int _i = 0; _i < 2; ++_i) \
;         __builtin_amdgcn_global_load_lds((const unsigned*)((const char*)(gbase) + (voff)[_i]), (PG8_LAS unsigned*)(lds + (bufoff) + ldsw + _i * 8192), 16, 0, 0); } while (0)
; #define PG8_LDA(dst, b, h) do { _Pragma("unroll") for (int m = 0; m < 4; ++m) _Pragma("unroll") for (int k = 0; k < 2; ++k) dst[m][k] = *(const PG8_LAS bf16x8*)(lds + PG8_SA(b, h) + aoff + m * 2048 + k * 1024); } while (0)
; #define PG8_MMA(ai, bj, At, Bt) do { __builtin_amdgcn_s_setprio(1); _Pragma("unroll") for (int m = 0; m < 4; ++m) _Pragma("unroll") for (int n = 0; n < 2; ++n) _Pragma("unroll") for (int k = 0; k < 2; ++k) \
;         acc[ai][bj][m][n] = __builtin_amdgcn_mfma_f32_16x16x32_bf16(Bt[n][k], At[m][k], acc[ai][bj][m][n], 0, 0, 0); __builtin_amdgcn_s_setprio(0); } while (0)
; #define PG8_WAIT_V(n) asm volatile("s_waitcnt vmcnt(" #n ")" ::: "memory")
; #define PG8_WAIT_L(n) asm volatile("s_waitcnt lgkmcnt(" #n ")" ::: "memory")
; #define PG8_BAR __builtin_amdgcn_s_barrier()
; #define PG8_SCHED __builtin_amdgcn_sched_barrier(0)
;     ...
;             PG8_LDA(At, 1, 1); PG8_STAGE(PG8_SB(1, 0), b3, voffB); PG8_STAGE(PG8_SB(1, 1), b3 + hstepB, voffB); PG8_STAGE(PG8_SA(1, 0), a3, voffA);
;             PG8_WAIT_V(8); PG8_WAIT_L(0); PG8_BAR; PG8_MMA(1, 0, At, B0); PG8_MMA(1, 1, At, B1); PG8_BAR; PG8_SCHED;
.Lpg_b2_24:
	s_add_i32 s34, s48, s42
	v_lshl_add_u64 v[188:189], v[188:189], 0, s[66:67]
	s_mov_b32 m0, s34
	ds_read_b128 v[174:177], v190 offset:49152
	ds_read_b128 v[180:183], v190 offset:50176
	ds_read_b128 v[184:187], v190 offset:51200
	ds_read_b128 v[192:195], v190 offset:52224
	ds_read_b128 v[196:199], v190 offset:53248
	ds_read_b128 v[200:203], v190 offset:54272
	ds_read_b128 v[204:207], v190 offset:55296
	ds_read_b128 v[210:213], v190 offset:56320
	global_load_lds_dwordx4 v[188:189], off
	s_add_i32 m0, s34, 0x2000
	s_add_u32 s28, s28, 0x18080
	v_lshl_add_u64 v[188:189], v[214:215], 0, s[66:67]
	s_addc_u32 s29, s29, 0
	s_add_i32 s34, s49, s42
	global_load_lds_dwordx4 v[188:189], off
	v_lshl_add_u64 v[188:189], s[28:29], 0, v[166:167]
	s_mov_b32 m0, s34
	s_nop 0
	global_load_lds_dwordx4 v[188:189], off
	v_lshl_add_u64 v[188:189], s[28:29], 0, v[162:163]
	s_add_i32 m0, s34, 0x2000
	s_nop 0
	global_load_lds_dwordx4 v[188:189], off
	v_lshl_add_u64 v[188:189], v[216:217], 0, s[66:67]
	s_mov_b32 m0, s55
	s_nop 0
	global_load_lds_dwordx4 v[188:189], off
	v_lshl_add_u64 v[188:189], v[218:219], 0, s[66:67]
	s_mov_b32 m0, s56
	s_nop 0
	global_load_lds_dwordx4 v[188:189], off
	s_waitcnt vmcnt(8)
	s_waitcnt lgkmcnt(0)
	s_setprio 1
	s_cmp_lg_u32 s98, 0
	s_cbranch_scc0 .Lpg_b1_25
	s_barrier
	s_setprio 2

; #define PG8_BAR __builtin_amdgcn_s_barrier()
;     ...
;         for (int t = 0; t < nt; t += 2) {
;             const bool last = (t == nt - 2);
;     ...
;         }
;         if constexpr (ALIGN_EPI) { if (wr == 0) PG8_BAR; }
.Lpg_b2_26:
	s_add_i32 s86, s86, 2
	s_add_u32 s8, s8, 0x100
	s_addc_u32 s9, s9, 0
	s_add_u32 s69, s69, 0x100
	s_addc_u32 s85, s85, 0
	s_cmp_gt_u32 s86, 3
	s_cbranch_scc0 .LBB0_632
	s_and_b64 vcc, exec, s[20:21]
	s_cbranch_vccz .LBB0_635

; #define PG8_STAGE(bufoff, gbase, voff) do { _Pragma("unroll") for (int _i = 0; _i < 2; ++_i) \
;         __builtin_amdgcn_global_load_lds((const unsigned*)((const char*)(gbase) + (voff)[_i]), (PG8_LAS unsigned*)(lds + (bufoff) + ldsw + _i * 8192), 16, 0, 0); } while (0)
; #define PG8_WAIT_V(n) asm volatile("s_waitcnt vmcnt(" #n ")" ::: "memory")
; #define PG8_BAR __builtin_amdgcn_s_barrier()
;     ...
;     for (int i = 0; i < 2; ++i) { int R, C; stage_rc(tid * 16 + i * 8192, R, C); const int Rb = Epi::PERM ? ((R & ~31) + perm32(R & 31)) : R;
;         voffA[i] = (unsigned)(R * lda_ + C) * 2u; voffB[i] = (unsigned)(Rb * K + C) * 2u; }
;     const size_t kstep = (size_t)(BK * 2);
;     const size_t hstepA = (size_t)HALF * lda_ * 2, hstepB = (size_t)HALF * K * 2;
;     const size_t tstepA = 2 * hstepA, tstepB = 2 * hstepB;
;     const unsigned ldsw = (unsigned)wid * 1024u;
;     const int aoff = lds_byte(wr * 64 + fr, fq * 8), boff = lds_byte(wc * 32 + fr, fq * 8);
;     ...
;         PG8_STAGE(PG8_SB(1, 0), cB + kstep, voffB); PG8_STAGE(PG8_SA(1, 0), cA + kstep, voffA); PG8_STAGE(PG8_SB(1, 1), cB + hstepB + kstep, voffB);
;         PG8_WAIT_V(6); PG8_BAR;
.LBB0_710:
	s_add_u32 s10, s10, 0x2c00000
	v_and_b32_e32 v10, 48, v1
	v_lshlrev_b32_e32 v11, 6, v1
	s_movk_i32 s14, 0x3c0
	v_lshlrev_b32_e32 v1, 2, v1
	s_addc_u32 s11, s11, 0
	s_and_b32 s2, s2, 3
	s_lshl_b32 s59, s1, 6
	s_lshl_b32 s1, s1, 13
	v_and_or_b32 v10, v11, s14, v10
	v_and_b32_e32 v1, 32, v1
	s_add_i32 m0, s55, 0x18000
	v_lshl_add_u64 v[8:9], v[8:9], 0, s[66:67]
	v_bitop3_b32 v11, v10, s1, v1 bitop3:0xde
	s_lshl_b32 s86, s2, 5
	s_lshl_b32 s1, s2, 12
	s_waitcnt vmcnt(2)
	s_barrier
	global_load_lds_dwordx4 v[8:9], off
	v_lshl_add_u64 v[6:7], v[6:7], 0, s[66:67]
	s_add_i32 m0, s55, 0x1a000
	s_add_i32 s87, s55, 0x8000
	s_add_i32 s88, s55, 0xa000
	global_load_lds_dwordx4 v[6:7], off
	v_lshl_add_u64 v[2:3], v[2:3], 0, s[66:67]
	s_mov_b32 m0, s87
	s_add_u32 s14, s24, 0x10080
	global_load_lds_dwordx4 v[2:3], off
	v_lshl_add_u64 v[2:3], v[4:5], 0, s[66:67]
	s_mov_b32 m0, s88
	s_addc_u32 s15, s25, 0
	global_load_lds_dwordx4 v[2:3], off
	s_add_i32 m0, s55, 0x1c000
	v_lshl_add_u64 v[2:3], s[14:15], 0, v[142:143]
	global_load_lds_dwordx4 v[2:3], off
	v_lshl_add_u64 v[2:3], s[14:15], 0, v[138:139]
	s_add_i32 m0, s55, 0x1e000
	s_cmpk_lt_u32 s0, 0x100
	global_load_lds_dwordx4 v[2:3], off
	s_waitcnt vmcnt(6)
	s_cselect_b64 s[14:15], -1, 0
	s_lshl_b32 s0, s2, 2
	v_bitop3_b32 v1, v10, s1, v1 bitop3:0xde
	s_add_i32 s89, s0, 0
	v_readlane_b32 s0, v253, 29
	s_add_i32 s89, s89, 0x20000
	s_mov_b32 s90, 0
	v_add_u32_e32 v159, 0, v11
	v_readlane_b32 s2, v253, 24
	s_mov_b32 s69, s0
	s_cmp_lg_u32 s98, 0
	s_cbranch_scc1 .Lpg_x2_36
	s_barrier
.Lpg_x2_36:
	v_readlane_b32 s1, v253, 30
	s_branch .LBB0_713

; #define PG8_STAGE(bufoff, gbase, voff) do { _Pragma("unroll") for (int _i = 0; _i < 2; ++_i) \
;         __builtin_amdgcn_global_load_lds((const unsigned*)((const char*)(gbase) + (voff)[_i]), (PG8_LAS unsigned*)(lds + (bufoff) + ldsw + _i * 8192), 16, 0, 0); } while (0)
; #define PG8_LDA(dst, b, h) do { _Pragma("unroll") for (int m = 0; m < 4; ++m) _Pragma("unroll") for (int k = 0; k < 2; ++k) dst[m][k] = *(const PG8_LAS bf16x8*)(lds + PG8_SA(b, h) + aoff + m * 2048 + k * 1024); } while (0)
; #define PG8_LDB(dst, b, h) do { _Pragma("unroll") for (int n = 0; n < 2; ++n) _Pragma("unroll") for (int k = 0; k < 2; ++k) dst[n][k] = *(const PG8_LAS bf16x8*)(lds + PG8_SB(b, h) + boff + n * 2048 + k * 1024); } while (0)
; #define PG8_MMA(ai, bj, At, Bt) do { __builtin_amdgcn_s_setprio(1); _Pragma("unroll") for (int m = 0; m < 4; ++m) _Pragma("unroll") for (int n = 0; n < 2; ++n) _Pragma("unroll") for (int k = 0; k < 2; ++k) \
;         acc[ai][bj][m][n] = __builtin_amdgcn_mfma_f32_16x16x32_bf16(Bt[n][k], At[m][k], acc[ai][bj][m][n], 0, 0, 0); __builtin_amdgcn_s_setprio(0); } while (0)
; #define PG8_WAIT_V(n) asm volatile("s_waitcnt vmcnt(" #n ")" ::: "memory")
; #define PG8_WAIT_L(n) asm volatile("s_waitcnt lgkmcnt(" #n ")" ::: "memory")
; #define PG8_BAR __builtin_amdgcn_s_barrier()
; #define PG8_SCHED __builtin_amdgcn_sched_barrier(0)
;     ...
;         for (int t = 0; t < nt; t += 2) {
;             const bool last = (t == nt - 2);
;             const char* a1 = cA + (size_t)(t + 1) * kstep;
;             const char* a2 = last ? nA : cA + (size_t)(t + 2) * kstep; const char* b2 = last ? nB : cB + (size_t)(t + 2) * kstep;
;             const char* a3 = a2 + kstep; const char* b3 = b2 + kstep;
;             if (last && has_next) S.a_ready(nxt);
;             if constexpr (SP2) {
;             PG8_LDB(B0, 0, 0); PG8_LDB(B1, 0, 1); PG8_SCHED; PG8_LDA(At, 0, 0); PG8_STAGE(PG8_SA(1, 1), a1 + hstepA, voffA);
;             PG8_WAIT_V(8); PG8_WAIT_L(0); PG8_BAR; PG8_MMA(0, 0, At, B0); PG8_MMA(0, 1, At, B1); PG8_BAR; PG8_SCHED;
.LBB0_720:
	s_add_u32 s42, s26, s36
	s_addc_u32 s43, s27, s37
	s_add_u32 s40, s42, 0x100
	s_addc_u32 s41, s43, 0
	s_and_b64 s[38:39], s[34:35], exec
	s_cselect_b32 s39, s19, s41
	s_cselect_b32 s38, s85, s40
	s_add_u32 s36, s24, s36
	s_addc_u32 s37, s25, s37
	s_add_u32 s36, s36, 0x100
	s_addc_u32 s37, s37, 0
	s_add_i32 s48, 0, 0x10000
	s_and_b64 s[34:35], s[34:35], exec
	s_cselect_b32 s41, s17, s37
	s_cselect_b32 s40, s91, s36
	s_add_i32 s35, 0, 0x14000
	s_add_u32 s44, s42, 0x10080
	s_addc_u32 s45, s43, 0
	s_add_i32 vcc_hi, s48, s54
	s_add_i32 m0, s55, 0xc000
	s_add_i32 s49, s55, 0xe000
	s_add_i32 s96, vcc_hi, 0x2000
	s_add_u32 s42, s40, 0x10000
	v_add_u32_e32 v150, s48, v1
	v_add_u32_e32 v158, s35, v1
	s_addc_u32 s43, s41, 0
	s_add_i32 vcc_lo, s35, s54
	ds_read_b128 v[130:133], v150
	ds_read_b128 v[134:137], v150 offset:1024
	ds_read_b128 v[146:149], v150 offset:2048
	ds_read_b128 v[150:153], v150 offset:3072
	ds_read_b128 v[154:157], v158
	ds_read_b128 v[160:163], v158 offset:1024
	ds_read_b128 v[164:167], v158 offset:2048
	ds_read_b128 v[168:171], v158 offset:3072
	s_add_i32 s97, vcc_lo, 0x2000
	s_add_i32 s95, 0, 0x18000
	s_add_i32 s94, 0, 0x1c000
	s_add_u32 s36, s38, 0x10000
	s_addc_u32 s37, s39, 0
	s_add_i32 s93, s95, s54
	s_add_i32 s92, s93, 0x2000
	s_add_u32 s34, s40, 0x10080
	s_addc_u32 s35, s41, 0
	s_add_i32 s61, s94, s54
	s_add_i32 s48, s61, 0x2000
	v_lshl_add_u64 v[176:177], s[44:45], 0, v[144:145]
	ds_read_b128 v[172:175], v159
	ds_read_b128 v[180:183], v159 offset:1024
	ds_read_b128 v[184:187], v159 offset:2048
	ds_read_b128 v[188:191], v159 offset:3072
	ds_read_b128 v[192:195], v159 offset:4096
	ds_read_b128 v[196:199], v159 offset:5120
	ds_read_b128 v[200:203], v159 offset:6144
	ds_read_b128 v[204:207], v159 offset:7168
	global_load_lds_dwordx4 v[176:177], off
	v_lshl_add_u64 v[176:177], s[44:45], 0, v[140:141]
	s_mov_b32 m0, s49
	s_nop 0
	global_load_lds_dwordx4 v[176:177], off
	s_waitcnt vmcnt(8)
	s_waitcnt lgkmcnt(0)
	s_setprio 1
	s_cmp_lg_u32 s98, 0
	s_cbranch_scc0 .Lpg_b1_28
	s_barrier
	s_setprio 2
.Lpg_b1_28:
	s_waitcnt lgkmcnt(0)
	v_mfma_f32_16x16x32_bf16 v[126:129], v[130:133], v[172:175], v[126:129]
	v_mfma_f32_16x16x32_bf16 v[122:125], v[146:149], v[172:175], v[122:125]
	v_mfma_f32_16x16x32_bf16 v[110:113], v[130:133], v[184:187], v[110:113]
	v_mfma_f32_16x16x32_bf16 v[106:109], v[146:149], v[184:187], v[106:109]
	v_mfma_f32_16x16x32_bf16 v[94:97], v[130:133], v[192:195], v[94:97]
	v_mfma_f32_16x16x32_bf16 v[90:93], v[146:149], v[192:195], v[90:93]
	v_mfma_f32_16x16x32_bf16 v[78:81], v[130:133], v[200:203], v[78:81]
	v_mfma_f32_16x16x32_bf16 v[74:77], v[146:149], v[200:203], v[74:77]
	v_mfma_f32_16x16x32_bf16 v[126:129], v[134:137], v[180:183], v[126:129]
	v_mfma_f32_16x16x32_bf16 v[122:125], v[150:153], v[180:183], v[122:125]
	v_mfma_f32_16x16x32_bf16 v[110:113], v[134:137], v[188:191], v[110:113]
	v_mfma_f32_16x16x32_bf16 v[106:109], v[150:153], v[188:191], v[106:109]
	v_mfma_f32_16x16x32_bf16 v[94:97], v[134:137], v[196:199], v[94:97]
	v_mfma_f32_16x16x32_bf16 v[90:93], v[150:153], v[196:199], v[90:93]
	v_mfma_f32_16x16x32_bf16 v[78:81], v[134:137], v[204:207], v[78:81]
	v_mfma_f32_16x16x32_bf16 v[74:77], v[150:153], v[204:207], v[74:77]
	v_mfma_f32_16x16x32_bf16 v[118:121], v[154:157], v[172:175], v[118:121]
	v_mfma_f32_16x16x32_bf16 v[114:117], v[164:167], v[172:175], v[114:117]
	v_mfma_f32_16x16x32_bf16 v[102:105], v[154:157], v[184:187], v[102:105]
	v_mfma_f32_16x16x32_bf16 v[98:101], v[164:167], v[184:187], v[98:101]
	v_mfma_f32_16x16x32_bf16 v[86:89], v[154:157], v[192:195], v[86:89]
	v_mfma_f32_16x16x32_bf16 v[82:85], v[164:167], v[192:195], v[82:85]
	v_mfma_f32_16x16x32_bf16 v[70:73], v[154:157], v[200:203], v[70:73]
	v_mfma_f32_16x16x32_bf16 v[66:69], v[164:167], v[200:203], v[66:69]
	v_mfma_f32_16x16x32_bf16 v[118:121], v[160:163], v[180:183], v[118:121]
	v_mfma_f32_16x16x32_bf16 v[114:117], v[168:171], v[180:183], v[114:117]
	v_mfma_f32_16x16x32_bf16 v[102:105], v[160:163], v[188:191], v[102:105]
	v_mfma_f32_16x16x32_bf16 v[98:101], v[168:171], v[188:191], v[98:101]
	v_mfma_f32_16x16x32_bf16 v[86:89], v[160:163], v[196:199], v[86:89]
	v_mfma_f32_16x16x32_bf16 v[82:85], v[168:171], v[196:199], v[82:85]
	v_mfma_f32_16x16x32_bf16 v[70:73], v[160:163], v[204:207], v[70:73]
	v_mfma_f32_16x16x32_bf16 v[66:69], v[168:171], v[204:207], v[66:69]
	s_setprio 0
	s_cmp_lg_u32 s98, 0
	s_cbranch_scc1 .Lpg_b2_29
	s_barrier
; #define PG8_STAGE(bufoff, gbase, voff) do { _Pragma("unroll") for (int _i = 0; _i < 2; ++_i) \
;         __builtin_amdgcn_global_load_lds((const unsigned*)((const char*)(gbase) + (voff)[_i]), (PG8_LAS unsigned*)(lds + (bufoff) + ldsw + _i * 8192), 16, 0, 0); } while (0)
; #define PG8_LDA(dst, b, h) do { _Pragma("unroll") for (int m = 0; m < 4; ++m) _Pragma("unroll") for (int k = 0; k < 2; ++k) dst[m][k] = *(const PG8_LAS bf16x8*)(lds + PG8_SA(b, h) + aoff + m * 2048 + k * 1024); } while (0)
; #define PG8_LDB(dst, b, h) do { _Pragma("unroll") for (int n = 0; n < 2; ++n) _Pragma("unroll") for (int k = 0; k < 2; ++k) dst[n][k] = *(const PG8_LAS bf16x8*)(lds + PG8_SB(b, h) + boff + n * 2048 + k * 1024); } while (0)
; #define PG8_MMA(ai, bj, At, Bt) do { __builtin_amdgcn_s_setprio(1); _Pragma("unroll") for (int m = 0; m < 4; ++m) _Pragma("unroll") for (int n = 0; n < 2; ++n) _Pragma("unroll") for (int k = 0; k < 2; ++k) \
;         acc[ai][bj][m][n] = __builtin_amdgcn_mfma_f32_16x16x32_bf16(Bt[n][k], At[m][k], acc[ai][bj][m][n], 0, 0, 0); __builtin_amdgcn_s_setprio(0); } while (0)
; #define PG8_WAIT_V(n) asm volatile("s_waitcnt vmcnt(" #n ")" ::: "memory")
; #define PG8_WAIT_L(n) asm volatile("s_waitcnt lgkmcnt(" #n ")" ::: "memory")
; #define PG8_BAR __builtin_amdgcn_s_barrier()
; #define PG8_SCHED __builtin_amdgcn_sched_barrier(0)
;     ...
;             PG8_LDA(At, 0, 1); PG8_STAGE(PG8_SB(0, 0), b2, voffB); PG8_STAGE(PG8_SB(0, 1), b2 + hstepB, voffB); PG8_STAGE(PG8_SA(0, 0), a2, voffA);
;             PG8_WAIT_V(8); PG8_WAIT_L(0); PG8_BAR; PG8_MMA(1, 0, At, B0); PG8_MMA(1, 1, At, B1); PG8_BAR; PG8_SCHED;
;             PG8_LDB(B0, 1, 0); PG8_LDB(B1, 1, 1); PG8_SCHED; PG8_LDA(At, 1, 0); PG8_STAGE(PG8_SA(0, 1), a2 + hstepA, voffA);
;             PG8_WAIT_V(8); PG8_WAIT_L(0); PG8_BAR; PG8_MMA(0, 0, At, B0); PG8_MMA(0, 1, At, B1); PG8_BAR; PG8_SCHED;
.Lpg_b2_29:
	s_mov_b32 m0, vcc_hi
	v_lshl_add_u64 v[176:177], s[40:41], 0, v[142:143]
	ds_read_b128 v[172:175], v159 offset:16384
	ds_read_b128 v[180:183], v159 offset:17408
	ds_read_b128 v[184:187], v159 offset:18432
	ds_read_b128 v[188:191], v159 offset:19456
	ds_read_b128 v[192:195], v159 offset:20480
	ds_read_b128 v[196:199], v159 offset:21504
	ds_read_b128 v[200:203], v159 offset:22528
	ds_read_b128 v[204:207], v159 offset:23552
	global_load_lds_dwordx4 v[176:177], off
	v_lshl_add_u64 v[210:211], s[40:41], 0, v[138:139]
	s_mov_b32 m0, s96
	v_lshl_add_u64 v[212:213], s[42:43], 0, v[142:143]
	global_load_lds_dwordx4 v[210:211], off
	s_mov_b32 m0, vcc_lo
	v_lshl_add_u64 v[214:215], s[38:39], 0, v[140:141]
	global_load_lds_dwordx4 v[212:213], off
	v_lshl_add_u64 v[212:213], s[42:43], 0, v[138:139]
	s_mov_b32 m0, s97
	s_nop 0
	global_load_lds_dwordx4 v[212:213], off
	v_lshl_add_u64 v[212:213], s[38:39], 0, v[144:145]
	s_mov_b32 m0, s55
	s_nop 0
	global_load_lds_dwordx4 v[212:213], off
	s_mov_b32 m0, s56
	s_nop 0
	global_load_lds_dwordx4 v[214:215], off
	s_waitcnt vmcnt(8)
	s_waitcnt lgkmcnt(0)
	s_setprio 1
	s_cmp_lg_u32 s98, 0
	s_cbranch_scc0 .Lpg_b1_30
	s_barrier
	s_setprio 2
.Lpg_b1_30:
	s_waitcnt lgkmcnt(0)
	v_mfma_f32_16x16x32_bf16 v[62:65], v[130:133], v[172:175], v[62:65]
	v_mfma_f32_16x16x32_bf16 v[58:61], v[146:149], v[172:175], v[58:61]
	v_mfma_f32_16x16x32_bf16 v[46:49], v[130:133], v[184:187], v[46:49]
	v_mfma_f32_16x16x32_bf16 v[42:45], v[146:149], v[184:187], v[42:45]
	v_mfma_f32_16x16x32_bf16 v[30:33], v[130:133], v[192:195], v[30:33]
	v_mfma_f32_16x16x32_bf16 v[26:29], v[146:149], v[192:195], v[26:29]
	v_mfma_f32_16x16x32_bf16 v[14:17], v[130:133], v[200:203], v[14:17]
	v_mfma_f32_16x16x32_bf16 v[10:13], v[146:149], v[200:203], v[10:13]
	v_mfma_f32_16x16x32_bf16 v[62:65], v[134:137], v[180:183], v[62:65]
	v_mfma_f32_16x16x32_bf16 v[58:61], v[150:153], v[180:183], v[58:61]
	v_mfma_f32_16x16x32_bf16 v[46:49], v[134:137], v[188:191], v[46:49]
	v_mfma_f32_16x16x32_bf16 v[42:45], v[150:153], v[188:191], v[42:45]
	v_mfma_f32_16x16x32_bf16 v[30:33], v[134:137], v[196:199], v[30:33]
	v_mfma_f32_16x16x32_bf16 v[26:29], v[150:153], v[196:199], v[26:29]
	v_mfma_f32_16x16x32_bf16 v[14:17], v[134:137], v[204:207], v[14:17]
	v_mfma_f32_16x16x32_bf16 v[10:13], v[150:153], v[204:207], v[10:13]
	v_mfma_f32_16x16x32_bf16 v[54:57], v[154:157], v[172:175], v[54:57]
	v_mfma_f32_16x16x32_bf16 v[50:53], v[164:167], v[172:175], v[50:53]
	v_mfma_f32_16x16x32_bf16 v[38:41], v[154:157], v[184:187], v[38:41]
	v_mfma_f32_16x16x32_bf16 v[34:37], v[164:167], v[184:187], v[34:37]
	v_mfma_f32_16x16x32_bf16 v[22:25], v[154:157], v[192:195], v[22:25]
	v_mfma_f32_16x16x32_bf16 v[18:21], v[164:167], v[192:195], v[18:21]
	v_mfma_f32_16x16x32_bf16 v[6:9], v[154:157], v[200:203], v[6:9]
	v_mfma_f32_16x16x32_bf16 v[2:5], v[164:167], v[200:203], v[2:5]
	v_mfma_f32_16x16x32_bf16 v[54:57], v[160:163], v[180:183], v[54:57]
	v_mfma_f32_16x16x32_bf16 v[50:53], v[168:171], v[180:183], v[50:53]
	v_mfma_f32_16x16x32_bf16 v[38:41], v[160:163], v[188:191], v[38:41]
	v_mfma_f32_16x16x32_bf16 v[34:37], v[168:171], v[188:191], v[34:37]
	v_mfma_f32_16x16x32_bf16 v[22:25], v[160:163], v[196:199], v[22:25]
	v_mfma_f32_16x16x32_bf16 v[18:21], v[168:171], v[196:199], v[18:21]
	v_mfma_f32_16x16x32_bf16 v[6:9], v[160:163], v[204:207], v[6:9]
	v_mfma_f32_16x16x32_bf16 v[2:5], v[168:171], v[204:207], v[2:5]
	s_setprio 0
	s_cmp_lg_u32 s98, 0
	s_cbranch_scc1 .Lpg_b2_31
	s_barrier
.Lpg_b2_31:
	v_add_u32_e32 v150, s95, v1
	v_add_u32_e32 v158, s94, v1
	ds_read_b128 v[130:133], v150
	ds_read_b128 v[134:137], v150 offset:1024
	ds_read_b128 v[146:149], v150 offset:2048
	ds_read_b128 v[150:153], v150 offset:3072
	ds_read_b128 v[154:157], v158
	ds_read_b128 v[160:163], v158 offset:1024
	ds_read_b128 v[164:167], v158 offset:2048
	ds_read_b128 v[168:171], v158 offset:3072
	s_mov_b32 m0, s57
	v_lshl_add_u64 v[216:217], s[36:37], 0, v[144:145]
	ds_read_b128 v[172:175], v159 offset:32768
	ds_read_b128 v[180:183], v159 offset:33792
	ds_read_b128 v[184:187], v159 offset:34816
	ds_read_b128 v[188:191], v159 offset:35840
	ds_read_b128 v[192:195], v159 offset:36864
	ds_read_b128 v[196:199], v159 offset:37888
	ds_read_b128 v[200:203], v159 offset:38912
	ds_read_b128 v[204:207], v159 offset:39936
	global_load_lds_dwordx4 v[216:217], off
	v_lshl_add_u64 v[216:217], s[36:37], 0, v[140:141]
	s_mov_b32 m0, s58
	s_nop 0
	global_load_lds_dwordx4 v[216:217], off
	s_waitcnt vmcnt(8)
	s_waitcnt lgkmcnt(0)
	s_setprio 1
	s_cmp_lg_u32 s98, 0
	s_cbranch_scc0 .Lpg_b1_32
	s_barrier
	s_setprio 2

; #define PG8_STAGE(bufoff, gbase, voff) do { _Pragma("unroll") for (int _i = 0; _i < 2; ++_i) \
;         __builtin_amdgcn_global_load_lds((const unsigned*)((const char*)(gbase) + (voff)[_i]), (PG8_LAS unsigned*)(lds + (bufoff) + ldsw + _i * 8192), 16, 0, 0); } while (0)
; #define PG8_LDA(dst, b, h) do { _Pragma("unroll") for (int m = 0; m < 4; ++m) _Pragma("unroll") for (int k = 0; k < 2; ++k) dst[m][k] = *(const PG8_LAS bf16x8*)(lds + PG8_SA(b, h) + aoff + m * 2048 + k * 1024); } while (0)
; #define PG8_MMA(ai, bj, At, Bt) do { __builtin_amdgcn_s_setprio(1); _Pragma("unroll") for (int m = 0; m < 4; ++m) _Pragma("unroll") for (int n = 0; n < 2; ++n) _Pragma("unroll") for (int k = 0; k < 2; ++k) \
;         acc[ai][bj][m][n] = __builtin_amdgcn_mfma_f32_16x16x32_bf16(Bt[n][k], At[m][k], acc[ai][bj][m][n], 0, 0, 0); __builtin_amdgcn_s_setprio(0); } while (0)
; #define PG8_WAIT_V(n) asm volatile("s_waitcnt vmcnt(" #n ")" ::: "memory")
; #define PG8_WAIT_L(n) asm volatile("s_waitcnt lgkmcnt(" #n ")" ::: "memory")
; #define PG8_BAR __builtin_amdgcn_s_barrier()
; #define PG8_SCHED __builtin_amdgcn_sched_barrier(0)
;     ...
;             PG8_LDA(At, 1, 1); PG8_STAGE(PG8_SB(1, 0), b3, voffB); PG8_STAGE(PG8_SB(1, 1), b3 + hstepB, voffB); PG8_STAGE(PG8_SA(1, 0), a3, voffA);
;             PG8_WAIT_V(8); PG8_WAIT_L(0); PG8_BAR; PG8_MMA(1, 0, At, B0); PG8_MMA(1, 1, At, B1); PG8_BAR; PG8_SCHED;
.Lpg_b2_33:
	s_mov_b32 m0, s93
	v_lshl_add_u64 v[176:177], v[176:177], 0, s[66:67]
	ds_read_b128 v[172:175], v159 offset:49152
	ds_read_b128 v[180:183], v159 offset:50176
	ds_read_b128 v[184:187], v159 offset:51200
	ds_read_b128 v[188:191], v159 offset:52224
	ds_read_b128 v[192:195], v159 offset:53248
	ds_read_b128 v[196:199], v159 offset:54272
	ds_read_b128 v[200:203], v159 offset:55296
	ds_read_b128 v[204:207], v159 offset:56320
	global_load_lds_dwordx4 v[176:177], off
	v_lshl_add_u64 v[176:177], v[210:211], 0, s[66:67]
	s_mov_b32 m0, s92
	s_nop 0
	global_load_lds_dwordx4 v[176:177], off
	v_lshl_add_u64 v[176:177], s[34:35], 0, v[142:143]
	s_mov_b32 m0, s61
	s_nop 0
	global_load_lds_dwordx4 v[176:177], off
	v_lshl_add_u64 v[176:177], s[34:35], 0, v[138:139]
	s_mov_b32 m0, s48
	s_nop 0
	global_load_lds_dwordx4 v[176:177], off
	v_lshl_add_u64 v[176:177], v[212:213], 0, s[66:67]
	s_mov_b32 m0, s87
	s_nop 0
	global_load_lds_dwordx4 v[176:177], off
	v_lshl_add_u64 v[176:177], v[214:215], 0, s[66:67]
	s_mov_b32 m0, s88
	s_nop 0
	global_load_lds_dwordx4 v[176:177], off
	s_waitcnt vmcnt(8)
	s_waitcnt lgkmcnt(0)
	s_setprio 1
	s_cmp_lg_u32 s98, 0
	s_cbranch_scc0 .Lpg_b1_34
	s_barrier
	s_setprio 2

; #define PG8_BAR __builtin_amdgcn_s_barrier()
;     ...
;         for (int t = 0; t < nt; t += 2) {
;             const bool last = (t == nt - 2);
;     ...
;         }
;         if constexpr (ALIGN_EPI) { if (wr == 0) PG8_BAR; }
.Lpg_b2_35:
	s_andn2_b64 vcc, exec, s[28:29]
	s_mov_b64 s[34:35], -1
	s_mov_b64 s[28:29], 0
	s_mov_b64 s[36:37], 0x100
	s_cbranch_vccz .LBB0_720
	s_and_b64 vcc, exec, s[14:15]
	s_cbranch_vccz .LBB0_723

; #define PG8_BAR __builtin_amdgcn_s_barrier()
;     ...
;         if constexpr (!Epi::AFTER_DRAIN) { E(acc, cur, wr, wc, fr, fq); S.done(cur); }
;         if (!has_next) break;
; #pragma unroll
;         for (int a = 0; a < 2; ++a)
; #pragma unroll
;             for (int b = 0; b < 2; ++b)
; #pragma unroll
;                 for (int m = 0; m < 4; ++m)
; #pragma unroll
;                     for (int n = 0; n < 2; ++n) acc[a][b][m][n] = (f32x4){0.f, 0.f, 0.f, 0.f};
;         cur = nxt; cA = nA; cB = nB; ++ui;
;         if constexpr (ALIGN_EPI) { if (wr == 1) PG8_BAR; }
.LBB0_760:
	s_andn2_b64 vcc, exec, s[12:13]
	s_cbranch_vccnz .LBB0_711
	s_branch .LBB0_711

; #define PG8_STAGE(bufoff, gbase, voff) do { _Pragma("unroll") for (int _i = 0; _i < 2; ++_i) \
;         __builtin_amdgcn_global_load_lds((const unsigned*)((const char*)(gbase) + (voff)[_i]), (PG8_LAS unsigned*)(lds + (bufoff) + ldsw + _i * 8192), 16, 0, 0); } while (0)
; #define PG8_WAIT_V(n) asm volatile("s_waitcnt vmcnt(" #n ")" ::: "memory")
; #define PG8_BAR __builtin_amdgcn_s_barrier()
;     ...
;     for (int i = 0; i < 2; ++i) { int R, C; stage_rc(tid * 16 + i * 8192, R, C); const int Rb = Epi::PERM ? ((R & ~31) + perm32(R & 31)) : R;
;         voffA[i] = (unsigned)(R * lda_ + C) * 2u; voffB[i] = (unsigned)(Rb * K + C) * 2u; }
;     const size_t kstep = (size_t)(BK * 2);
;     const size_t hstepA = (size_t)HALF * lda_ * 2, hstepB = (size_t)HALF * K * 2;
;     const size_t tstepA = 2 * hstepA, tstepB = 2 * hstepB;
;     const unsigned ldsw = (unsigned)wid * 1024u;
;     const int aoff = lds_byte(wr * 64 + fr, fq * 8), boff = lds_byte(wc * 32 + fr, fq * 8);
;     ...
;         PG8_STAGE(PG8_SB(1, 0), cB + kstep, voffB); PG8_STAGE(PG8_SA(1, 0), cA + kstep, voffA); PG8_STAGE(PG8_SB(1, 1), cB + hstepB + kstep, voffB);
;         PG8_WAIT_V(6); PG8_BAR;
.LBB0_953:
	s_lshl_b32 s5, s5, 5
	s_and_b32 s71, s5, 0x60
	s_add_i32 m0, s66, 0x18000
	v_lshl_add_u64 v[6:7], v[6:7], 0, s[22:23]
	s_lshl_b32 s70, s35, 6
	s_lshl_b32 s35, s35, 13
	s_lshl_b32 s5, s71, 7
	s_waitcnt vmcnt(2)
	s_barrier
	global_load_lds_dwordx4 v[6:7], off
	v_lshl_add_u64 v[4:5], v[4:5], 0, s[22:23]
	s_add_i32 m0, s66, 0x1a000
	s_add_i32 s72, s66, 0x8000
	s_add_i32 s73, s66, 0xa000
	global_load_lds_dwordx4 v[4:5], off
	v_lshl_add_u64 v[0:1], v[0:1], 0, s[22:23]
	s_mov_b32 m0, s72
	s_add_u32 s38, s28, 0x20080
	global_load_lds_dwordx4 v[0:1], off
	v_lshl_add_u64 v[0:1], v[2:3], 0, s[22:23]
	s_mov_b32 m0, s73
	s_addc_u32 s39, s29, 0
	global_load_lds_dwordx4 v[0:1], off
	s_add_i32 m0, s66, 0x1c000
	v_lshl_add_u64 v[0:1], s[38:39], 0, v[192:193]
	global_load_lds_dwordx4 v[0:1], off
	v_lshl_add_u64 v[0:1], s[38:39], 0, v[198:199]
	s_add_i32 m0, s66, 0x1e000
	s_cmpk_lt_u32 s4, 0x100
	global_load_lds_dwordx4 v[0:1], off
	v_and_b32_e32 v0, 48, v9
	v_lshlrev_b32_e32 v1, 6, v9
	v_and_or_b32 v0, v1, s44, v0
	v_lshlrev_b32_e32 v1, 2, v9
	v_and_b32_e32 v1, 32, v1
	v_bitop3_b32 v2, v0, s35, v1 bitop3:0xde
	v_bitop3_b32 v234, s5, v0, v1 bitop3:0xf6
	v_lshlrev_b32_e32 v0, 13, v13
	v_and_b32_e32 v0, 0xffffc000, v0
	v_lshl_add_u32 v0, v12, 10, v0
	v_and_b32_e32 v1, 1, v13
	v_lshl_or_b32 v0, v1, 6, v0
	s_cselect_b64 s[38:39], -1, 0
	s_cmpk_gt_u32 s40, 0xff
	v_lshl_add_u32 v204, v14, 1, v0
	v_lshlrev_b32_e32 v0, 13, v8
	s_cselect_b64 s[50:51], -1, 0
	s_lshl_b32 s4, s34, 11
	v_and_b32_e32 v0, 0xffffc000, v0
	s_waitcnt vmcnt(6)
	s_and_b32 s4, s4, 0x1800
	v_lshl_add_u32 v0, v10, 10, v0
	v_and_b32_e32 v1, 1, v8
	s_add_u32 s52, s26, s4
	v_lshl_or_b32 v0, v1, 6, v0
	s_addc_u32 s53, s27, 0
	v_mov_b32_e32 v205, v193
	v_lshl_add_u32 v206, v11, 1, v0
	v_mov_b32_e32 v207, v193
	s_mov_b32 s74, 0
	v_add_u32_e32 v235, 0, v2
	s_mov_b32 s75, s2
	s_mov_b32 s76, s12
	s_cmp_lg_u32 s98, 0
	s_cbranch_scc1 .Lpg_x2_45
	s_barrier
.Lpg_x2_45:
	s_branch .LBB0_956
.LBB0_954:
	s_mov_b64 s[4:5], 0

; #define PG8_STAGE(bufoff, gbase, voff) do { _Pragma("unroll") for (int _i = 0; _i < 2; ++_i) \
;         __builtin_amdgcn_global_load_lds((const unsigned*)((const char*)(gbase) + (voff)[_i]), (PG8_LAS unsigned*)(lds + (bufoff) + ldsw + _i * 8192), 16, 0, 0); } while (0)
; #define PG8_LDA(dst, b, h) do { _Pragma("unroll") for (int m = 0; m < 4; ++m) _Pragma("unroll") for (int k = 0; k < 2; ++k) dst[m][k] = *(const PG8_LAS bf16x8*)(lds + PG8_SA(b, h) + aoff + m * 2048 + k * 1024); } while (0)
; #define PG8_LDB(dst, b, h) do { _Pragma("unroll") for (int n = 0; n < 2; ++n) _Pragma("unroll") for (int k = 0; k < 2; ++k) dst[n][k] = *(const PG8_LAS bf16x8*)(lds + PG8_SB(b, h) + boff + n * 2048 + k * 1024); } while (0)
; #define PG8_MMA(ai, bj, At, Bt) do { __builtin_amdgcn_s_setprio(1); _Pragma("unroll") for (int m = 0; m < 4; ++m) _Pragma("unroll") for (int n = 0; n < 2; ++n) _Pragma("unroll") for (int k = 0; k < 2; ++k) \
;         acc[ai][bj][m][n] = __builtin_amdgcn_mfma_f32_16x16x32_bf16(Bt[n][k], At[m][k], acc[ai][bj][m][n], 0, 0, 0); __builtin_amdgcn_s_setprio(0); } while (0)
; #define PG8_WAIT_V(n) asm volatile("s_waitcnt vmcnt(" #n ")" ::: "memory")
; #define PG8_WAIT_L(n) asm volatile("s_waitcnt lgkmcnt(" #n ")" ::: "memory")
; #define PG8_BAR __builtin_amdgcn_s_barrier()
; #define PG8_SCHED __builtin_amdgcn_sched_barrier(0)
;     ...
;             const bool last = (t == nt - 2);
;             const char* a1 = cA + (size_t)(t + 1) * kstep;
;             const char* a2 = last ? nA : cA + (size_t)(t + 2) * kstep; const char* b2 = last ? nB : cB + (size_t)(t + 2) * kstep;
;             const char* a3 = a2 + kstep; const char* b3 = b2 + kstep;
;             if (last && has_next) S.a_ready(nxt);
;             if constexpr (SP2) {
;             PG8_LDB(B0, 0, 0); PG8_LDB(B1, 0, 1); PG8_SCHED; PG8_LDA(At, 0, 0); PG8_STAGE(PG8_SA(1, 1), a1 + hstepA, voffA);
;             PG8_WAIT_V(8); PG8_WAIT_L(0); PG8_BAR; PG8_MMA(0, 0, At, B0); PG8_MMA(0, 1, At, B1); PG8_BAR; PG8_SCHED;
.LBB0_963:
	s_add_u32 s28, s6, 0xfffe0080
	s_addc_u32 s29, s7, -1
	s_add_i32 s48, 0, 0x10000
	s_cmp_eq_u32 s81, 4
	s_cselect_b32 s35, s57, s29
	s_cselect_b32 s34, s77, s28
	s_cselect_b32 s29, s55, s80
	s_cselect_b32 s28, s78, s79
	s_add_i32 s82, 0, 0x14000
	v_add_u32_e32 v92, s48, v234
	v_add_u32_e32 v132, s82, v234
	ds_read_b128 v[64:67], v92
	ds_read_b128 v[68:71], v92 offset:1024
	ds_read_b128 v[80:83], v92 offset:2048
	ds_read_b128 v[92:95], v92 offset:3072
	ds_read_b128 v[104:107], v132
	ds_read_b128 v[108:111], v132 offset:1024
	ds_read_b128 v[120:123], v132 offset:2048
	ds_read_b128 v[132:135], v132 offset:3072
	v_lshl_add_u64 v[208:209], s[6:7], 0, v[204:205]
	s_add_i32 m0, s66, 0xc000
	ds_read_b128 v[152:155], v235
	ds_read_b128 v[164:167], v235 offset:1024
	ds_read_b128 v[168:171], v235 offset:2048
	ds_read_b128 v[172:175], v235 offset:3072
	ds_read_b128 v[176:179], v235 offset:4096
	ds_read_b128 v[180:183], v235 offset:5120
	ds_read_b128 v[184:187], v235 offset:6144
	ds_read_b128 v[188:191], v235 offset:7168
	global_load_lds_dwordx4 v[208:209], off
	v_lshl_add_u64 v[208:209], s[6:7], 0, v[206:207]
	s_add_i32 m0, s66, 0xe000
	s_nop 0
	global_load_lds_dwordx4 v[208:209], off
	s_waitcnt vmcnt(8)
	s_waitcnt lgkmcnt(0)
	s_setprio 1
	s_cmp_lg_u32 s98, 0
	s_cbranch_scc0 .Lpg_b1_37
	s_barrier
	s_setprio 2
.Lpg_b1_37:
	s_waitcnt lgkmcnt(0)
	v_mfma_f32_16x16x32_bf16 v[160:163], v[64:67], v[152:155], v[160:163]
	v_mfma_f32_16x16x32_bf16 v[156:159], v[80:83], v[152:155], v[156:159]
	v_mfma_f32_16x16x32_bf16 v[140:143], v[64:67], v[168:171], v[140:143]
	v_mfma_f32_16x16x32_bf16 v[136:139], v[80:83], v[168:171], v[136:139]
	v_mfma_f32_16x16x32_bf16 v[116:119], v[64:67], v[176:179], v[116:119]
	v_mfma_f32_16x16x32_bf16 v[112:115], v[80:83], v[176:179], v[112:115]
	v_mfma_f32_16x16x32_bf16 v[88:91], v[64:67], v[184:187], v[88:91]
	v_mfma_f32_16x16x32_bf16 v[84:87], v[80:83], v[184:187], v[84:87]
	v_mfma_f32_16x16x32_bf16 v[160:163], v[68:71], v[164:167], v[160:163]
	v_mfma_f32_16x16x32_bf16 v[156:159], v[92:95], v[164:167], v[156:159]
	v_mfma_f32_16x16x32_bf16 v[140:143], v[68:71], v[172:175], v[140:143]
	v_mfma_f32_16x16x32_bf16 v[136:139], v[92:95], v[172:175], v[136:139]
	v_mfma_f32_16x16x32_bf16 v[116:119], v[68:71], v[180:183], v[116:119]
	v_mfma_f32_16x16x32_bf16 v[112:115], v[92:95], v[180:183], v[112:115]
	v_mfma_f32_16x16x32_bf16 v[88:91], v[68:71], v[188:191], v[88:91]
	v_mfma_f32_16x16x32_bf16 v[84:87], v[92:95], v[188:191], v[84:87]
	v_mfma_f32_16x16x32_bf16 v[148:151], v[104:107], v[152:155], v[148:151]
	v_mfma_f32_16x16x32_bf16 v[144:147], v[120:123], v[152:155], v[144:147]
	v_mfma_f32_16x16x32_bf16 v[128:131], v[104:107], v[168:171], v[128:131]
	v_mfma_f32_16x16x32_bf16 v[124:127], v[120:123], v[168:171], v[124:127]
	v_mfma_f32_16x16x32_bf16 v[100:103], v[104:107], v[176:179], v[100:103]
	v_mfma_f32_16x16x32_bf16 v[96:99], v[120:123], v[176:179], v[96:99]
	v_mfma_f32_16x16x32_bf16 v[76:79], v[104:107], v[184:187], v[76:79]
	v_mfma_f32_16x16x32_bf16 v[72:75], v[120:123], v[184:187], v[72:75]
	v_mfma_f32_16x16x32_bf16 v[148:151], v[108:111], v[164:167], v[148:151]
	v_mfma_f32_16x16x32_bf16 v[144:147], v[132:135], v[164:167], v[144:147]
	v_mfma_f32_16x16x32_bf16 v[128:131], v[108:111], v[172:175], v[128:131]
	v_mfma_f32_16x16x32_bf16 v[124:127], v[132:135], v[172:175], v[124:127]
	v_mfma_f32_16x16x32_bf16 v[100:103], v[108:111], v[180:183], v[100:103]
	v_mfma_f32_16x16x32_bf16 v[96:99], v[132:135], v[180:183], v[96:99]
	v_mfma_f32_16x16x32_bf16 v[76:79], v[108:111], v[188:191], v[76:79]
	v_mfma_f32_16x16x32_bf16 v[72:75], v[132:135], v[188:191], v[72:75]
	s_setprio 0
	s_cmp_lg_u32 s98, 0
	s_cbranch_scc1 .Lpg_b2_38
	s_barrier
; #define PG8_STAGE(bufoff, gbase, voff) do { _Pragma("unroll") for (int _i = 0; _i < 2; ++_i) \
;         __builtin_amdgcn_global_load_lds((const unsigned*)((const char*)(gbase) + (voff)[_i]), (PG8_LAS unsigned*)(lds + (bufoff) + ldsw + _i * 8192), 16, 0, 0); } while (0)
; #define PG8_LDA(dst, b, h) do { _Pragma("unroll") for (int m = 0; m < 4; ++m) _Pragma("unroll") for (int k = 0; k < 2; ++k) dst[m][k] = *(const PG8_LAS bf16x8*)(lds + PG8_SA(b, h) + aoff + m * 2048 + k * 1024); } while (0)
; #define PG8_LDB(dst, b, h) do { _Pragma("unroll") for (int n = 0; n < 2; ++n) _Pragma("unroll") for (int k = 0; k < 2; ++k) dst[n][k] = *(const PG8_LAS bf16x8*)(lds + PG8_SB(b, h) + boff + n * 2048 + k * 1024); } while (0)
; #define PG8_MMA(ai, bj, At, Bt) do { __builtin_amdgcn_s_setprio(1); _Pragma("unroll") for (int m = 0; m < 4; ++m) _Pragma("unroll") for (int n = 0; n < 2; ++n) _Pragma("unroll") for (int k = 0; k < 2; ++k) \
;         acc[ai][bj][m][n] = __builtin_amdgcn_mfma_f32_16x16x32_bf16(Bt[n][k], At[m][k], acc[ai][bj][m][n], 0, 0, 0); __builtin_amdgcn_s_setprio(0); } while (0)
; #define PG8_WAIT_V(n) asm volatile("s_waitcnt vmcnt(" #n ")" ::: "memory")
; #define PG8_WAIT_L(n) asm volatile("s_waitcnt lgkmcnt(" #n ")" ::: "memory")
; #define PG8_BAR __builtin_amdgcn_s_barrier()
; #define PG8_SCHED __builtin_amdgcn_sched_barrier(0)
;     ...
;             PG8_LDA(At, 0, 1); PG8_STAGE(PG8_SB(0, 0), b2, voffB); PG8_STAGE(PG8_SB(0, 1), b2 + hstepB, voffB); PG8_STAGE(PG8_SA(0, 0), a2, voffA);
;             PG8_WAIT_V(8); PG8_WAIT_L(0); PG8_BAR; PG8_MMA(1, 0, At, B0); PG8_MMA(1, 1, At, B1); PG8_BAR; PG8_SCHED;
;             PG8_LDB(B0, 1, 0); PG8_LDB(B1, 1, 1); PG8_SCHED; PG8_LDA(At, 1, 0); PG8_STAGE(PG8_SA(0, 1), a2 + hstepA, voffA);
;             PG8_WAIT_V(8); PG8_WAIT_L(0); PG8_BAR; PG8_MMA(0, 0, At, B0); PG8_MMA(0, 1, At, B1); PG8_BAR; PG8_SCHED;
.Lpg_b2_38:
	s_add_i32 s48, s48, s65
	v_lshl_add_u64 v[208:209], s[28:29], 0, v[192:193]
	s_mov_b32 m0, s48
	ds_read_b128 v[152:155], v235 offset:16384
	ds_read_b128 v[164:167], v235 offset:17408
	ds_read_b128 v[168:171], v235 offset:18432
	ds_read_b128 v[172:175], v235 offset:19456
	ds_read_b128 v[176:179], v235 offset:20480
	ds_read_b128 v[180:183], v235 offset:21504
	ds_read_b128 v[184:187], v235 offset:22528
	ds_read_b128 v[188:191], v235 offset:23552
	global_load_lds_dwordx4 v[208:209], off
	s_add_i32 m0, s48, 0x2000
	s_add_u32 s48, s28, 0x20000
	v_lshl_add_u64 v[210:211], s[28:29], 0, v[198:199]
	s_addc_u32 s49, s29, 0
	s_add_i32 s82, s82, s65
	global_load_lds_dwordx4 v[210:211], off
	v_lshl_add_u64 v[212:213], s[48:49], 0, v[192:193]
	s_mov_b32 m0, s82
	v_lshl_add_u64 v[214:215], s[34:35], 0, v[200:201]
	global_load_lds_dwordx4 v[212:213], off
	v_lshl_add_u64 v[212:213], s[48:49], 0, v[198:199]
	s_add_i32 m0, s82, 0x2000
	s_nop 0
	global_load_lds_dwordx4 v[212:213], off
	v_lshl_add_u64 v[212:213], s[34:35], 0, v[202:203]
	s_mov_b32 m0, s66
	s_nop 0
	global_load_lds_dwordx4 v[212:213], off
	s_mov_b32 m0, s67
	s_nop 0
	global_load_lds_dwordx4 v[214:215], off
	s_waitcnt vmcnt(8)
	s_waitcnt lgkmcnt(0)
	s_setprio 1
	s_cmp_lg_u32 s98, 0
	s_cbranch_scc0 .Lpg_b1_39
	s_barrier
	s_setprio 2
.Lpg_b1_39:
	s_waitcnt lgkmcnt(0)
	v_mfma_f32_16x16x32_bf16 v[60:63], v[64:67], v[152:155], v[60:63]
	v_mfma_f32_16x16x32_bf16 v[56:59], v[80:83], v[152:155], v[56:59]
	v_mfma_f32_16x16x32_bf16 v[44:47], v[64:67], v[168:171], v[44:47]
	v_mfma_f32_16x16x32_bf16 v[40:43], v[80:83], v[168:171], v[40:43]
	v_mfma_f32_16x16x32_bf16 v[28:31], v[64:67], v[176:179], v[28:31]
	v_mfma_f32_16x16x32_bf16 v[24:27], v[80:83], v[176:179], v[24:27]
	v_mfma_f32_16x16x32_bf16 v[12:15], v[64:67], v[184:187], v[12:15]
	v_mfma_f32_16x16x32_bf16 v[8:11], v[80:83], v[184:187], v[8:11]
	v_mfma_f32_16x16x32_bf16 v[60:63], v[68:71], v[164:167], v[60:63]
	v_mfma_f32_16x16x32_bf16 v[56:59], v[92:95], v[164:167], v[56:59]
	v_mfma_f32_16x16x32_bf16 v[44:47], v[68:71], v[172:175], v[44:47]
	v_mfma_f32_16x16x32_bf16 v[40:43], v[92:95], v[172:175], v[40:43]
	v_mfma_f32_16x16x32_bf16 v[28:31], v[68:71], v[180:183], v[28:31]
	v_mfma_f32_16x16x32_bf16 v[24:27], v[92:95], v[180:183], v[24:27]
	v_mfma_f32_16x16x32_bf16 v[12:15], v[68:71], v[188:191], v[12:15]
	v_mfma_f32_16x16x32_bf16 v[8:11], v[92:95], v[188:191], v[8:11]
	v_mfma_f32_16x16x32_bf16 v[52:55], v[104:107], v[152:155], v[52:55]
	v_mfma_f32_16x16x32_bf16 v[48:51], v[120:123], v[152:155], v[48:51]
	v_mfma_f32_16x16x32_bf16 v[36:39], v[104:107], v[168:171], v[36:39]
	v_mfma_f32_16x16x32_bf16 v[32:35], v[120:123], v[168:171], v[32:35]
	v_mfma_f32_16x16x32_bf16 v[20:23], v[104:107], v[176:179], v[20:23]
	v_mfma_f32_16x16x32_bf16 v[16:19], v[120:123], v[176:179], v[16:19]
	v_mfma_f32_16x16x32_bf16 v[4:7], v[104:107], v[184:187], v[4:7]
	v_mfma_f32_16x16x32_bf16 v[0:3], v[120:123], v[184:187], v[0:3]
	v_mfma_f32_16x16x32_bf16 v[52:55], v[108:111], v[164:167], v[52:55]
	v_mfma_f32_16x16x32_bf16 v[48:51], v[132:135], v[164:167], v[48:51]
	v_mfma_f32_16x16x32_bf16 v[36:39], v[108:111], v[172:175], v[36:39]
	v_mfma_f32_16x16x32_bf16 v[32:35], v[132:135], v[172:175], v[32:35]
	v_mfma_f32_16x16x32_bf16 v[20:23], v[108:111], v[180:183], v[20:23]
	v_mfma_f32_16x16x32_bf16 v[16:19], v[132:135], v[180:183], v[16:19]
	v_mfma_f32_16x16x32_bf16 v[4:7], v[108:111], v[188:191], v[4:7]
	v_mfma_f32_16x16x32_bf16 v[0:3], v[132:135], v[188:191], v[0:3]
	s_setprio 0
	s_cmp_lg_u32 s98, 0
	s_cbranch_scc1 .Lpg_b2_40
	s_barrier
.Lpg_b2_40:
	s_add_i32 s48, 0, 0x18000
	s_add_i32 s49, 0, 0x1c000
	v_add_u32_e32 v92, s48, v234
	v_add_u32_e32 v132, s49, v234
	ds_read_b128 v[64:67], v92
	ds_read_b128 v[68:71], v92 offset:1024
	ds_read_b128 v[80:83], v92 offset:2048
	ds_read_b128 v[92:95], v92 offset:3072
	ds_read_b128 v[104:107], v132
	ds_read_b128 v[108:111], v132 offset:1024
	ds_read_b128 v[120:123], v132 offset:2048
	ds_read_b128 v[132:135], v132 offset:3072
	s_add_u32 s34, s34, 0x20000
	s_addc_u32 s35, s35, 0
	s_mov_b32 m0, s68
	v_lshl_add_u64 v[216:217], s[34:35], 0, v[202:203]
	ds_read_b128 v[152:155], v235 offset:32768
	ds_read_b128 v[164:167], v235 offset:33792
	ds_read_b128 v[168:171], v235 offset:34816
	ds_read_b128 v[172:175], v235 offset:35840
	ds_read_b128 v[176:179], v235 offset:36864
	ds_read_b128 v[180:183], v235 offset:37888
	ds_read_b128 v[184:187], v235 offset:38912
	ds_read_b128 v[188:191], v235 offset:39936
	global_load_lds_dwordx4 v[216:217], off
	v_lshl_add_u64 v[216:217], s[34:35], 0, v[200:201]
	s_mov_b32 m0, s69
	s_nop 0
	global_load_lds_dwordx4 v[216:217], off
	s_waitcnt vmcnt(8)
	s_waitcnt lgkmcnt(0)
	s_setprio 1
	s_cmp_lg_u32 s98, 0
	s_cbranch_scc0 .Lpg_b1_41
	s_barrier
	s_setprio 2

; #define PG8_STAGE(bufoff, gbase, voff) do { _Pragma("unroll") for (int _i = 0; _i < 2; ++_i) \
;         __builtin_amdgcn_global_load_lds((const unsigned*)((const char*)(gbase) + (voff)[_i]), (PG8_LAS unsigned*)(lds + (bufoff) + ldsw + _i * 8192), 16, 0, 0); } while (0)
; #define PG8_LDA(dst, b, h) do { _Pragma("unroll") for (int m = 0; m < 4; ++m) _Pragma("unroll") for (int k = 0; k < 2; ++k) dst[m][k] = *(const PG8_LAS bf16x8*)(lds + PG8_SA(b, h) + aoff + m * 2048 + k * 1024); } while (0)
; #define PG8_MMA(ai, bj, At, Bt) do { __builtin_amdgcn_s_setprio(1); _Pragma("unroll") for (int m = 0; m < 4; ++m) _Pragma("unroll") for (int n = 0; n < 2; ++n) _Pragma("unroll") for (int k = 0; k < 2; ++k) \
;         acc[ai][bj][m][n] = __builtin_amdgcn_mfma_f32_16x16x32_bf16(Bt[n][k], At[m][k], acc[ai][bj][m][n], 0, 0, 0); __builtin_amdgcn_s_setprio(0); } while (0)
; #define PG8_WAIT_V(n) asm volatile("s_waitcnt vmcnt(" #n ")" ::: "memory")
; #define PG8_WAIT_L(n) asm volatile("s_waitcnt lgkmcnt(" #n ")" ::: "memory")
; #define PG8_BAR __builtin_amdgcn_s_barrier()
; #define PG8_SCHED __builtin_amdgcn_sched_barrier(0)
;     ...
;             PG8_LDA(At, 1, 1); PG8_STAGE(PG8_SB(1, 0), b3, voffB); PG8_STAGE(PG8_SB(1, 1), b3 + hstepB, voffB); PG8_STAGE(PG8_SA(1, 0), a3, voffA);
;             PG8_WAIT_V(8); PG8_WAIT_L(0); PG8_BAR; PG8_MMA(1, 0, At, B0); PG8_MMA(1, 1, At, B1); PG8_BAR; PG8_SCHED;
.Lpg_b2_42:
	s_add_i32 s34, s48, s65
	v_lshl_add_u64 v[208:209], v[208:209], 0, s[22:23]
	s_mov_b32 m0, s34
	ds_read_b128 v[152:155], v235 offset:49152
	ds_read_b128 v[164:167], v235 offset:50176
	ds_read_b128 v[168:171], v235 offset:51200
	ds_read_b128 v[172:175], v235 offset:52224
	ds_read_b128 v[176:179], v235 offset:53248
	ds_read_b128 v[180:183], v235 offset:54272
	ds_read_b128 v[184:187], v235 offset:55296
	ds_read_b128 v[188:191], v235 offset:56320
	global_load_lds_dwordx4 v[208:209], off
	s_add_i32 m0, s34, 0x2000
	s_add_u32 s28, s28, 0x20080
	v_lshl_add_u64 v[208:209], v[210:211], 0, s[22:23]
	s_addc_u32 s29, s29, 0
	s_add_i32 s34, s49, s65
	global_load_lds_dwordx4 v[208:209], off
	v_lshl_add_u64 v[208:209], s[28:29], 0, v[192:193]
	s_mov_b32 m0, s34
	s_nop 0
	global_load_lds_dwordx4 v[208:209], off
	v_lshl_add_u64 v[208:209], s[28:29], 0, v[198:199]
	s_add_i32 m0, s34, 0x2000
	s_nop 0
	global_load_lds_dwordx4 v[208:209], off
	v_lshl_add_u64 v[208:209], v[212:213], 0, s[22:23]
	s_mov_b32 m0, s72
	s_nop 0
	global_load_lds_dwordx4 v[208:209], off
	v_lshl_add_u64 v[208:209], v[214:215], 0, s[22:23]
	s_mov_b32 m0, s73
	s_nop 0
	global_load_lds_dwordx4 v[208:209], off
	s_waitcnt vmcnt(8)
	s_waitcnt lgkmcnt(0)
	s_setprio 1
	s_cmp_lg_u32 s98, 0
	s_cbranch_scc0 .Lpg_b1_43
	s_barrier
	s_setprio 2

; #define PG8_BAR __builtin_amdgcn_s_barrier()
;     ...
;         for (int t = 0; t < nt; t += 2) {
;             const bool last = (t == nt - 2);
;     ...
;         }
;         if constexpr (ALIGN_EPI) { if (wr == 0) PG8_BAR; }
.Lpg_b2_44:
	s_add_i32 s81, s81, 2
	s_add_u32 s6, s6, 0x100
	s_addc_u32 s7, s7, 0
	s_add_u32 s79, s79, 0x100
	s_addc_u32 s80, s80, 0
	s_cmp_gt_u32 s81, 5
	s_cbranch_scc0 .LBB0_963
	s_and_b64 vcc, exec, s[38:39]
	s_cbranch_vccz .LBB0_966

; #define PG8_BAR __builtin_amdgcn_s_barrier()
; DI void st8(bf16_t* p, const float (&v)[8]) { u32x4 w; w.x = cvtpk(v[0], v[1]); w.y = cvtpk(v[2], v[3]); w.z = cvtpk(v[4], v[5]); w.w = cvtpk(v[6], v[7]); *(u32x4*)p = w; }
; #define SBE() __builtin_amdgcn_sched_barrier(0)
; #define OUT_LOAD(itn, buf) do { const size_t rw_ = (size_t)(grow0 + ((itn) >> 2) * 128 + ((itn) & 3) * 16); BJLOOP { pg[buf][bj] = *(const u32x4*)(b.zG + rw_ * 3072 + brn * 1024 + tc0 + bj * 128); \
;                 if (accum) pm[buf][bj] = *(const u32x4*)(b.merged + rw_ * 1024 + tc0 + bj * 128); } } while (0)
;     ...
;         if constexpr (!Epi::AFTER_DRAIN) { E(acc, cur, wr, wc, fr, fq); S.done(cur); }
;         if (!has_next) break;
; #pragma unroll
;         for (int a = 0; a < 2; ++a)
; #pragma unroll
;             for (int b = 0; b < 2; ++b)
; #pragma unroll
;                 for (int m = 0; m < 4; ++m)
; #pragma unroll
;                     for (int n = 0; n < 2; ++n) acc[a][b][m][n] = (f32x4){0.f, 0.f, 0.f, 0.f};
;         cur = nxt; cA = nA; cB = nB; ++ui;
;         if constexpr (ALIGN_EPI) { if (wr == 1) PG8_BAR; }
;     DI void operator()(const AccT& acc, const pg8::Unit& u, int wr, int wc, int fr_in, int fq_in) const {
;     ...
;                     st8(b.merged + IT_ROW * 1024 + tc0 + bj * 128, v); }
;                 SBE(); if (it + 4 < 8) OUT_LOAD(it + 4, it & 3); SBE(); }
.LBB0_1062:
	v_cvt_pk_bf16_f32 v0, v12, v13
	v_cvt_pk_bf16_f32 v1, v18, v19
	v_cvt_pk_bf16_f32 v2, v20, v21
	v_cvt_pk_bf16_f32 v3, v22, v23
	global_store_dwordx4 v[84:85], v[0:3], off offset:256
	s_andn2_b64 vcc, exec, s[4:5]
	s_mov_b64 s[4:5], -1
	s_cbranch_vccnz .LBB0_955
	s_andn2_b64 vcc, exec, s[36:37]
	s_cbranch_vccnz .LBB0_954
	s_branch .LBB0_954

; #define PG8_STAGE(bufoff, gbase, voff) do { _Pragma("unroll") for (int _i = 0; _i < 2; ++_i) \
;         __builtin_amdgcn_global_load_lds((const unsigned*)((const char*)(gbase) + (voff)[_i]), (PG8_LAS unsigned*)(lds + (bufoff) + ldsw + _i * 8192), 16, 0, 0); } while (0)
; #define PG8_WAIT_V(n) asm volatile("s_waitcnt vmcnt(" #n ")" ::: "memory")
; #define PG8_BAR __builtin_amdgcn_s_barrier()
;     ...
;     for (int i = 0; i < 2; ++i) { int R, C; stage_rc(tid * 16 + i * 8192, R, C); const int Rb = Epi::PERM ? ((R & ~31) + perm32(R & 31)) : R;
;         voffA[i] = (unsigned)(R * lda_ + C) * 2u; voffB[i] = (unsigned)(Rb * K + C) * 2u; }
;     const size_t kstep = (size_t)(BK * 2);
;     const size_t hstepA = (size_t)HALF * lda_ * 2, hstepB = (size_t)HALF * K * 2;
;     const size_t tstepA = 2 * hstepA, tstepB = 2 * hstepB;
;     const unsigned ldsw = (unsigned)wid * 1024u;
;     const int aoff = lds_byte(wr * 64 + fr, fq * 8), boff = lds_byte(wc * 32 + fr, fq * 8);
;     ...
;         PG8_STAGE(PG8_SB(1, 0), cB + kstep, voffB); PG8_STAGE(PG8_SA(1, 0), cA + kstep, voffA); PG8_STAGE(PG8_SB(1, 1), cB + hstepB + kstep, voffB);
;         PG8_WAIT_V(6); PG8_BAR;
.LBB0_1071:
	s_lshl_b32 s5, s5, 5
	s_and_b32 s66, s5, 0x60
	s_add_i32 m0, s61, 0x18000
	v_lshl_add_u64 v[6:7], v[6:7], 0, s[22:23]
	s_lshl_b32 s65, s6, 6
	s_lshl_b32 s36, s6, 13
	s_lshl_b32 s5, s66, 7
	s_waitcnt vmcnt(2)
	s_barrier
	global_load_lds_dwordx4 v[6:7], off
	v_lshl_add_u64 v[4:5], v[4:5], 0, s[22:23]
	s_add_i32 m0, s61, 0x1a000
	s_add_i32 s67, s61, 0x8000
	s_add_i32 s68, s61, 0xa000
	global_load_lds_dwordx4 v[4:5], off
	v_lshl_add_u64 v[0:1], v[0:1], 0, s[22:23]
	s_mov_b32 m0, s67
	s_add_u32 s6, s34, 0x40080
	global_load_lds_dwordx4 v[0:1], off
	v_lshl_add_u64 v[0:1], v[2:3], 0, s[22:23]
	s_mov_b32 m0, s68
	s_addc_u32 s7, s35, 0
	global_load_lds_dwordx4 v[0:1], off
	s_add_i32 m0, s61, 0x1c000
	v_lshl_add_u64 v[0:1], s[6:7], 0, v[192:193]
	global_load_lds_dwordx4 v[0:1], off
	v_lshl_add_u64 v[0:1], s[6:7], 0, v[198:199]
	s_add_i32 m0, s61, 0x1e000
	s_cmpk_lt_u32 s4, 0x100
	global_load_lds_dwordx4 v[0:1], off
	v_and_b32_e32 v0, 48, v9
	v_lshlrev_b32_e32 v1, 6, v9
	v_and_or_b32 v0, v1, s44, v0
	v_lshlrev_b32_e32 v1, 2, v9
	v_and_b32_e32 v1, 32, v1
	v_bitop3_b32 v2, v0, s36, v1 bitop3:0xde
	v_bitop3_b32 v234, s5, v0, v1 bitop3:0xf6
	v_lshrrev_b32_e32 v1, 1, v14
	v_mul_lo_u32 v0, v13, s47
	v_mad_u64_u32 v[0:1], s[4:5], v1, s43, v[0:1]
	v_or_b32_e32 v0, v0, v15
	v_add_lshl_u32 v0, v0, v16, 1
	v_mov_b32_e32 v1, v193
	v_lshl_add_u64 v[204:205], v[0:1], 0, s[24:25]
	v_lshrrev_b32_e32 v1, 1, v8
	v_mul_lo_u32 v0, v10, s47
	v_mad_u64_u32 v[0:1], s[4:5], v1, s43, v[0:1]
	s_waitcnt vmcnt(6)
	v_or_b32_e32 v0, v0, v11
	s_cselect_b64 s[36:37], -1, 0
	s_cmpk_gt_u32 s40, 0xff
	v_add_lshl_u32 v0, v0, v12, 1
	v_mov_b32_e32 v1, v193
	s_cselect_b64 s[38:39], -1, 0
	v_lshl_add_u64 v[206:207], v[0:1], 0, s[24:25]
	s_mov_b32 s69, 0
	v_add_u32_e32 v235, 0, v2
	s_mov_b32 s71, s2
	s_mov_b32 s72, s12
	s_cmp_lg_u32 s98, 0
	s_cbranch_scc1 .Lpg_x2_54
	s_barrier
.Lpg_x2_54:
	s_branch .LBB0_1074
.LBB0_1072:
	s_mov_b64 s[4:5], 0

; #define PG8_STAGE(bufoff, gbase, voff) do { _Pragma("unroll") for (int _i = 0; _i < 2; ++_i) \
;         __builtin_amdgcn_global_load_lds((const unsigned*)((const char*)(gbase) + (voff)[_i]), (PG8_LAS unsigned*)(lds + (bufoff) + ldsw + _i * 8192), 16, 0, 0); } while (0)
; #define PG8_LDA(dst, b, h) do { _Pragma("unroll") for (int m = 0; m < 4; ++m) _Pragma("unroll") for (int k = 0; k < 2; ++k) dst[m][k] = *(const PG8_LAS bf16x8*)(lds + PG8_SA(b, h) + aoff + m * 2048 + k * 1024); } while (0)
; #define PG8_LDB(dst, b, h) do { _Pragma("unroll") for (int n = 0; n < 2; ++n) _Pragma("unroll") for (int k = 0; k < 2; ++k) dst[n][k] = *(const PG8_LAS bf16x8*)(lds + PG8_SB(b, h) + boff + n * 2048 + k * 1024); } while (0)
; #define PG8_MMA(ai, bj, At, Bt) do { __builtin_amdgcn_s_setprio(1); _Pragma("unroll") for (int m = 0; m < 4; ++m) _Pragma("unroll") for (int n = 0; n < 2; ++n) _Pragma("unroll") for (int k = 0; k < 2; ++k) \
;         acc[ai][bj][m][n] = __builtin_amdgcn_mfma_f32_16x16x32_bf16(Bt[n][k], At[m][k], acc[ai][bj][m][n], 0, 0, 0); __builtin_amdgcn_s_setprio(0); } while (0)
; #define PG8_WAIT_V(n) asm volatile("s_waitcnt vmcnt(" #n ")" ::: "memory")
; #define PG8_WAIT_L(n) asm volatile("s_waitcnt lgkmcnt(" #n ")" ::: "memory")
; #define PG8_BAR __builtin_amdgcn_s_barrier()
; #define PG8_SCHED __builtin_amdgcn_sched_barrier(0)
;     ...
;             const bool last = (t == nt - 2);
;             const char* a1 = cA + (size_t)(t + 1) * kstep;
;             const char* a2 = last ? nA : cA + (size_t)(t + 2) * kstep; const char* b2 = last ? nB : cB + (size_t)(t + 2) * kstep;
;             const char* a3 = a2 + kstep; const char* b3 = b2 + kstep;
;             if (last && has_next) S.a_ready(nxt);
;             if constexpr (SP2) {
;             PG8_LDB(B0, 0, 0); PG8_LDB(B1, 0, 1); PG8_SCHED; PG8_LDA(At, 0, 0); PG8_STAGE(PG8_SA(1, 1), a1 + hstepA, voffA);
;             PG8_WAIT_V(8); PG8_WAIT_L(0); PG8_BAR; PG8_MMA(0, 0, At, B0); PG8_MMA(0, 1, At, B1); PG8_BAR; PG8_SCHED;
.LBB0_1083:
	s_add_u32 s6, s28, 0x100
	s_addc_u32 s7, s29, 0
	s_add_i32 s48, 0, 0x10000
	s_cmp_eq_u32 s76, 12
	s_cselect_b32 s41, s53, s7
	s_cselect_b32 s40, s52, s6
	s_cselect_b32 s35, s51, s75
	s_cselect_b32 s34, s73, s74
	s_add_i32 s49, 0, 0x14000
	v_add_u32_e32 v92, s48, v234
	v_add_u32_e32 v132, s49, v234
	ds_read_b128 v[64:67], v92
	ds_read_b128 v[68:71], v92 offset:1024
	ds_read_b128 v[80:83], v92 offset:2048
	ds_read_b128 v[92:95], v92 offset:3072
	ds_read_b128 v[104:107], v132
	ds_read_b128 v[108:111], v132 offset:1024
	ds_read_b128 v[120:123], v132 offset:2048
	ds_read_b128 v[132:135], v132 offset:3072
	v_lshl_add_u64 v[208:209], s[28:29], 0, v[204:205]
	s_add_i32 m0, s61, 0xc000
	ds_read_b128 v[152:155], v235
	ds_read_b128 v[164:167], v235 offset:1024
	ds_read_b128 v[168:171], v235 offset:2048
	ds_read_b128 v[172:175], v235 offset:3072
	ds_read_b128 v[176:179], v235 offset:4096
	ds_read_b128 v[180:183], v235 offset:5120
	ds_read_b128 v[184:187], v235 offset:6144
	ds_read_b128 v[188:191], v235 offset:7168
	global_load_lds_dwordx4 v[208:209], off
	v_lshl_add_u64 v[208:209], s[28:29], 0, v[206:207]
	s_add_i32 m0, s61, 0xe000
	s_nop 0
	global_load_lds_dwordx4 v[208:209], off
	s_waitcnt vmcnt(8)
	s_waitcnt lgkmcnt(0)
	s_setprio 1
	s_cmp_lg_u32 s98, 0
	s_cbranch_scc0 .Lpg_b1_46
	s_barrier
	s_setprio 2

; #define PG8_STAGE(bufoff, gbase, voff) do { _Pragma("unroll") for (int _i = 0; _i < 2; ++_i) \
;         __builtin_amdgcn_global_load_lds((const unsigned*)((const char*)(gbase) + (voff)[_i]), (PG8_LAS unsigned*)(lds + (bufoff) + ldsw + _i * 8192), 16, 0, 0); } while (0)
; #define PG8_LDA(dst, b, h) do { _Pragma("unroll") for (int m = 0; m < 4; ++m) _Pragma("unroll") for (int k = 0; k < 2; ++k) dst[m][k] = *(const PG8_LAS bf16x8*)(lds + PG8_SA(b, h) + aoff + m * 2048 + k * 1024); } while (0)
; #define PG8_MMA(ai, bj, At, Bt) do { __builtin_amdgcn_s_setprio(1); _Pragma("unroll") for (int m = 0; m < 4; ++m) _Pragma("unroll") for (int n = 0; n < 2; ++n) _Pragma("unroll") for (int k = 0; k < 2; ++k) \
;         acc[ai][bj][m][n] = __builtin_amdgcn_mfma_f32_16x16x32_bf16(Bt[n][k], At[m][k], acc[ai][bj][m][n], 0, 0, 0); __builtin_amdgcn_s_setprio(0); } while (0)
; #define PG8_WAIT_V(n) asm volatile("s_waitcnt vmcnt(" #n ")" ::: "memory")
; #define PG8_WAIT_L(n) asm volatile("s_waitcnt lgkmcnt(" #n ")" ::: "memory")
; #define PG8_BAR __builtin_amdgcn_s_barrier()
; #define PG8_SCHED __builtin_amdgcn_sched_barrier(0)
;     ...
;             PG8_LDA(At, 0, 1); PG8_STAGE(PG8_SB(0, 0), b2, voffB); PG8_STAGE(PG8_SB(0, 1), b2 + hstepB, voffB); PG8_STAGE(PG8_SA(0, 0), a2, voffA);
;             PG8_WAIT_V(8); PG8_WAIT_L(0); PG8_BAR; PG8_MMA(1, 0, At, B0); PG8_MMA(1, 1, At, B1); PG8_BAR; PG8_SCHED;
.Lpg_b2_47:
	s_add_i32 s28, s48, s58
	v_lshl_add_u64 v[208:209], s[34:35], 0, v[192:193]
	s_mov_b32 m0, s28
	ds_read_b128 v[152:155], v235 offset:16384
	ds_read_b128 v[164:167], v235 offset:17408
	ds_read_b128 v[168:171], v235 offset:18432
	ds_read_b128 v[172:175], v235 offset:19456
	ds_read_b128 v[176:179], v235 offset:20480
	ds_read_b128 v[180:183], v235 offset:21504
	ds_read_b128 v[184:187], v235 offset:22528
	ds_read_b128 v[188:191], v235 offset:23552
	global_load_lds_dwordx4 v[208:209], off
	s_add_i32 m0, s28, 0x2000
	s_add_u32 s28, s34, 0x40000
	v_lshl_add_u64 v[210:211], s[34:35], 0, v[198:199]
	s_addc_u32 s29, s35, 0
	s_add_i32 s48, s49, s58
	global_load_lds_dwordx4 v[210:211], off
	v_lshl_add_u64 v[212:213], s[28:29], 0, v[192:193]
	s_mov_b32 m0, s48
	v_lshl_add_u64 v[214:215], s[40:41], 0, v[200:201]
	global_load_lds_dwordx4 v[212:213], off
	v_lshl_add_u64 v[212:213], s[28:29], 0, v[198:199]
	s_add_i32 m0, s48, 0x2000
	s_nop 0
	global_load_lds_dwordx4 v[212:213], off
	v_lshl_add_u64 v[212:213], s[40:41], 0, v[202:203]
	s_mov_b32 m0, s61
	s_nop 0
	global_load_lds_dwordx4 v[212:213], off
	s_mov_b32 m0, s62
	s_nop 0
	global_load_lds_dwordx4 v[214:215], off
	s_waitcnt vmcnt(8)
	s_waitcnt lgkmcnt(0)
	s_setprio 1
	s_cmp_lg_u32 s98, 0
	s_cbranch_scc0 .Lpg_b1_48
	s_barrier
	s_setprio 2

; #define PG8_STAGE(bufoff, gbase, voff) do { _Pragma("unroll") for (int _i = 0; _i < 2; ++_i) \
;         __builtin_amdgcn_global_load_lds((const unsigned*)((const char*)(gbase) + (voff)[_i]), (PG8_LAS unsigned*)(lds + (bufoff) + ldsw + _i * 8192), 16, 0, 0); } while (0)
; #define PG8_LDA(dst, b, h) do { _Pragma("unroll") for (int m = 0; m < 4; ++m) _Pragma("unroll") for (int k = 0; k < 2; ++k) dst[m][k] = *(const PG8_LAS bf16x8*)(lds + PG8_SA(b, h) + aoff + m * 2048 + k * 1024); } while (0)
; #define PG8_LDB(dst, b, h) do { _Pragma("unroll") for (int n = 0; n < 2; ++n) _Pragma("unroll") for (int k = 0; k < 2; ++k) dst[n][k] = *(const PG8_LAS bf16x8*)(lds + PG8_SB(b, h) + boff + n * 2048 + k * 1024); } while (0)
; #define PG8_MMA(ai, bj, At, Bt) do { __builtin_amdgcn_s_setprio(1); _Pragma("unroll") for (int m = 0; m < 4; ++m) _Pragma("unroll") for (int n = 0; n < 2; ++n) _Pragma("unroll") for (int k = 0; k < 2; ++k) \
;         acc[ai][bj][m][n] = __builtin_amdgcn_mfma_f32_16x16x32_bf16(Bt[n][k], At[m][k], acc[ai][bj][m][n], 0, 0, 0); __builtin_amdgcn_s_setprio(0); } while (0)
; #define PG8_WAIT_V(n) asm volatile("s_waitcnt vmcnt(" #n ")" ::: "memory")
; #define PG8_WAIT_L(n) asm volatile("s_waitcnt lgkmcnt(" #n ")" ::: "memory")
; #define PG8_BAR __builtin_amdgcn_s_barrier()
; #define PG8_SCHED __builtin_amdgcn_sched_barrier(0)
;     ...
;             PG8_LDB(B0, 1, 0); PG8_LDB(B1, 1, 1); PG8_SCHED; PG8_LDA(At, 1, 0); PG8_STAGE(PG8_SA(0, 1), a2 + hstepA, voffA);
;             PG8_WAIT_V(8); PG8_WAIT_L(0); PG8_BAR; PG8_MMA(0, 0, At, B0); PG8_MMA(0, 1, At, B1); PG8_BAR; PG8_SCHED;
.Lpg_b2_49:
	s_add_i32 s48, 0, 0x18000
	s_add_i32 s49, 0, 0x1c000
	v_add_u32_e32 v92, s48, v234
	v_add_u32_e32 v132, s49, v234
	ds_read_b128 v[64:67], v92
	ds_read_b128 v[68:71], v92 offset:1024
	ds_read_b128 v[80:83], v92 offset:2048
	ds_read_b128 v[92:95], v92 offset:3072
	ds_read_b128 v[104:107], v132
	ds_read_b128 v[108:111], v132 offset:1024
	ds_read_b128 v[120:123], v132 offset:2048
	ds_read_b128 v[132:135], v132 offset:3072
	s_add_u32 s28, s40, 0x60000
	s_addc_u32 s29, s41, 0
	s_mov_b32 m0, s63
	v_lshl_add_u64 v[216:217], s[28:29], 0, v[202:203]
	ds_read_b128 v[152:155], v235 offset:32768
	ds_read_b128 v[164:167], v235 offset:33792
	ds_read_b128 v[168:171], v235 offset:34816
	ds_read_b128 v[172:175], v235 offset:35840
	ds_read_b128 v[176:179], v235 offset:36864
	ds_read_b128 v[180:183], v235 offset:37888
	ds_read_b128 v[184:187], v235 offset:38912
	ds_read_b128 v[188:191], v235 offset:39936
	global_load_lds_dwordx4 v[216:217], off
	v_lshl_add_u64 v[216:217], s[28:29], 0, v[200:201]
	s_mov_b32 m0, s64
	s_nop 0
	global_load_lds_dwordx4 v[216:217], off
	s_waitcnt vmcnt(8)
	s_waitcnt lgkmcnt(0)
	s_setprio 1
	s_cmp_lg_u32 s98, 0
	s_cbranch_scc0 .Lpg_b1_50
	s_barrier
	s_setprio 2

; #define PG8_STAGE(bufoff, gbase, voff) do { _Pragma("unroll") for (int _i = 0; _i < 2; ++_i) \
;         __builtin_amdgcn_global_load_lds((const unsigned*)((const char*)(gbase) + (voff)[_i]), (PG8_LAS unsigned*)(lds + (bufoff) + ldsw + _i * 8192), 16, 0, 0); } while (0)
; #define PG8_LDA(dst, b, h) do { _Pragma("unroll") for (int m = 0; m < 4; ++m) _Pragma("unroll") for (int k = 0; k < 2; ++k) dst[m][k] = *(const PG8_LAS bf16x8*)(lds + PG8_SA(b, h) + aoff + m * 2048 + k * 1024); } while (0)
; #define PG8_MMA(ai, bj, At, Bt) do { __builtin_amdgcn_s_setprio(1); _Pragma("unroll") for (int m = 0; m < 4; ++m) _Pragma("unroll") for (int n = 0; n < 2; ++n) _Pragma("unroll") for (int k = 0; k < 2; ++k) \
;         acc[ai][bj][m][n] = __builtin_amdgcn_mfma_f32_16x16x32_bf16(Bt[n][k], At[m][k], acc[ai][bj][m][n], 0, 0, 0); __builtin_amdgcn_s_setprio(0); } while (0)
; #define PG8_WAIT_V(n) asm volatile("s_waitcnt vmcnt(" #n ")" ::: "memory")
; #define PG8_WAIT_L(n) asm volatile("s_waitcnt lgkmcnt(" #n ")" ::: "memory")
; #define PG8_BAR __builtin_amdgcn_s_barrier()
; #define PG8_SCHED __builtin_amdgcn_sched_barrier(0)
;     ...
;             PG8_LDA(At, 1, 1); PG8_STAGE(PG8_SB(1, 0), b3, voffB); PG8_STAGE(PG8_SB(1, 1), b3 + hstepB, voffB); PG8_STAGE(PG8_SA(1, 0), a3, voffA);
;             PG8_WAIT_V(8); PG8_WAIT_L(0); PG8_BAR; PG8_MMA(1, 0, At, B0); PG8_MMA(1, 1, At, B1); PG8_BAR; PG8_SCHED;
.Lpg_b2_51:
	s_add_i32 s28, s48, s58
	v_lshl_add_u64 v[208:209], v[208:209], 0, s[22:23]
	s_mov_b32 m0, s28
	ds_read_b128 v[152:155], v235 offset:49152
	ds_read_b128 v[164:167], v235 offset:50176
	ds_read_b128 v[168:171], v235 offset:51200
	ds_read_b128 v[172:175], v235 offset:52224
	ds_read_b128 v[176:179], v235 offset:53248
	ds_read_b128 v[180:183], v235 offset:54272
	ds_read_b128 v[184:187], v235 offset:55296
	ds_read_b128 v[188:191], v235 offset:56320
	global_load_lds_dwordx4 v[208:209], off
	s_add_i32 m0, s28, 0x2000
	s_add_u32 s28, s34, 0x40080
	v_lshl_add_u64 v[208:209], v[210:211], 0, s[22:23]
	s_addc_u32 s29, s35, 0
	s_add_i32 s34, s49, s58
	global_load_lds_dwordx4 v[208:209], off
	v_lshl_add_u64 v[208:209], s[28:29], 0, v[192:193]
	s_mov_b32 m0, s34
	s_nop 0
	global_load_lds_dwordx4 v[208:209], off
	v_lshl_add_u64 v[208:209], s[28:29], 0, v[198:199]
	s_add_i32 m0, s34, 0x2000
	s_nop 0
	global_load_lds_dwordx4 v[208:209], off
	v_lshl_add_u64 v[208:209], v[212:213], 0, s[22:23]
	s_mov_b32 m0, s67
	s_nop 0
	global_load_lds_dwordx4 v[208:209], off
	v_lshl_add_u64 v[208:209], v[214:215], 0, s[22:23]
	s_mov_b32 m0, s68
	s_nop 0
	global_load_lds_dwordx4 v[208:209], off
	s_waitcnt vmcnt(8)
	s_waitcnt lgkmcnt(0)
	s_setprio 1
	s_cmp_lg_u32 s98, 0
	s_cbranch_scc0 .Lpg_b1_52
	s_barrier
	s_setprio 2

; #define PG8_BAR __builtin_amdgcn_s_barrier()
;     ...
;         for (int t = 0; t < nt; t += 2) {
;             const bool last = (t == nt - 2);
;     ...
;         }
;         if constexpr (ALIGN_EPI) { if (wr == 0) PG8_BAR; }
.Lpg_b2_53:
	s_add_i32 s76, s76, 2
	s_add_u32 s74, s74, 0x100
	s_addc_u32 s75, s75, 0
	s_cmp_gt_u32 s76, 13
	s_mov_b64 s[28:29], s[6:7]
	s_cbranch_scc0 .LBB0_1083
	s_and_b64 vcc, exec, s[36:37]
	s_cbranch_vccz .LBB0_1086

; #define PG8_BAR __builtin_amdgcn_s_barrier()
; DI void st8(bf16_t* p, const float (&v)[8]) { u32x4 w; w.x = cvtpk(v[0], v[1]); w.y = cvtpk(v[2], v[3]); w.z = cvtpk(v[4], v[5]); w.w = cvtpk(v[6], v[7]); *(u32x4*)p = w; }
; #define SBE() __builtin_amdgcn_sched_barrier(0)
; #define OUT_LOAD(itn, buf) do { const size_t rw_ = (size_t)(grow0 + ((itn) >> 2) * 128 + ((itn) & 3) * 16); BJLOOP { pg[buf][bj] = *(const u32x4*)(b.zG + rw_ * 3072 + brn * 1024 + tc0 + bj * 128); \
;                 if (accum) pm[buf][bj] = *(const u32x4*)(b.merged + rw_ * 1024 + tc0 + bj * 128); } } while (0)
;     ...
;         if constexpr (!Epi::AFTER_DRAIN) { E(acc, cur, wr, wc, fr, fq); S.done(cur); }
;         if (!has_next) break;
; #pragma unroll
;         for (int a = 0; a < 2; ++a)
; #pragma unroll
;             for (int b = 0; b < 2; ++b)
; #pragma unroll
;                 for (int m = 0; m < 4; ++m)
; #pragma unroll
;                     for (int n = 0; n < 2; ++n) acc[a][b][m][n] = (f32x4){0.f, 0.f, 0.f, 0.f};
;         cur = nxt; cA = nA; cB = nB; ++ui;
;         if constexpr (ALIGN_EPI) { if (wr == 1) PG8_BAR; }
;     DI void operator()(const AccT& acc, const pg8::Unit& u, int wr, int wc, int fr_in, int fq_in) const {
;     ...
;                     st8(b.merged + IT_ROW * 1024 + tc0 + bj * 128, v); }
;                 SBE(); if (it + 4 < 8) OUT_LOAD(it + 4, it & 3); SBE(); }
.LBB0_1182:
	v_cvt_pk_bf16_f32 v0, v12, v13
	v_cvt_pk_bf16_f32 v1, v18, v19
	v_cvt_pk_bf16_f32 v2, v20, v21
	v_cvt_pk_bf16_f32 v3, v22, v23
	global_store_dwordx4 v[84:85], v[0:3], off offset:256
	s_and_b64 vcc, exec, s[4:5]
	s_mov_b64 s[4:5], -1
	s_cbranch_vccnz .LBB0_1073
	s_andn2_b64 vcc, exec, s[10:11]
	s_cbranch_vccnz .LBB0_1072
	s_branch .LBB0_1072

; #define PG8_STAGE(bufoff, gbase, voff) do { _Pragma("unroll") for (int _i = 0; _i < 2; ++_i) \
;         __builtin_amdgcn_global_load_lds((const unsigned*)((const char*)(gbase) + (voff)[_i]), (PG8_LAS unsigned*)(lds + (bufoff) + ldsw + _i * 8192), 16, 0, 0); } while (0)
; #define PG8_WAIT_V(n) asm volatile("s_waitcnt vmcnt(" #n ")" ::: "memory")
; #define PG8_BAR __builtin_amdgcn_s_barrier()
;     ...
;     for (int i = 0; i < 2; ++i) { int R, C; stage_rc(tid * 16 + i * 8192, R, C); const int Rb = Epi::PERM ? ((R & ~31) + perm32(R & 31)) : R;
;         voffA[i] = (unsigned)(R * lda_ + C) * 2u; voffB[i] = (unsigned)(Rb * K + C) * 2u; }
;     const size_t kstep = (size_t)(BK * 2);
;     const size_t hstepA = (size_t)HALF * lda_ * 2, hstepB = (size_t)HALF * K * 2;
;     const size_t tstepA = 2 * hstepA, tstepB = 2 * hstepB;
;     const unsigned ldsw = (unsigned)wid * 1024u;
;     const int aoff = lds_byte(wr * 64 + fr, fq * 8), boff = lds_byte(wc * 32 + fr, fq * 8);
;     ...
;         PG8_STAGE(PG8_SB(1, 0), cB + kstep, voffB); PG8_STAGE(PG8_SA(1, 0), cA + kstep, voffA); PG8_STAGE(PG8_SB(1, 1), cB + hstepB + kstep, voffB);
;         PG8_WAIT_V(6); PG8_BAR;
.LBB0_1242:
	s_add_u32 s16, s6, 0x2e00000
	s_addc_u32 s17, s7, 0
	s_add_u32 s6, s6, 0x4800000
	s_addc_u32 s7, s7, 0
	s_lshl_b32 s51, s0, 6
	s_lshl_b32 s21, s0, 13
	s_lshl_b32 s0, s1, 5
	s_mov_b64 s[18:19], 0x80
	s_and_b32 s52, s0, 0x60
	s_add_i32 m0, s39, 0x18000
	v_lshl_add_u64 v[6:7], v[6:7], 0, s[18:19]
	s_lshl_b32 s22, s52, 7
	s_waitcnt vmcnt(2)
	s_barrier
	global_load_lds_dwordx4 v[6:7], off
	v_lshl_add_u64 v[4:5], v[4:5], 0, s[18:19]
	s_add_i32 m0, s39, 0x1a000
	s_add_i32 s53, s39, 0x8000
	s_add_i32 s54, s39, 0xa000
	global_load_lds_dwordx4 v[4:5], off
	v_lshl_add_u64 v[0:1], v[0:1], 0, s[18:19]
	s_mov_b32 m0, s53
	s_add_u32 s0, s34, 0x40080
	global_load_lds_dwordx4 v[0:1], off
	v_lshl_add_u64 v[0:1], v[2:3], 0, s[18:19]
	s_mov_b32 m0, s54
	s_addc_u32 s1, s35, 0
	global_load_lds_dwordx4 v[0:1], off
	s_add_i32 m0, s39, 0x1c000
	v_lshl_add_u64 v[0:1], s[0:1], 0, v[178:179]
	global_load_lds_dwordx4 v[0:1], off
	v_lshl_add_u64 v[0:1], s[0:1], 0, v[182:183]
	s_add_i32 m0, s39, 0x1e000
	s_movk_i32 s0, 0x3c0
	global_load_lds_dwordx4 v[0:1], off
	v_and_b32_e32 v0, 48, v8
	v_lshlrev_b32_e32 v1, 6, v8
	v_and_or_b32 v0, v1, s0, v0
	v_lshlrev_b32_e32 v1, 2, v8
	v_and_b32_e32 v1, 32, v1
	v_bitop3_b32 v2, v0, s21, v1 bitop3:0xde
	v_bitop3_b32 v202, s22, v0, v1 bitop3:0xf6
	v_lshlrev_b32_e32 v0, 14, v9
	v_and_b32_e32 v0, 0xffff8000, v0
	v_lshl_add_u32 v0, v10, 11, v0
	v_and_b32_e32 v1, 1, v9
	v_lshl_or_b32 v0, v1, 6, v0
	v_lshl_add_u32 v184, v11, 1, v0
	v_lshlrev_b32_e32 v0, 14, v12
	v_and_b32_e32 v0, 0xffff8000, v0
	s_waitcnt vmcnt(6)
	s_cmpk_lt_u32 s20, 0x100
	v_lshl_add_u32 v0, v13, 11, v0
	v_and_b32_e32 v1, 1, v12
	s_cselect_b64 s[20:21], -1, 0
	v_lshl_or_b32 v0, v1, 6, v0
	s_add_i32 s55, 0, 0x10000
	s_add_i32 s56, 0, 0x14000
	v_mov_b32_e32 v185, v179
	v_lshl_add_u32 v186, v14, 1, v0
	v_mov_b32_e32 v187, v179
	v_mov_b64_e32 v[188:189], 0x400
	v_mov_b64_e32 v[190:191], 0x3ff
	v_add_u32_e32 v203, s55, v202
	v_add_u32_e32 v204, s56, v202
	v_add_u32_e32 v205, 0, v2
	s_cmp_lg_u32 s98, 0
	s_cbranch_scc1 .Lpg_x2_63
	s_barrier
.Lpg_x2_63:
	s_branch .LBB0_1245
.LBB0_1243:
	s_mov_b64 s[0:1], 0

; #define PG8_STAGE(bufoff, gbase, voff) do { _Pragma("unroll") for (int _i = 0; _i < 2; ++_i) \
;         __builtin_amdgcn_global_load_lds((const unsigned*)((const char*)(gbase) + (voff)[_i]), (PG8_LAS unsigned*)(lds + (bufoff) + ldsw + _i * 8192), 16, 0, 0); } while (0)
; #define PG8_LDA(dst, b, h) do { _Pragma("unroll") for (int m = 0; m < 4; ++m) _Pragma("unroll") for (int k = 0; k < 2; ++k) dst[m][k] = *(const PG8_LAS bf16x8*)(lds + PG8_SA(b, h) + aoff + m * 2048 + k * 1024); } while (0)
; #define PG8_LDB(dst, b, h) do { _Pragma("unroll") for (int n = 0; n < 2; ++n) _Pragma("unroll") for (int k = 0; k < 2; ++k) dst[n][k] = *(const PG8_LAS bf16x8*)(lds + PG8_SB(b, h) + boff + n * 2048 + k * 1024); } while (0)
; #define PG8_MMA(ai, bj, At, Bt) do { __builtin_amdgcn_s_setprio(1); _Pragma("unroll") for (int m = 0; m < 4; ++m) _Pragma("unroll") for (int n = 0; n < 2; ++n) _Pragma("unroll") for (int k = 0; k < 2; ++k) \
;         acc[ai][bj][m][n] = __builtin_amdgcn_mfma_f32_16x16x32_bf16(Bt[n][k], At[m][k], acc[ai][bj][m][n], 0, 0, 0); __builtin_amdgcn_s_setprio(0); } while (0)
; #define PG8_WAIT_V(n) asm volatile("s_waitcnt vmcnt(" #n ")" ::: "memory")
; #define PG8_WAIT_L(n) asm volatile("s_waitcnt lgkmcnt(" #n ")" ::: "memory")
; #define PG8_BAR __builtin_amdgcn_s_barrier()
; #define PG8_SCHED __builtin_amdgcn_sched_barrier(0)
;     ...
;             PG8_LDB(B0, 0, 0); PG8_LDB(B1, 0, 1); PG8_SCHED; PG8_LDA(At, 0, 0); PG8_STAGE(PG8_SA(1, 1), a1 + hstepA, voffA);
;             PG8_WAIT_V(8); PG8_WAIT_L(0); PG8_BAR; PG8_MMA(0, 0, At, B0); PG8_MMA(0, 1, At, B1); PG8_BAR; PG8_SCHED;
.LBB0_1252:
	ds_read_b128 v[128:131], v203
	ds_read_b128 v[132:135], v203 offset:1024
	ds_read_b128 v[136:139], v203 offset:2048
	ds_read_b128 v[140:143], v203 offset:3072
	ds_read_b128 v[144:147], v204
	ds_read_b128 v[148:151], v204 offset:1024
	ds_read_b128 v[152:155], v204 offset:2048
	ds_read_b128 v[156:159], v204 offset:3072
	s_add_u32 s34, s28, 0xfffc0080
	s_addc_u32 s35, s29, -1
	s_cmp_eq_u32 s61, 12
	s_cselect_b32 s41, s25, s35
	s_cselect_b32 s40, s57, s34
	s_cselect_b32 s35, s23, s60
	s_cselect_b32 s34, s58, s59
	v_lshl_add_u64 v[200:201], s[28:29], 0, v[184:185]
	s_add_i32 m0, s39, 0xc000
	ds_read_b128 v[160:163], v205
	ds_read_b128 v[164:167], v205 offset:1024
	ds_read_b128 v[168:171], v205 offset:2048
	ds_read_b128 v[172:175], v205 offset:3072
	ds_read_b128 v[192:195], v205 offset:4096
	ds_read_b128 v[196:199], v205 offset:5120
	ds_read_b128 v[206:209], v205 offset:6144
	ds_read_b128 v[210:213], v205 offset:7168
	global_load_lds_dwordx4 v[200:201], off
	v_lshl_add_u64 v[200:201], s[28:29], 0, v[186:187]
	s_add_i32 m0, s39, 0xe000
	s_nop 0
	global_load_lds_dwordx4 v[200:201], off
	s_waitcnt vmcnt(8)
	s_waitcnt lgkmcnt(0)
	s_setprio 1
	s_cmp_lg_u32 s98, 0
	s_cbranch_scc0 .Lpg_b1_55
	s_barrier
	s_setprio 2
.Lpg_b1_55:
	s_waitcnt lgkmcnt(0)
	v_mfma_f32_16x16x32_bf16 v[124:127], v[128:131], v[160:163], v[124:127]
	v_mfma_f32_16x16x32_bf16 v[120:123], v[136:139], v[160:163], v[120:123]
	v_mfma_f32_16x16x32_bf16 v[108:111], v[128:131], v[168:171], v[108:111]
	v_mfma_f32_16x16x32_bf16 v[104:107], v[136:139], v[168:171], v[104:107]
	v_mfma_f32_16x16x32_bf16 v[92:95], v[128:131], v[192:195], v[92:95]
	v_mfma_f32_16x16x32_bf16 v[88:91], v[136:139], v[192:195], v[88:91]
	v_mfma_f32_16x16x32_bf16 v[76:79], v[128:131], v[206:209], v[76:79]
	v_mfma_f32_16x16x32_bf16 v[72:75], v[136:139], v[206:209], v[72:75]
	v_mfma_f32_16x16x32_bf16 v[124:127], v[132:135], v[164:167], v[124:127]
	v_mfma_f32_16x16x32_bf16 v[120:123], v[140:143], v[164:167], v[120:123]
	v_mfma_f32_16x16x32_bf16 v[108:111], v[132:135], v[172:175], v[108:111]
	v_mfma_f32_16x16x32_bf16 v[104:107], v[140:143], v[172:175], v[104:107]
	v_mfma_f32_16x16x32_bf16 v[92:95], v[132:135], v[196:199], v[92:95]
	v_mfma_f32_16x16x32_bf16 v[88:91], v[140:143], v[196:199], v[88:91]
	v_mfma_f32_16x16x32_bf16 v[76:79], v[132:135], v[210:213], v[76:79]
	v_mfma_f32_16x16x32_bf16 v[72:75], v[140:143], v[210:213], v[72:75]
	v_mfma_f32_16x16x32_bf16 v[116:119], v[144:147], v[160:163], v[116:119]
	v_mfma_f32_16x16x32_bf16 v[112:115], v[152:155], v[160:163], v[112:115]
	v_mfma_f32_16x16x32_bf16 v[100:103], v[144:147], v[168:171], v[100:103]
	v_mfma_f32_16x16x32_bf16 v[96:99], v[152:155], v[168:171], v[96:99]
	v_mfma_f32_16x16x32_bf16 v[84:87], v[144:147], v[192:195], v[84:87]
	v_mfma_f32_16x16x32_bf16 v[80:83], v[152:155], v[192:195], v[80:83]
	v_mfma_f32_16x16x32_bf16 v[68:71], v[144:147], v[206:209], v[68:71]
	v_mfma_f32_16x16x32_bf16 v[64:67], v[152:155], v[206:209], v[64:67]
	v_mfma_f32_16x16x32_bf16 v[116:119], v[148:151], v[164:167], v[116:119]
	v_mfma_f32_16x16x32_bf16 v[112:115], v[156:159], v[164:167], v[112:115]
	v_mfma_f32_16x16x32_bf16 v[100:103], v[148:151], v[172:175], v[100:103]
	v_mfma_f32_16x16x32_bf16 v[96:99], v[156:159], v[172:175], v[96:99]
	v_mfma_f32_16x16x32_bf16 v[84:87], v[148:151], v[196:199], v[84:87]
	v_mfma_f32_16x16x32_bf16 v[80:83], v[156:159], v[196:199], v[80:83]
	v_mfma_f32_16x16x32_bf16 v[68:71], v[148:151], v[210:213], v[68:71]
	v_mfma_f32_16x16x32_bf16 v[64:67], v[156:159], v[210:213], v[64:67]
	s_setprio 0
	s_cmp_lg_u32 s98, 0
	s_cbranch_scc1 .Lpg_b2_56
	s_barrier
; #define PG8_STAGE(bufoff, gbase, voff) do { _Pragma("unroll") for (int _i = 0; _i < 2; ++_i) \
;         __builtin_amdgcn_global_load_lds((const unsigned*)((const char*)(gbase) + (voff)[_i]), (PG8_LAS unsigned*)(lds + (bufoff) + ldsw + _i * 8192), 16, 0, 0); } while (0)
; #define PG8_LDA(dst, b, h) do { _Pragma("unroll") for (int m = 0; m < 4; ++m) _Pragma("unroll") for (int k = 0; k < 2; ++k) dst[m][k] = *(const PG8_LAS bf16x8*)(lds + PG8_SA(b, h) + aoff + m * 2048 + k * 1024); } while (0)
; #define PG8_LDB(dst, b, h) do { _Pragma("unroll") for (int n = 0; n < 2; ++n) _Pragma("unroll") for (int k = 0; k < 2; ++k) dst[n][k] = *(const PG8_LAS bf16x8*)(lds + PG8_SB(b, h) + boff + n * 2048 + k * 1024); } while (0)
; #define PG8_MMA(ai, bj, At, Bt) do { __builtin_amdgcn_s_setprio(1); _Pragma("unroll") for (int m = 0; m < 4; ++m) _Pragma("unroll") for (int n = 0; n < 2; ++n) _Pragma("unroll") for (int k = 0; k < 2; ++k) \
;         acc[ai][bj][m][n] = __builtin_amdgcn_mfma_f32_16x16x32_bf16(Bt[n][k], At[m][k], acc[ai][bj][m][n], 0, 0, 0); __builtin_amdgcn_s_setprio(0); } while (0)
; #define PG8_WAIT_V(n) asm volatile("s_waitcnt vmcnt(" #n ")" ::: "memory")
; #define PG8_WAIT_L(n) asm volatile("s_waitcnt lgkmcnt(" #n ")" ::: "memory")
; #define PG8_BAR __builtin_amdgcn_s_barrier()
; #define PG8_SCHED __builtin_amdgcn_sched_barrier(0)
;     ...
;             PG8_LDA(At, 0, 1); PG8_STAGE(PG8_SB(0, 0), b2, voffB); PG8_STAGE(PG8_SB(0, 1), b2 + hstepB, voffB); PG8_STAGE(PG8_SA(0, 0), a2, voffA);
;             PG8_WAIT_V(8); PG8_WAIT_L(0); PG8_BAR; PG8_MMA(1, 0, At, B0); PG8_MMA(1, 1, At, B1); PG8_BAR; PG8_SCHED;
;             PG8_LDB(B0, 1, 0); PG8_LDB(B1, 1, 1); PG8_SCHED; PG8_LDA(At, 1, 0); PG8_STAGE(PG8_SA(0, 1), a2 + hstepA, voffA);
;             PG8_WAIT_V(8); PG8_WAIT_L(0); PG8_BAR; PG8_MMA(0, 0, At, B0); PG8_MMA(0, 1, At, B1); PG8_BAR; PG8_SCHED;
.Lpg_b2_56:
	s_add_i32 s48, s55, s43
	v_lshl_add_u64 v[200:201], s[34:35], 0, v[178:179]
	s_mov_b32 m0, s48
	ds_read_b128 v[160:163], v205 offset:16384
	ds_read_b128 v[164:167], v205 offset:17408
	ds_read_b128 v[168:171], v205 offset:18432
	ds_read_b128 v[172:175], v205 offset:19456
	ds_read_b128 v[192:195], v205 offset:20480
	ds_read_b128 v[196:199], v205 offset:21504
	ds_read_b128 v[206:209], v205 offset:22528
	ds_read_b128 v[210:213], v205 offset:23552
	global_load_lds_dwordx4 v[200:201], off
	s_add_i32 m0, s48, 0x2000
	s_add_u32 s48, s34, 0x40000
	v_lshl_add_u64 v[214:215], s[34:35], 0, v[182:183]
	s_addc_u32 s49, s35, 0
	s_add_i32 s62, s56, s43
	global_load_lds_dwordx4 v[214:215], off
	v_lshl_add_u64 v[216:217], s[48:49], 0, v[178:179]
	s_mov_b32 m0, s62
	v_lshl_add_u64 v[218:219], s[40:41], 0, v[180:181]
	global_load_lds_dwordx4 v[216:217], off
	v_lshl_add_u64 v[216:217], s[48:49], 0, v[182:183]
	s_add_i32 m0, s62, 0x2000
	s_nop 0
	global_load_lds_dwordx4 v[216:217], off
	v_lshl_add_u64 v[216:217], s[40:41], 0, v[176:177]
	s_mov_b32 m0, s39
	s_nop 0
	global_load_lds_dwordx4 v[216:217], off
	s_mov_b32 m0, s45
	s_nop 0
	global_load_lds_dwordx4 v[218:219], off
	s_waitcnt vmcnt(8)
	s_waitcnt lgkmcnt(0)
	s_setprio 1
	s_cmp_lg_u32 s98, 0
	s_cbranch_scc0 .Lpg_b1_57
	s_barrier
	s_setprio 2
.Lpg_b1_57:
	s_waitcnt lgkmcnt(0)
	v_mfma_f32_16x16x32_bf16 v[60:63], v[128:131], v[160:163], v[60:63]
	v_mfma_f32_16x16x32_bf16 v[56:59], v[136:139], v[160:163], v[56:59]
	v_mfma_f32_16x16x32_bf16 v[44:47], v[128:131], v[168:171], v[44:47]
	v_mfma_f32_16x16x32_bf16 v[40:43], v[136:139], v[168:171], v[40:43]
	v_mfma_f32_16x16x32_bf16 v[28:31], v[128:131], v[192:195], v[28:31]
	v_mfma_f32_16x16x32_bf16 v[24:27], v[136:139], v[192:195], v[24:27]
	v_mfma_f32_16x16x32_bf16 v[12:15], v[128:131], v[206:209], v[12:15]
	v_mfma_f32_16x16x32_bf16 v[8:11], v[136:139], v[206:209], v[8:11]
	v_mfma_f32_16x16x32_bf16 v[60:63], v[132:135], v[164:167], v[60:63]
	v_mfma_f32_16x16x32_bf16 v[56:59], v[140:143], v[164:167], v[56:59]
	v_mfma_f32_16x16x32_bf16 v[44:47], v[132:135], v[172:175], v[44:47]
	v_mfma_f32_16x16x32_bf16 v[40:43], v[140:143], v[172:175], v[40:43]
	v_mfma_f32_16x16x32_bf16 v[28:31], v[132:135], v[196:199], v[28:31]
	v_mfma_f32_16x16x32_bf16 v[24:27], v[140:143], v[196:199], v[24:27]
	v_mfma_f32_16x16x32_bf16 v[12:15], v[132:135], v[210:213], v[12:15]
	v_mfma_f32_16x16x32_bf16 v[8:11], v[140:143], v[210:213], v[8:11]
	v_mfma_f32_16x16x32_bf16 v[52:55], v[144:147], v[160:163], v[52:55]
	v_mfma_f32_16x16x32_bf16 v[48:51], v[152:155], v[160:163], v[48:51]
	v_mfma_f32_16x16x32_bf16 v[36:39], v[144:147], v[168:171], v[36:39]
	v_mfma_f32_16x16x32_bf16 v[32:35], v[152:155], v[168:171], v[32:35]
	v_mfma_f32_16x16x32_bf16 v[20:23], v[144:147], v[192:195], v[20:23]
	v_mfma_f32_16x16x32_bf16 v[16:19], v[152:155], v[192:195], v[16:19]
	v_mfma_f32_16x16x32_bf16 v[4:7], v[144:147], v[206:209], v[4:7]
	v_mfma_f32_16x16x32_bf16 v[0:3], v[152:155], v[206:209], v[0:3]
	v_mfma_f32_16x16x32_bf16 v[52:55], v[148:151], v[164:167], v[52:55]
	v_mfma_f32_16x16x32_bf16 v[48:51], v[156:159], v[164:167], v[48:51]
	v_mfma_f32_16x16x32_bf16 v[36:39], v[148:151], v[172:175], v[36:39]
	v_mfma_f32_16x16x32_bf16 v[32:35], v[156:159], v[172:175], v[32:35]
	v_mfma_f32_16x16x32_bf16 v[20:23], v[148:151], v[196:199], v[20:23]
	v_mfma_f32_16x16x32_bf16 v[16:19], v[156:159], v[196:199], v[16:19]
	v_mfma_f32_16x16x32_bf16 v[4:7], v[148:151], v[210:213], v[4:7]
	v_mfma_f32_16x16x32_bf16 v[0:3], v[156:159], v[210:213], v[0:3]
	s_setprio 0
	s_cmp_lg_u32 s98, 0
	s_cbranch_scc1 .Lpg_b2_58
	s_barrier
.Lpg_b2_58:
	s_add_i32 s48, 0, 0x18000
	s_add_i32 s49, 0, 0x1c000
	v_add_u32_e32 v140, s48, v202
	v_add_u32_e32 v156, s49, v202
	ds_read_b128 v[128:131], v140
	ds_read_b128 v[132:135], v140 offset:1024
	ds_read_b128 v[136:139], v140 offset:2048
	ds_read_b128 v[140:143], v140 offset:3072
	ds_read_b128 v[144:147], v156
	ds_read_b128 v[148:151], v156 offset:1024
	ds_read_b128 v[152:155], v156 offset:2048
	ds_read_b128 v[156:159], v156 offset:3072
	s_add_u32 s40, s40, 0x40000
	s_addc_u32 s41, s41, 0
	s_mov_b32 m0, s46
	v_lshl_add_u64 v[220:221], s[40:41], 0, v[176:177]
	ds_read_b128 v[160:163], v205 offset:32768
	ds_read_b128 v[164:167], v205 offset:33792
	ds_read_b128 v[168:171], v205 offset:34816
	ds_read_b128 v[172:175], v205 offset:35840
	ds_read_b128 v[192:195], v205 offset:36864
	ds_read_b128 v[196:199], v205 offset:37888
	ds_read_b128 v[206:209], v205 offset:38912
	ds_read_b128 v[210:213], v205 offset:39936
	global_load_lds_dwordx4 v[220:221], off
	v_lshl_add_u64 v[220:221], s[40:41], 0, v[180:181]
	s_mov_b32 m0, s47
	s_nop 0
	global_load_lds_dwordx4 v[220:221], off
	s_waitcnt vmcnt(8)
	s_waitcnt lgkmcnt(0)
	s_setprio 1
	s_cmp_lg_u32 s98, 0
	s_cbranch_scc0 .Lpg_b1_59
	s_barrier
	s_setprio 2

; #define PG8_STAGE(bufoff, gbase, voff) do { _Pragma("unroll") for (int _i = 0; _i < 2; ++_i) \
;         __builtin_amdgcn_global_load_lds((const unsigned*)((const char*)(gbase) + (voff)[_i]), (PG8_LAS unsigned*)(lds + (bufoff) + ldsw + _i * 8192), 16, 0, 0); } while (0)
; #define PG8_LDA(dst, b, h) do { _Pragma("unroll") for (int m = 0; m < 4; ++m) _Pragma("unroll") for (int k = 0; k < 2; ++k) dst[m][k] = *(const PG8_LAS bf16x8*)(lds + PG8_SA(b, h) + aoff + m * 2048 + k * 1024); } while (0)
; #define PG8_MMA(ai, bj, At, Bt) do { __builtin_amdgcn_s_setprio(1); _Pragma("unroll") for (int m = 0; m < 4; ++m) _Pragma("unroll") for (int n = 0; n < 2; ++n) _Pragma("unroll") for (int k = 0; k < 2; ++k) \
;         acc[ai][bj][m][n] = __builtin_amdgcn_mfma_f32_16x16x32_bf16(Bt[n][k], At[m][k], acc[ai][bj][m][n], 0, 0, 0); __builtin_amdgcn_s_setprio(0); } while (0)
; #define PG8_WAIT_V(n) asm volatile("s_waitcnt vmcnt(" #n ")" ::: "memory")
; #define PG8_WAIT_L(n) asm volatile("s_waitcnt lgkmcnt(" #n ")" ::: "memory")
; #define PG8_BAR __builtin_amdgcn_s_barrier()
; #define PG8_SCHED __builtin_amdgcn_sched_barrier(0)
;     ...
;             PG8_LDA(At, 1, 1); PG8_STAGE(PG8_SB(1, 0), b3, voffB); PG8_STAGE(PG8_SB(1, 1), b3 + hstepB, voffB); PG8_STAGE(PG8_SA(1, 0), a3, voffA);
;             PG8_WAIT_V(8); PG8_WAIT_L(0); PG8_BAR; PG8_MMA(1, 0, At, B0); PG8_MMA(1, 1, At, B1); PG8_BAR; PG8_SCHED;
.Lpg_b2_60:
	s_add_i32 s40, s48, s43
	v_lshl_add_u64 v[200:201], v[200:201], 0, s[18:19]
	s_mov_b32 m0, s40
	ds_read_b128 v[160:163], v205 offset:49152
	ds_read_b128 v[164:167], v205 offset:50176
	ds_read_b128 v[168:171], v205 offset:51200
	ds_read_b128 v[172:175], v205 offset:52224
	ds_read_b128 v[192:195], v205 offset:53248
	ds_read_b128 v[196:199], v205 offset:54272
	ds_read_b128 v[206:209], v205 offset:55296
	ds_read_b128 v[210:213], v205 offset:56320
	global_load_lds_dwordx4 v[200:201], off
	s_add_i32 m0, s40, 0x2000
	s_add_u32 s34, s34, 0x40080
	v_lshl_add_u64 v[200:201], v[214:215], 0, s[18:19]
	s_addc_u32 s35, s35, 0
	s_add_i32 s40, s49, s43
	global_load_lds_dwordx4 v[200:201], off
	v_lshl_add_u64 v[200:201], s[34:35], 0, v[178:179]
	s_mov_b32 m0, s40
	s_nop 0
	global_load_lds_dwordx4 v[200:201], off
	v_lshl_add_u64 v[200:201], s[34:35], 0, v[182:183]
	s_add_i32 m0, s40, 0x2000
	s_nop 0
	global_load_lds_dwordx4 v[200:201], off
	v_lshl_add_u64 v[200:201], v[216:217], 0, s[18:19]
	s_mov_b32 m0, s53
	s_nop 0
	global_load_lds_dwordx4 v[200:201], off
	v_lshl_add_u64 v[200:201], v[218:219], 0, s[18:19]
	s_mov_b32 m0, s54
	s_nop 0
	global_load_lds_dwordx4 v[200:201], off
	s_waitcnt vmcnt(8)
	s_waitcnt lgkmcnt(0)
	s_setprio 1
	s_cmp_lg_u32 s98, 0
	s_cbranch_scc0 .Lpg_b1_61
	s_barrier
	s_setprio 2

; #define PG8_BAR __builtin_amdgcn_s_barrier()
;     ...
;         for (int t = 0; t < nt; t += 2) {
;             const bool last = (t == nt - 2);
;     ...
;         }
;         if constexpr (ALIGN_EPI) { if (wr == 0) PG8_BAR; }
.Lpg_b2_62:
	s_add_i32 s61, s61, 2
	s_add_u32 s28, s28, 0x100
	s_addc_u32 s29, s29, 0
	s_add_u32 s59, s59, 0x100
	s_addc_u32 s60, s60, 0
	s_cmp_gt_u32 s61, 13
	s_cbranch_scc0 .LBB0_1252
	s_and_b64 vcc, exec, s[20:21]
	s_cbranch_vccz .LBB0_1255

; #define PG8_BAR __builtin_amdgcn_s_barrier()
; DI float xsum16(float s) { const auto r = __builtin_amdgcn_permlane16_swap(__float_as_uint(s), __float_as_uint(s), false, false); return __uint_as_float(r[0]) + __uint_as_float(r[1]); }
; DI float xsum32(float s) { const auto r = __builtin_amdgcn_permlane32_swap(__float_as_uint(s), __float_as_uint(s), false, false); return __uint_as_float(r[0]) + __uint_as_float(r[1]); }
; #define SBE() __builtin_amdgcn_sched_barrier(0)
; #define RES_LOAD(itn, buf) do { const float* p_ = b.x + (size_t)(grow0 + ((itn) >> 2) * 128 + ((itn) & 3) * 16) * 1024 + tc0; BJLOOP { px[buf][bj][0] = *(const f32x4*)(p_ + bj * 128); px[buf][bj][1] = *(const f32x4*)(p_ + bj * 128 + 4); } } while (0)
; #define RES_LOAD(itn, buf) do { const bf16_t* p_ = b.x1b + (size_t)(grow0 + ((itn) >> 2) * 128 + ((itn) & 3) * 16) * 1024 + tc0; BJLOOP { px[buf][bj] = *(const u32x4*)(p_ + bj * 128); } } while (0)
;     ...
;         if constexpr (!Epi::AFTER_DRAIN) { E(acc, cur, wr, wc, fr, fq); S.done(cur); }
;         if (!has_next) break;
; #pragma unroll
;         for (int a = 0; a < 2; ++a)
; #pragma unroll
;             for (int b = 0; b < 2; ++b)
; #pragma unroll
;                 for (int m = 0; m < 4; ++m)
; #pragma unroll
;                     for (int n = 0; n < 2; ++n) acc[a][b][m][n] = (f32x4){0.f, 0.f, 0.f, 0.f};
;         cur = nxt; cA = nA; cB = nB; ++ui;
;         if constexpr (ALIGN_EPI) { if (wr == 1) PG8_BAR; }
;     DI void operator()(const AccT& acc, const pg8::Unit& u, int wr, int wc, int fr_in, int fq_in) const {
;     ...
;                 s = xsum16(s); s = xsum32(s); if (fq == 0) __hip_atomic_fetch_add(b.ssq2 + IT_ROW, s, __ATOMIC_RELAXED, __HIP_MEMORY_SCOPE_AGENT);
;                 SBE(); if (it + 4 < 8) RES_LOAD(it + 4, it & 3); SBE(); }
.LBB0_1271:
	s_or_b64 exec, exec, s[28:29]
	s_andn2_b64 vcc, exec, s[0:1]
	s_mov_b64 s[0:1], -1
	s_cbranch_vccnz .LBB0_1244
	s_andn2_b64 vcc, exec, s[10:11]
	s_cbranch_vccnz .LBB0_1243
	s_branch .LBB0_1243

; #define PG8_STAGE(bufoff, gbase, voff) do { _Pragma("unroll") for (int _i = 0; _i < 2; ++_i) \
;         __builtin_amdgcn_global_load_lds((const unsigned*)((const char*)(gbase) + (voff)[_i]), (PG8_LAS unsigned*)(lds + (bufoff) + ldsw + _i * 8192), 16, 0, 0); } while (0)
; #define PG8_WAIT_V(n) asm volatile("s_waitcnt vmcnt(" #n ")" ::: "memory")
; #define PG8_BAR __builtin_amdgcn_s_barrier()
;     ...
;     for (int i = 0; i < 2; ++i) { int R, C; stage_rc(tid * 16 + i * 8192, R, C); const int Rb = Epi::PERM ? ((R & ~31) + perm32(R & 31)) : R;
;         voffA[i] = (unsigned)(R * lda_ + C) * 2u; voffB[i] = (unsigned)(Rb * K + C) * 2u; }
;     const size_t kstep = (size_t)(BK * 2);
;     const size_t hstepA = (size_t)HALF * lda_ * 2, hstepB = (size_t)HALF * K * 2;
;     const size_t tstepA = 2 * hstepA, tstepB = 2 * hstepB;
;     const unsigned ldsw = (unsigned)wid * 1024u;
;     const int aoff = lds_byte(wr * 64 + fr, fq * 8), boff = lds_byte(wc * 32 + fr, fq * 8);
;     ...
;         PG8_STAGE(PG8_SB(1, 0), cB + kstep, voffB); PG8_STAGE(PG8_SA(1, 0), cA + kstep, voffA); PG8_STAGE(PG8_SB(1, 1), cB + hstepB + kstep, voffB);
;         PG8_WAIT_V(6); PG8_BAR;
.LBB0_1331:
	s_add_u32 s6, s0, 0x2e00000
	s_addc_u32 s7, s1, 0
	s_add_u32 s8, s0, 0xc800000
	s_addc_u32 s9, s1, 0
	s_lshl_b32 s50, s11, 6
	s_lshl_b32 s18, s11, 13
	s_lshl_b32 s0, s10, 5
	s_mov_b64 s[10:11], 0x80
	s_and_b32 s51, s0, 0x60
	s_add_i32 m0, s29, 0x18000
	v_lshl_add_u64 v[6:7], v[6:7], 0, s[10:11]
	s_lshl_b32 s19, s51, 7
	s_waitcnt vmcnt(2)
	s_barrier
	global_load_lds_dwordx4 v[6:7], off
	v_lshl_add_u64 v[4:5], v[4:5], 0, s[10:11]
	s_add_i32 m0, s29, 0x1a000
	s_add_i32 s52, s29, 0x8000
	s_add_i32 s53, s29, 0xa000
	global_load_lds_dwordx4 v[4:5], off
	v_lshl_add_u64 v[0:1], v[0:1], 0, s[10:11]
	s_mov_b32 m0, s52
	s_add_u32 s0, s36, 0x40080
	global_load_lds_dwordx4 v[0:1], off
	v_lshl_add_u64 v[0:1], v[2:3], 0, s[10:11]
	s_mov_b32 m0, s53
	s_addc_u32 s1, s37, 0
	global_load_lds_dwordx4 v[0:1], off
	s_add_i32 m0, s29, 0x1c000
	v_lshl_add_u64 v[0:1], s[0:1], 0, v[132:133]
	global_load_lds_dwordx4 v[0:1], off
	v_lshl_add_u64 v[0:1], s[0:1], 0, v[128:129]
	s_add_i32 m0, s29, 0x1e000
	s_movk_i32 s0, 0x3c0
	global_load_lds_dwordx4 v[0:1], off
	v_and_b32_e32 v0, 48, v8
	v_lshlrev_b32_e32 v1, 6, v8
	v_and_or_b32 v0, v1, s0, v0
	v_lshlrev_b32_e32 v1, 2, v8
	v_and_b32_e32 v1, 32, v1
	v_bitop3_b32 v2, v0, s18, v1 bitop3:0xde
	v_bitop3_b32 v149, s19, v0, v1 bitop3:0xf6
	v_lshlrev_b32_e32 v0, 14, v13
	v_and_b32_e32 v0, 0xffff8000, v0
	v_lshl_add_u32 v0, v12, 11, v0
	v_and_b32_e32 v1, 1, v13
	v_lshl_or_b32 v0, v1, 6, v0
	v_lshl_add_u32 v136, v14, 1, v0
	v_lshlrev_b32_e32 v0, 14, v9
	v_and_b32_e32 v0, 0xffff8000, v0
	s_waitcnt vmcnt(6)
	s_cmpk_lt_u32 s17, 0x100
	v_lshl_add_u32 v0, v10, 11, v0
	v_and_b32_e32 v1, 1, v9
	s_sext_i32_i8 s57, s16
	s_cselect_b64 s[16:17], -1, 0
	v_lshl_or_b32 v0, v1, 6, v0
	s_add_i32 s54, 0, 0x10000
	s_add_i32 s55, 0, 0x14000
	v_mov_b32_e32 v137, v133
	v_lshl_add_u32 v138, v11, 1, v0
	v_mov_b32_e32 v139, v133
	v_mov_b64_e32 v[140:141], 0x1000
	v_mov_b64_e32 v[142:143], 0xfff
	v_add_u32_e32 v151, s54, v149
	v_add_u32_e32 v153, s55, v149
	v_add_u32_e32 v157, 0, v2
	v_mov_b32_e32 v159, 0x358637bd
	s_mov_b64 s[18:19], 0x100000
	s_mov_b32 s56, 0x100000
	s_cmp_lg_u32 s98, 0
	s_cbranch_scc1 .Lpg_x2_72
	s_barrier
.Lpg_x2_72:
	s_branch .LBB0_1334
.LBB0_1332:
	s_mov_b64 s[0:1], 0

; #define PG8_STAGE(bufoff, gbase, voff) do { _Pragma("unroll") for (int _i = 0; _i < 2; ++_i) \
;         __builtin_amdgcn_global_load_lds((const unsigned*)((const char*)(gbase) + (voff)[_i]), (PG8_LAS unsigned*)(lds + (bufoff) + ldsw + _i * 8192), 16, 0, 0); } while (0)
; #define PG8_LDA(dst, b, h) do { _Pragma("unroll") for (int m = 0; m < 4; ++m) _Pragma("unroll") for (int k = 0; k < 2; ++k) dst[m][k] = *(const PG8_LAS bf16x8*)(lds + PG8_SA(b, h) + aoff + m * 2048 + k * 1024); } while (0)
; #define PG8_LDB(dst, b, h) do { _Pragma("unroll") for (int n = 0; n < 2; ++n) _Pragma("unroll") for (int k = 0; k < 2; ++k) dst[n][k] = *(const PG8_LAS bf16x8*)(lds + PG8_SB(b, h) + boff + n * 2048 + k * 1024); } while (0)
; #define PG8_MMA(ai, bj, At, Bt) do { __builtin_amdgcn_s_setprio(1); _Pragma("unroll") for (int m = 0; m < 4; ++m) _Pragma("unroll") for (int n = 0; n < 2; ++n) _Pragma("unroll") for (int k = 0; k < 2; ++k) \
;         acc[ai][bj][m][n] = __builtin_amdgcn_mfma_f32_16x16x32_bf16(Bt[n][k], At[m][k], acc[ai][bj][m][n], 0, 0, 0); __builtin_amdgcn_s_setprio(0); } while (0)
; #define PG8_WAIT_V(n) asm volatile("s_waitcnt vmcnt(" #n ")" ::: "memory")
; #define PG8_WAIT_L(n) asm volatile("s_waitcnt lgkmcnt(" #n ")" ::: "memory")
; #define PG8_BAR __builtin_amdgcn_s_barrier()
; #define PG8_SCHED __builtin_amdgcn_sched_barrier(0)
;     ...
;             PG8_LDB(B0, 0, 0); PG8_LDB(B1, 0, 1); PG8_SCHED; PG8_LDA(At, 0, 0); PG8_STAGE(PG8_SA(1, 1), a1 + hstepA, voffA);
;             PG8_WAIT_V(8); PG8_WAIT_L(0); PG8_BAR; PG8_MMA(0, 0, At, B0); PG8_MMA(0, 1, At, B1); PG8_BAR; PG8_SCHED;
.LBB0_1341:
	ds_read_b128 v[144:147], v151
	ds_read_b128 v[160:163], v151 offset:1024
	ds_read_b128 v[164:167], v151 offset:2048
	ds_read_b128 v[168:171], v151 offset:3072
	ds_read_b128 v[172:175], v153
	ds_read_b128 v[176:179], v153 offset:1024
	ds_read_b128 v[180:183], v153 offset:2048
	ds_read_b128 v[184:187], v153 offset:3072
	s_add_u32 s36, s34, 0xfffc0080
	s_addc_u32 s37, s35, -1
	s_cmp_eq_u32 s62, 12
	s_cselect_b32 s39, s23, s37
	s_cselect_b32 s38, s58, s36
	s_cselect_b32 s37, s21, s61
	s_cselect_b32 s36, s59, s60
	v_lshl_add_u64 v[154:155], s[34:35], 0, v[136:137]
	s_add_i32 m0, s29, 0xc000
	ds_read_b128 v[188:191], v157
	ds_read_b128 v[192:195], v157 offset:1024
	ds_read_b128 v[196:199], v157 offset:2048
	ds_read_b128 v[200:203], v157 offset:3072
	ds_read_b128 v[204:207], v157 offset:4096
	ds_read_b128 v[208:211], v157 offset:5120
	ds_read_b128 v[212:215], v157 offset:6144
	ds_read_b128 v[216:219], v157 offset:7168
	global_load_lds_dwordx4 v[154:155], off
	v_lshl_add_u64 v[154:155], s[34:35], 0, v[138:139]
	s_add_i32 m0, s29, 0xe000
	s_nop 0
	global_load_lds_dwordx4 v[154:155], off
	s_waitcnt vmcnt(8)
	s_waitcnt lgkmcnt(0)
	s_setprio 1
	s_cmp_lg_u32 s98, 0
	s_cbranch_scc0 .Lpg_b1_64
	s_barrier
	s_setprio 2
.Lpg_b1_64:
	s_waitcnt lgkmcnt(0)
	v_mfma_f32_16x16x32_bf16 v[124:127], v[144:147], v[188:191], v[124:127]
	v_mfma_f32_16x16x32_bf16 v[120:123], v[164:167], v[188:191], v[120:123]
	v_mfma_f32_16x16x32_bf16 v[108:111], v[144:147], v[196:199], v[108:111]
	v_mfma_f32_16x16x32_bf16 v[104:107], v[164:167], v[196:199], v[104:107]
	v_mfma_f32_16x16x32_bf16 v[92:95], v[144:147], v[204:207], v[92:95]
	v_mfma_f32_16x16x32_bf16 v[88:91], v[164:167], v[204:207], v[88:91]
	v_mfma_f32_16x16x32_bf16 v[76:79], v[144:147], v[212:215], v[76:79]
	v_mfma_f32_16x16x32_bf16 v[72:75], v[164:167], v[212:215], v[72:75]
	v_mfma_f32_16x16x32_bf16 v[124:127], v[160:163], v[192:195], v[124:127]
	v_mfma_f32_16x16x32_bf16 v[120:123], v[168:171], v[192:195], v[120:123]
	v_mfma_f32_16x16x32_bf16 v[108:111], v[160:163], v[200:203], v[108:111]
	v_mfma_f32_16x16x32_bf16 v[104:107], v[168:171], v[200:203], v[104:107]
	v_mfma_f32_16x16x32_bf16 v[92:95], v[160:163], v[208:211], v[92:95]
	v_mfma_f32_16x16x32_bf16 v[88:91], v[168:171], v[208:211], v[88:91]
	v_mfma_f32_16x16x32_bf16 v[76:79], v[160:163], v[216:219], v[76:79]
	v_mfma_f32_16x16x32_bf16 v[72:75], v[168:171], v[216:219], v[72:75]
	v_mfma_f32_16x16x32_bf16 v[116:119], v[172:175], v[188:191], v[116:119]
	v_mfma_f32_16x16x32_bf16 v[112:115], v[180:183], v[188:191], v[112:115]
	v_mfma_f32_16x16x32_bf16 v[100:103], v[172:175], v[196:199], v[100:103]
	v_mfma_f32_16x16x32_bf16 v[96:99], v[180:183], v[196:199], v[96:99]
	v_mfma_f32_16x16x32_bf16 v[84:87], v[172:175], v[204:207], v[84:87]
	v_mfma_f32_16x16x32_bf16 v[80:83], v[180:183], v[204:207], v[80:83]
	v_mfma_f32_16x16x32_bf16 v[68:71], v[172:175], v[212:215], v[68:71]
	v_mfma_f32_16x16x32_bf16 v[64:67], v[180:183], v[212:215], v[64:67]
	v_mfma_f32_16x16x32_bf16 v[116:119], v[176:179], v[192:195], v[116:119]
	v_mfma_f32_16x16x32_bf16 v[112:115], v[184:187], v[192:195], v[112:115]
	v_mfma_f32_16x16x32_bf16 v[100:103], v[176:179], v[200:203], v[100:103]
	v_mfma_f32_16x16x32_bf16 v[96:99], v[184:187], v[200:203], v[96:99]
	v_mfma_f32_16x16x32_bf16 v[84:87], v[176:179], v[208:211], v[84:87]
	v_mfma_f32_16x16x32_bf16 v[80:83], v[184:187], v[208:211], v[80:83]
	v_mfma_f32_16x16x32_bf16 v[68:71], v[176:179], v[216:219], v[68:71]
	v_mfma_f32_16x16x32_bf16 v[64:67], v[184:187], v[216:219], v[64:67]
	s_setprio 0
	s_cmp_lg_u32 s98, 0
	s_cbranch_scc1 .Lpg_b2_65
	s_barrier
; #define PG8_STAGE(bufoff, gbase, voff) do { _Pragma("unroll") for (int _i = 0; _i < 2; ++_i) \
;         __builtin_amdgcn_global_load_lds((const unsigned*)((const char*)(gbase) + (voff)[_i]), (PG8_LAS unsigned*)(lds + (bufoff) + ldsw + _i * 8192), 16, 0, 0); } while (0)
; #define PG8_LDA(dst, b, h) do { _Pragma("unroll") for (int m = 0; m < 4; ++m) _Pragma("unroll") for (int k = 0; k < 2; ++k) dst[m][k] = *(const PG8_LAS bf16x8*)(lds + PG8_SA(b, h) + aoff + m * 2048 + k * 1024); } while (0)
; #define PG8_LDB(dst, b, h) do { _Pragma("unroll") for (int n = 0; n < 2; ++n) _Pragma("unroll") for (int k = 0; k < 2; ++k) dst[n][k] = *(const PG8_LAS bf16x8*)(lds + PG8_SB(b, h) + boff + n * 2048 + k * 1024); } while (0)
; #define PG8_MMA(ai, bj, At, Bt) do { __builtin_amdgcn_s_setprio(1); _Pragma("unroll") for (int m = 0; m < 4; ++m) _Pragma("unroll") for (int n = 0; n < 2; ++n) _Pragma("unroll") for (int k = 0; k < 2; ++k) \
;         acc[ai][bj][m][n] = __builtin_amdgcn_mfma_f32_16x16x32_bf16(Bt[n][k], At[m][k], acc[ai][bj][m][n], 0, 0, 0); __builtin_amdgcn_s_setprio(0); } while (0)
; #define PG8_WAIT_V(n) asm volatile("s_waitcnt vmcnt(" #n ")" ::: "memory")
; #define PG8_WAIT_L(n) asm volatile("s_waitcnt lgkmcnt(" #n ")" ::: "memory")
; #define PG8_BAR __builtin_amdgcn_s_barrier()
; #define PG8_SCHED __builtin_amdgcn_sched_barrier(0)
;     ...
;             PG8_LDA(At, 0, 1); PG8_STAGE(PG8_SB(0, 0), b2, voffB); PG8_STAGE(PG8_SB(0, 1), b2 + hstepB, voffB); PG8_STAGE(PG8_SA(0, 0), a2, voffA);
;             PG8_WAIT_V(8); PG8_WAIT_L(0); PG8_BAR; PG8_MMA(1, 0, At, B0); PG8_MMA(1, 1, At, B1); PG8_BAR; PG8_SCHED;
;             PG8_LDB(B0, 1, 0); PG8_LDB(B1, 1, 1); PG8_SCHED; PG8_LDA(At, 1, 0); PG8_STAGE(PG8_SA(0, 1), a2 + hstepA, voffA);
;             PG8_WAIT_V(8); PG8_WAIT_L(0); PG8_BAR; PG8_MMA(0, 0, At, B0); PG8_MMA(0, 1, At, B1); PG8_BAR; PG8_SCHED;
.Lpg_b2_65:
	s_add_i32 s48, s54, s43
	v_lshl_add_u64 v[154:155], s[36:37], 0, v[132:133]
	s_mov_b32 m0, s48
	ds_read_b128 v[188:191], v157 offset:16384
	ds_read_b128 v[192:195], v157 offset:17408
	ds_read_b128 v[196:199], v157 offset:18432
	ds_read_b128 v[200:203], v157 offset:19456
	ds_read_b128 v[204:207], v157 offset:20480
	ds_read_b128 v[208:211], v157 offset:21504
	ds_read_b128 v[212:215], v157 offset:22528
	ds_read_b128 v[216:219], v157 offset:23552
	global_load_lds_dwordx4 v[154:155], off
	s_add_i32 m0, s48, 0x2000
	s_add_u32 s48, s36, 0x40000
	v_lshl_add_u64 v[220:221], s[36:37], 0, v[128:129]
	s_addc_u32 s49, s37, 0
	s_add_i32 s63, s55, s43
	global_load_lds_dwordx4 v[220:221], off
	v_lshl_add_u64 v[222:223], s[48:49], 0, v[132:133]
	s_mov_b32 m0, s63
	v_lshl_add_u64 v[224:225], s[38:39], 0, v[130:131]
	global_load_lds_dwordx4 v[222:223], off
	v_lshl_add_u64 v[222:223], s[48:49], 0, v[128:129]
	s_add_i32 m0, s63, 0x2000
	s_nop 0
	global_load_lds_dwordx4 v[222:223], off
	v_lshl_add_u64 v[222:223], s[38:39], 0, v[134:135]
	s_mov_b32 m0, s29
	s_nop 0
	global_load_lds_dwordx4 v[222:223], off
	s_mov_b32 m0, s44
	s_nop 0
	global_load_lds_dwordx4 v[224:225], off
	s_waitcnt vmcnt(8)
	s_waitcnt lgkmcnt(0)
	s_setprio 1
	s_cmp_lg_u32 s98, 0
	s_cbranch_scc0 .Lpg_b1_66
	s_barrier
	s_setprio 2
.Lpg_b1_66:
	s_waitcnt lgkmcnt(0)
	v_mfma_f32_16x16x32_bf16 v[60:63], v[144:147], v[188:191], v[60:63]
	v_mfma_f32_16x16x32_bf16 v[56:59], v[164:167], v[188:191], v[56:59]
	v_mfma_f32_16x16x32_bf16 v[44:47], v[144:147], v[196:199], v[44:47]
	v_mfma_f32_16x16x32_bf16 v[40:43], v[164:167], v[196:199], v[40:43]
	v_mfma_f32_16x16x32_bf16 v[28:31], v[144:147], v[204:207], v[28:31]
	v_mfma_f32_16x16x32_bf16 v[24:27], v[164:167], v[204:207], v[24:27]
	v_mfma_f32_16x16x32_bf16 v[12:15], v[144:147], v[212:215], v[12:15]
	v_mfma_f32_16x16x32_bf16 v[8:11], v[164:167], v[212:215], v[8:11]
	v_mfma_f32_16x16x32_bf16 v[60:63], v[160:163], v[192:195], v[60:63]
	v_mfma_f32_16x16x32_bf16 v[56:59], v[168:171], v[192:195], v[56:59]
	v_mfma_f32_16x16x32_bf16 v[44:47], v[160:163], v[200:203], v[44:47]
	v_mfma_f32_16x16x32_bf16 v[40:43], v[168:171], v[200:203], v[40:43]
	v_mfma_f32_16x16x32_bf16 v[28:31], v[160:163], v[208:211], v[28:31]
	v_mfma_f32_16x16x32_bf16 v[24:27], v[168:171], v[208:211], v[24:27]
	v_mfma_f32_16x16x32_bf16 v[12:15], v[160:163], v[216:219], v[12:15]
	v_mfma_f32_16x16x32_bf16 v[8:11], v[168:171], v[216:219], v[8:11]
	v_mfma_f32_16x16x32_bf16 v[52:55], v[172:175], v[188:191], v[52:55]
	v_mfma_f32_16x16x32_bf16 v[48:51], v[180:183], v[188:191], v[48:51]
	v_mfma_f32_16x16x32_bf16 v[36:39], v[172:175], v[196:199], v[36:39]
	v_mfma_f32_16x16x32_bf16 v[32:35], v[180:183], v[196:199], v[32:35]
	v_mfma_f32_16x16x32_bf16 v[20:23], v[172:175], v[204:207], v[20:23]
	v_mfma_f32_16x16x32_bf16 v[16:19], v[180:183], v[204:207], v[16:19]
	v_mfma_f32_16x16x32_bf16 v[4:7], v[172:175], v[212:215], v[4:7]
	v_mfma_f32_16x16x32_bf16 v[0:3], v[180:183], v[212:215], v[0:3]
	v_mfma_f32_16x16x32_bf16 v[52:55], v[176:179], v[192:195], v[52:55]
	v_mfma_f32_16x16x32_bf16 v[48:51], v[184:187], v[192:195], v[48:51]
	v_mfma_f32_16x16x32_bf16 v[36:39], v[176:179], v[200:203], v[36:39]
	v_mfma_f32_16x16x32_bf16 v[32:35], v[184:187], v[200:203], v[32:35]
	v_mfma_f32_16x16x32_bf16 v[20:23], v[176:179], v[208:211], v[20:23]
	v_mfma_f32_16x16x32_bf16 v[16:19], v[184:187], v[208:211], v[16:19]
	v_mfma_f32_16x16x32_bf16 v[4:7], v[176:179], v[216:219], v[4:7]
	v_mfma_f32_16x16x32_bf16 v[0:3], v[184:187], v[216:219], v[0:3]
	s_setprio 0
	s_cmp_lg_u32 s98, 0
	s_cbranch_scc1 .Lpg_b2_67
	s_barrier
.Lpg_b2_67:
	s_add_i32 s48, 0, 0x18000
	v_add_u32_e32 v148, s48, v149
	s_add_i32 s49, 0, 0x1c000
	ds_read_b128 v[144:147], v148
	ds_read_b128 v[160:163], v148 offset:1024
	ds_read_b128 v[164:167], v148 offset:2048
	ds_read_b128 v[168:171], v148 offset:3072
	v_add_u32_e32 v148, s49, v149
	ds_read_b128 v[172:175], v148
	ds_read_b128 v[176:179], v148 offset:1024
	ds_read_b128 v[180:183], v148 offset:2048
	ds_read_b128 v[184:187], v148 offset:3072
	s_add_u32 s38, s38, 0x40000
	s_addc_u32 s39, s39, 0
	s_mov_b32 m0, s45
	v_lshl_add_u64 v[226:227], s[38:39], 0, v[134:135]
	ds_read_b128 v[188:191], v157 offset:32768
	ds_read_b128 v[192:195], v157 offset:33792
	ds_read_b128 v[196:199], v157 offset:34816
	ds_read_b128 v[200:203], v157 offset:35840
	ds_read_b128 v[204:207], v157 offset:36864
	ds_read_b128 v[208:211], v157 offset:37888
	ds_read_b128 v[212:215], v157 offset:38912
	ds_read_b128 v[216:219], v157 offset:39936
	global_load_lds_dwordx4 v[226:227], off
	v_lshl_add_u64 v[226:227], s[38:39], 0, v[130:131]
	s_mov_b32 m0, s46
	s_nop 0
	global_load_lds_dwordx4 v[226:227], off
	s_waitcnt vmcnt(8)
	s_waitcnt lgkmcnt(0)
	s_setprio 1
	s_cmp_lg_u32 s98, 0
	s_cbranch_scc0 .Lpg_b1_68
	s_barrier
	s_setprio 2

; #define PG8_STAGE(bufoff, gbase, voff) do { _Pragma("unroll") for (int _i = 0; _i < 2; ++_i) \
;         __builtin_amdgcn_global_load_lds((const unsigned*)((const char*)(gbase) + (voff)[_i]), (PG8_LAS unsigned*)(lds + (bufoff) + ldsw + _i * 8192), 16, 0, 0); } while (0)
; #define PG8_LDA(dst, b, h) do { _Pragma("unroll") for (int m = 0; m < 4; ++m) _Pragma("unroll") for (int k = 0; k < 2; ++k) dst[m][k] = *(const PG8_LAS bf16x8*)(lds + PG8_SA(b, h) + aoff + m * 2048 + k * 1024); } while (0)
; #define PG8_MMA(ai, bj, At, Bt) do { __builtin_amdgcn_s_setprio(1); _Pragma("unroll") for (int m = 0; m < 4; ++m) _Pragma("unroll") for (int n = 0; n < 2; ++n) _Pragma("unroll") for (int k = 0; k < 2; ++k) \
;         acc[ai][bj][m][n] = __builtin_amdgcn_mfma_f32_16x16x32_bf16(Bt[n][k], At[m][k], acc[ai][bj][m][n], 0, 0, 0); __builtin_amdgcn_s_setprio(0); } while (0)
; #define PG8_WAIT_V(n) asm volatile("s_waitcnt vmcnt(" #n ")" ::: "memory")
; #define PG8_WAIT_L(n) asm volatile("s_waitcnt lgkmcnt(" #n ")" ::: "memory")
; #define PG8_BAR __builtin_amdgcn_s_barrier()
; #define PG8_SCHED __builtin_amdgcn_sched_barrier(0)
;     ...
;             PG8_LDA(At, 1, 1); PG8_STAGE(PG8_SB(1, 0), b3, voffB); PG8_STAGE(PG8_SB(1, 1), b3 + hstepB, voffB); PG8_STAGE(PG8_SA(1, 0), a3, voffA);
;             PG8_WAIT_V(8); PG8_WAIT_L(0); PG8_BAR; PG8_MMA(1, 0, At, B0); PG8_MMA(1, 1, At, B1); PG8_BAR; PG8_SCHED;
.Lpg_b2_69:
	s_add_i32 s38, s48, s43
	v_lshl_add_u64 v[154:155], v[154:155], 0, s[10:11]
	s_mov_b32 m0, s38
	ds_read_b128 v[188:191], v157 offset:49152
	ds_read_b128 v[192:195], v157 offset:50176
	ds_read_b128 v[196:199], v157 offset:51200
	ds_read_b128 v[200:203], v157 offset:52224
	ds_read_b128 v[204:207], v157 offset:53248
	ds_read_b128 v[208:211], v157 offset:54272
	ds_read_b128 v[212:215], v157 offset:55296
	ds_read_b128 v[216:219], v157 offset:56320
	global_load_lds_dwordx4 v[154:155], off
	s_add_i32 m0, s38, 0x2000
	s_add_u32 s36, s36, 0x40080
	v_lshl_add_u64 v[154:155], v[220:221], 0, s[10:11]
	s_addc_u32 s37, s37, 0
	s_add_i32 s38, s49, s43
	global_load_lds_dwordx4 v[154:155], off
	v_lshl_add_u64 v[154:155], s[36:37], 0, v[132:133]
	s_mov_b32 m0, s38
	s_nop 0
	global_load_lds_dwordx4 v[154:155], off
	v_lshl_add_u64 v[154:155], s[36:37], 0, v[128:129]
	s_add_i32 m0, s38, 0x2000
	s_nop 0
	global_load_lds_dwordx4 v[154:155], off
	v_lshl_add_u64 v[154:155], v[222:223], 0, s[10:11]
	s_mov_b32 m0, s52
	s_nop 0
	global_load_lds_dwordx4 v[154:155], off
	v_lshl_add_u64 v[154:155], v[224:225], 0, s[10:11]
	s_mov_b32 m0, s53
	s_nop 0
	global_load_lds_dwordx4 v[154:155], off
	s_waitcnt vmcnt(8)
	s_waitcnt lgkmcnt(0)
	s_setprio 1
	s_cmp_lg_u32 s98, 0
	s_cbranch_scc0 .Lpg_b1_70
	s_barrier
	s_setprio 2

; DI void st8(bf16_t* p, const float (&v)[8]) { u32x4 w; w.x = cvtpk(v[0], v[1]); w.y = cvtpk(v[2], v[3]); w.z = cvtpk(v[4], v[5]); w.w = cvtpk(v[6], v[7]); *(u32x4*)p = w; }
; #define ACC8(v, ai, bj, m, s) do { const f32x4 a_ = acc[ai][bj][m][0] * (s), b_ = acc[ai][bj][m][1] * (s); v[0] = a_[0]; v[1] = a_[1]; v[2] = a_[2]; v[3] = a_[3]; v[4] = b_[0]; v[5] = b_[1]; v[6] = b_[2]; v[7] = b_[3]; } while (0)
; #define ITLOOP _Pragma("unroll") for (int it = 0; it < 8; ++it)
; #define BJLOOP _Pragma("unroll") for (int bj = 0; bj < 2; ++bj)
; #define SBE() __builtin_amdgcn_sched_barrier(0)
; template <int NS> DI void row_scales(const float* rsp, float inv, int grow0, float (&rs)[8]) {
; #pragma unroll
;     for (int it = 0; it < 8; ++it) rs[it] = rsp[grow0 + (it >> 2) * 128 + (it & 3) * 16];
;     if (NS != 0) {
; #pragma unroll
;         for (int it = 0; it < 8; ++it) rs[it] = __builtin_amdgcn_rsqf(rs[it] * inv + EPSN); }
;     DI void operator()(const AccT& acc, const pg8::Unit& u, int wr, int wc, int fr_in, int fq_in) const {
;     ...
;         if (KIND == K_FF1) {
;             float rs[8]; row_scales<1>(b.ssq2, 1.0f / 1024.0f, grow0, rs);
;             ITLOOP { BJLOOP { float v[8]; ACC8(v, IT_AI, bj, IT_M, rs[it]);
; #pragma unroll
;                 for (int e = 0; e < 8; ++e) { const float t = fmaxf(v[e], 0.f); v[e] = t * t; }
;                 st8(b.hdn + IT_ROW * 4096 + tc0 + bj * 128, v); } SBE(); }
.Lpg_b2_71:
	s_add_i32 s62, s62, 2
	s_add_u32 s34, s34, 0x100
	s_addc_u32 s35, s35, 0
	s_add_u32 s60, s60, 0x100
	s_addc_u32 s61, s61, 0
	s_cmp_gt_u32 s62, 13
	s_cbranch_scc0 .LBB0_1341
	s_and_b64 vcc, exec, s[16:17]
	s_cbranch_vccz .LBB0_1344
.LBB0_1344:
	s_lshl_b32 s21, s28, 8
	s_add_i32 s21, s21, s50
	v_mbcnt_lo_u32_b32 v148, -1, 0
	v_mbcnt_hi_u32_b32 v148, -1, v148
	s_nop 0
	v_and_or_b32 v144, v148, 15, s21
	v_ashrrev_i32_e32 v145, 31, v144
	v_lshl_add_u64 v[146:147], v[144:145], 2, s[6:7]
	global_load_dword v150, v[146:147], off
	global_load_dword v152, v[146:147], off offset:64
	global_load_dword v156, v[146:147], off offset:128
	global_load_dword v158, v[146:147], off offset:192
	global_load_dword v160, v[146:147], off offset:512
	global_load_dword v161, v[146:147], off offset:576
	global_load_dword v162, v[146:147], off offset:640
	global_load_dword v163, v[146:147], off offset:704
	v_lshlrev_b64 v[154:155], 13, v[144:145]
	s_lshl_b32 s21, s57, 8
	v_ashrrev_i32_e32 v146, 1, v148
	s_or_b32 s21, s21, s51
	v_and_b32_e32 v146, -8, v146
	v_add_u32_e32 v146, s21, v146
	v_ashrrev_i32_e32 v147, 31, v146
	v_lshl_add_u64 v[154:155], s[8:9], 0, v[154:155]
	v_lshlrev_b64 v[146:147], 1, v[146:147]
	v_lshl_add_u64 v[154:155], v[154:155], 0, v[146:147]
	s_waitcnt vmcnt(0)
	v_fmamk_f32 v145, v150, 0x3a800000, v159
	v_fmamk_f32 v148, v152, 0x3a800000, v159
	v_fmamk_f32 v150, v156, 0x3a800000, v159
	v_fmamk_f32 v152, v158, 0x3a800000, v159
	v_fmamk_f32 v156, v160, 0x3a800000, v159
	v_rsq_f32_e32 v160, v145
	v_fmamk_f32 v161, v161, 0x3a800000, v159
	v_fmamk_f32 v165, v162, 0x3a800000, v159
	v_fmamk_f32 v163, v163, 0x3a800000, v159
	v_pk_mul_f32 v[126:127], v[126:127], v[160:161] op_sel_hi:[1,0]
	v_pk_mul_f32 v[124:125], v[124:125], v[160:161] op_sel_hi:[1,0]
	v_pk_mul_f32 v[122:123], v[122:123], v[160:161] op_sel_hi:[1,0]
	v_pk_mul_f32 v[120:121], v[120:121], v[160:161] op_sel_hi:[1,0]
	v_pk_mul_f32 v[118:119], v[118:119], v[160:161] op_sel_hi:[1,0]
	v_pk_mul_f32 v[116:117], v[116:117], v[160:161] op_sel_hi:[1,0]
	v_pk_mul_f32 v[114:115], v[114:115], v[160:161] op_sel_hi:[1,0]
	v_pk_mul_f32 v[112:113], v[112:113], v[160:161] op_sel_hi:[1,0]
	v_max_f32_e32 v124, 0, v124
	v_max_f32_e32 v125, 0, v125
	v_max_f32_e32 v126, 0, v126
	v_max_f32_e32 v127, 0, v127
	v_max_f32_e32 v120, 0, v120
	v_max_f32_e32 v121, 0, v121
	v_max_f32_e32 v122, 0, v122
	v_max_f32_e32 v123, 0, v123
	v_max_f32_e32 v116, 0, v116
	v_max_f32_e32 v117, 0, v117
	v_max_f32_e32 v118, 0, v118
	v_max_f32_e32 v119, 0, v119
	v_max_f32_e32 v112, 0, v112
	v_max_f32_e32 v113, 0, v113
	v_max_f32_e32 v114, 0, v114
	v_max_f32_e32 v115, 0, v115
	v_pk_mul_f32 v[124:125], v[124:125], v[124:125]
	v_pk_mul_f32 v[126:127], v[126:127], v[126:127]
	v_pk_mul_f32 v[120:121], v[120:121], v[120:121]
	v_pk_mul_f32 v[122:123], v[122:123], v[122:123]
	v_rsq_f32_e32 v158, v152
	v_rsq_f32_e32 v152, v161
	v_pk_mul_f32 v[116:117], v[116:117], v[116:117]
	v_pk_mul_f32 v[118:119], v[118:119], v[118:119]
	v_pk_mul_f32 v[160:161], v[112:113], v[112:113]
	v_pk_mul_f32 v[166:167], v[114:115], v[114:115]
	v_cvt_pk_bf16_f32 v112, v124, v125
	v_cvt_pk_bf16_f32 v113, v126, v127
	v_cvt_pk_bf16_f32 v114, v120, v121
	v_cvt_pk_bf16_f32 v115, v122, v123
	v_rsq_f32_e32 v162, v148
	v_rsq_f32_e32 v164, v150
	v_rsq_f32_e32 v156, v156
	v_rsq_f32_e32 v150, v165
	v_rsq_f32_e32 v148, v163
	v_cvt_pk_bf16_f32 v116, v116, v117
	v_cvt_pk_bf16_f32 v117, v118, v119
	v_cvt_pk_bf16_f32 v118, v160, v161
	v_cvt_pk_bf16_f32 v119, v166, v167
	global_store_dwordx4 v[154:155], v[112:115], off
	global_store_dwordx4 v[154:155], v[116:119], off offset:256
	s_nop 0
	v_or_b32_e32 v112, 16, v144
	v_pk_mul_f32 v[104:105], v[104:105], v[162:163] op_sel_hi:[1,0]
	v_ashrrev_i32_e32 v113, 31, v112
	v_pk_mul_f32 v[110:111], v[110:111], v[162:163] op_sel_hi:[1,0]
	v_pk_mul_f32 v[108:109], v[108:109], v[162:163] op_sel_hi:[1,0]
	v_pk_mul_f32 v[106:107], v[106:107], v[162:163] op_sel_hi:[1,0]
	v_max_f32_e32 v104, 0, v104
	v_max_f32_e32 v105, 0, v105
	v_lshlrev_b64 v[112:113], 13, v[112:113]
	v_max_f32_e32 v108, 0, v108
	v_max_f32_e32 v109, 0, v109
	v_max_f32_e32 v110, 0, v110
	v_max_f32_e32 v111, 0, v111
	v_pk_mul_f32 v[114:115], v[104:105], v[104:105]
	v_max_f32_e32 v104, 0, v106
	v_max_f32_e32 v105, 0, v107
	v_pk_mul_f32 v[108:109], v[108:109], v[108:109]
	v_pk_mul_f32 v[110:111], v[110:111], v[110:111]
	v_pk_mul_f32 v[116:117], v[104:105], v[104:105]
	v_lshl_add_u64 v[104:105], s[8:9], 0, v[112:113]
	v_pk_mul_f32 v[96:97], v[96:97], v[162:163] op_sel_hi:[1,0]
	v_lshl_add_u64 v[112:113], v[104:105], 0, v[146:147]
	v_cvt_pk_bf16_f32 v104, v108, v109
	v_cvt_pk_bf16_f32 v105, v110, v111
	v_cvt_pk_bf16_f32 v106, v114, v115
	v_cvt_pk_bf16_f32 v107, v116, v117
	v_pk_mul_f32 v[102:103], v[102:103], v[162:163] op_sel_hi:[1,0]
	v_pk_mul_f32 v[100:101], v[100:101], v[162:163] op_sel_hi:[1,0]
	v_pk_mul_f32 v[98:99], v[98:99], v[162:163] op_sel_hi:[1,0]
	v_max_f32_e32 v96, 0, v96
	v_max_f32_e32 v97, 0, v97
	global_store_dwordx4 v[112:113], v[104:107], off
	v_max_f32_e32 v100, 0, v100
	v_max_f32_e32 v101, 0, v101
	v_max_f32_e32 v102, 0, v102
	v_max_f32_e32 v103, 0, v103
	v_pk_mul_f32 v[104:105], v[96:97], v[96:97]
	v_max_f32_e32 v96, 0, v98
	v_max_f32_e32 v97, 0, v99
	v_pk_mul_f32 v[100:101], v[100:101], v[100:101]
	v_pk_mul_f32 v[102:103], v[102:103], v[102:103]
	v_pk_mul_f32 v[106:107], v[96:97], v[96:97]
	v_cvt_pk_bf16_f32 v96, v100, v101
	v_cvt_pk_bf16_f32 v97, v102, v103
	v_cvt_pk_bf16_f32 v98, v104, v105
	v_cvt_pk_bf16_f32 v99, v106, v107
	global_store_dwordx4 v[112:113], v[96:99], off offset:256
	s_nop 1
	v_or_b32_e32 v96, 32, v144
	v_pk_mul_f32 v[88:89], v[88:89], v[164:165] op_sel_hi:[1,0]
; DI void st8(bf16_t* p, const float (&v)[8]) { u32x4 w; w.x = cvtpk(v[0], v[1]); w.y = cvtpk(v[2], v[3]); w.z = cvtpk(v[4], v[5]); w.w = cvtpk(v[6], v[7]); *(u32x4*)p = w; }
; #define ACC8(v, ai, bj, m, s) do { const f32x4 a_ = acc[ai][bj][m][0] * (s), b_ = acc[ai][bj][m][1] * (s); v[0] = a_[0]; v[1] = a_[1]; v[2] = a_[2]; v[3] = a_[3]; v[4] = b_[0]; v[5] = b_[1]; v[6] = b_[2]; v[7] = b_[3]; } while (0)
; #define ITLOOP _Pragma("unroll") for (int it = 0; it < 8; ++it)
; #define BJLOOP _Pragma("unroll") for (int bj = 0; bj < 2; ++bj)
; #define SBE() __builtin_amdgcn_sched_barrier(0)
;     DI void operator()(const AccT& acc, const pg8::Unit& u, int wr, int wc, int fr_in, int fq_in) const {
;     ...
;             ITLOOP { BJLOOP { float v[8]; ACC8(v, IT_AI, bj, IT_M, rs[it]);
; #pragma unroll
;                 for (int e = 0; e < 8; ++e) { const float t = fmaxf(v[e], 0.f); v[e] = t * t; }
;                 st8(b.hdn + IT_ROW * 4096 + tc0 + bj * 128, v); } SBE(); }
	v_ashrrev_i32_e32 v97, 31, v96
	v_pk_mul_f32 v[94:95], v[94:95], v[164:165] op_sel_hi:[1,0]
	v_pk_mul_f32 v[92:93], v[92:93], v[164:165] op_sel_hi:[1,0]
	v_pk_mul_f32 v[90:91], v[90:91], v[164:165] op_sel_hi:[1,0]
	v_max_f32_e32 v88, 0, v88
	v_max_f32_e32 v89, 0, v89
	v_lshlrev_b64 v[96:97], 13, v[96:97]
	v_max_f32_e32 v92, 0, v92
	v_max_f32_e32 v93, 0, v93
	v_max_f32_e32 v94, 0, v94
	v_max_f32_e32 v95, 0, v95
	v_pk_mul_f32 v[98:99], v[88:89], v[88:89]
	v_max_f32_e32 v88, 0, v90
	v_max_f32_e32 v89, 0, v91
	v_pk_mul_f32 v[92:93], v[92:93], v[92:93]
	v_pk_mul_f32 v[94:95], v[94:95], v[94:95]
	v_pk_mul_f32 v[100:101], v[88:89], v[88:89]
	v_lshl_add_u64 v[88:89], s[8:9], 0, v[96:97]
	v_pk_mul_f32 v[80:81], v[80:81], v[164:165] op_sel_hi:[1,0]
	v_lshl_add_u64 v[96:97], v[88:89], 0, v[146:147]
	v_cvt_pk_bf16_f32 v88, v92, v93
	v_cvt_pk_bf16_f32 v89, v94, v95
	v_cvt_pk_bf16_f32 v90, v98, v99
	v_cvt_pk_bf16_f32 v91, v100, v101
	v_pk_mul_f32 v[86:87], v[86:87], v[164:165] op_sel_hi:[1,0]
	v_pk_mul_f32 v[84:85], v[84:85], v[164:165] op_sel_hi:[1,0]
	v_pk_mul_f32 v[82:83], v[82:83], v[164:165] op_sel_hi:[1,0]
	v_max_f32_e32 v80, 0, v80
	v_max_f32_e32 v81, 0, v81
	global_store_dwordx4 v[96:97], v[88:91], off
	v_max_f32_e32 v84, 0, v84
	v_max_f32_e32 v85, 0, v85
	v_max_f32_e32 v86, 0, v86
	v_max_f32_e32 v87, 0, v87
	v_pk_mul_f32 v[88:89], v[80:81], v[80:81]
	v_max_f32_e32 v80, 0, v82
	v_max_f32_e32 v81, 0, v83
	v_pk_mul_f32 v[84:85], v[84:85], v[84:85]
	v_pk_mul_f32 v[86:87], v[86:87], v[86:87]
	v_pk_mul_f32 v[90:91], v[80:81], v[80:81]
	v_cvt_pk_bf16_f32 v80, v84, v85
	v_cvt_pk_bf16_f32 v81, v86, v87
	v_cvt_pk_bf16_f32 v82, v88, v89
	v_cvt_pk_bf16_f32 v83, v90, v91
	global_store_dwordx4 v[96:97], v[80:83], off offset:256
	s_nop 1
	v_or_b32_e32 v80, 48, v144
	v_pk_mul_f32 v[72:73], v[72:73], v[158:159] op_sel_hi:[1,0]
	v_ashrrev_i32_e32 v81, 31, v80
	v_pk_mul_f32 v[78:79], v[78:79], v[158:159] op_sel_hi:[1,0]
	v_pk_mul_f32 v[76:77], v[76:77], v[158:159] op_sel_hi:[1,0]
	v_pk_mul_f32 v[74:75], v[74:75], v[158:159] op_sel_hi:[1,0]
	v_max_f32_e32 v72, 0, v72
	v_max_f32_e32 v73, 0, v73
	v_lshlrev_b64 v[80:81], 13, v[80:81]
	v_max_f32_e32 v76, 0, v76
	v_max_f32_e32 v77, 0, v77
	v_max_f32_e32 v78, 0, v78
	v_max_f32_e32 v79, 0, v79
	v_pk_mul_f32 v[82:83], v[72:73], v[72:73]
	v_max_f32_e32 v72, 0, v74
	v_max_f32_e32 v73, 0, v75
	v_pk_mul_f32 v[76:77], v[76:77], v[76:77]
	v_pk_mul_f32 v[78:79], v[78:79], v[78:79]
	v_pk_mul_f32 v[84:85], v[72:73], v[72:73]
	v_lshl_add_u64 v[72:73], s[8:9], 0, v[80:81]
	v_pk_mul_f32 v[64:65], v[64:65], v[158:159] op_sel_hi:[1,0]
	v_lshl_add_u64 v[80:81], v[72:73], 0, v[146:147]
	v_cvt_pk_bf16_f32 v72, v76, v77
	v_cvt_pk_bf16_f32 v73, v78, v79
	v_cvt_pk_bf16_f32 v74, v82, v83
	v_cvt_pk_bf16_f32 v75, v84, v85
	v_pk_mul_f32 v[70:71], v[70:71], v[158:159] op_sel_hi:[1,0]
	v_pk_mul_f32 v[68:69], v[68:69], v[158:159] op_sel_hi:[1,0]
	v_pk_mul_f32 v[66:67], v[66:67], v[158:159] op_sel_hi:[1,0]
	v_max_f32_e32 v64, 0, v64
	v_max_f32_e32 v65, 0, v65
	global_store_dwordx4 v[80:81], v[72:75], off
	v_max_f32_e32 v68, 0, v68
	v_max_f32_e32 v69, 0, v69
	v_max_f32_e32 v70, 0, v70
	v_max_f32_e32 v71, 0, v71
	v_pk_mul_f32 v[72:73], v[64:65], v[64:65]
	v_max_f32_e32 v64, 0, v66
	v_max_f32_e32 v65, 0, v67
	v_pk_mul_f32 v[68:69], v[68:69], v[68:69]
	v_pk_mul_f32 v[70:71], v[70:71], v[70:71]
	v_pk_mul_f32 v[74:75], v[64:65], v[64:65]
	v_cvt_pk_bf16_f32 v64, v68, v69
	v_cvt_pk_bf16_f32 v65, v70, v71
	v_cvt_pk_bf16_f32 v66, v72, v73
	v_cvt_pk_bf16_f32 v67, v74, v75
	global_store_dwordx4 v[80:81], v[64:67], off offset:256
	v_pk_mul_f32 v[60:61], v[60:61], v[156:157] op_sel_hi:[1,0]
	v_pk_mul_f32 v[56:57], v[56:57], v[156:157] op_sel_hi:[1,0]
	v_pk_mul_f32 v[62:63], v[62:63], v[156:157] op_sel_hi:[1,0]
	v_pk_mul_f32 v[58:59], v[58:59], v[156:157] op_sel_hi:[1,0]
	v_max_f32_e32 v60, 0, v60
	v_max_f32_e32 v61, 0, v61
	v_max_f32_e32 v56, 0, v56
	v_max_f32_e32 v57, 0, v57
	v_pk_mul_f32 v[60:61], v[60:61], v[60:61]
	v_max_f32_e32 v62, 0, v62
	v_max_f32_e32 v63, 0, v63
	v_pk_mul_f32 v[64:65], v[56:57], v[56:57]
	v_max_f32_e32 v56, 0, v58
	v_max_f32_e32 v57, 0, v59
	v_pk_mul_f32 v[62:63], v[62:63], v[62:63]
	v_pk_mul_f32 v[66:67], v[56:57], v[56:57]
	v_cvt_pk_bf16_f32 v56, v60, v61
	v_add_co_u32_e32 v60, vcc, s56, v154
	v_pk_mul_f32 v[48:49], v[48:49], v[156:157] op_sel_hi:[1,0]
	v_cvt_pk_bf16_f32 v57, v62, v63
	v_cvt_pk_bf16_f32 v58, v64, v65
	v_cvt_pk_bf16_f32 v59, v66, v67
	v_addc_co_u32_e32 v61, vcc, 0, v155, vcc
	v_pk_mul_f32 v[54:55], v[54:55], v[156:157] op_sel_hi:[1,0]
	v_pk_mul_f32 v[52:53], v[52:53], v[156:157] op_sel_hi:[1,0]
	v_pk_mul_f32 v[50:51], v[50:51], v[156:157] op_sel_hi:[1,0]
	v_max_f32_e32 v48, 0, v48
	v_max_f32_e32 v49, 0, v49
	global_store_dwordx4 v[60:61], v[56:59], off
	v_max_f32_e32 v52, 0, v52
	v_max_f32_e32 v53, 0, v53
	v_max_f32_e32 v54, 0, v54
	v_max_f32_e32 v55, 0, v55
	v_pk_mul_f32 v[56:57], v[48:49], v[48:49]
	v_max_f32_e32 v48, 0, v50
	v_max_f32_e32 v49, 0, v51
	v_pk_mul_f32 v[52:53], v[52:53], v[52:53]
	v_pk_mul_f32 v[54:55], v[54:55], v[54:55]
	v_pk_mul_f32 v[58:59], v[48:49], v[48:49]
	v_lshl_add_u64 v[68:69], v[154:155], 0, s[18:19]
	v_cvt_pk_bf16_f32 v48, v52, v53
	v_cvt_pk_bf16_f32 v49, v54, v55
	v_cvt_pk_bf16_f32 v50, v56, v57
	v_cvt_pk_bf16_f32 v51, v58, v59
	global_store_dwordx4 v[68:69], v[48:51], off offset:256
	s_nop 1
	v_add_u32_e32 v48, 0x90, v144
	v_pk_mul_f32 v[40:41], v[40:41], v[152:153] op_sel_hi:[1,0]
	v_ashrrev_i32_e32 v49, 31, v48
; #define PG8_BAR __builtin_amdgcn_s_barrier()
; DI void st8(bf16_t* p, const float (&v)[8]) { u32x4 w; w.x = cvtpk(v[0], v[1]); w.y = cvtpk(v[2], v[3]); w.z = cvtpk(v[4], v[5]); w.w = cvtpk(v[6], v[7]); *(u32x4*)p = w; }
; #define ACC8(v, ai, bj, m, s) do { const f32x4 a_ = acc[ai][bj][m][0] * (s), b_ = acc[ai][bj][m][1] * (s); v[0] = a_[0]; v[1] = a_[1]; v[2] = a_[2]; v[3] = a_[3]; v[4] = b_[0]; v[5] = b_[1]; v[6] = b_[2]; v[7] = b_[3]; } while (0)
; #define ITLOOP _Pragma("unroll") for (int it = 0; it < 8; ++it)
; #define BJLOOP _Pragma("unroll") for (int bj = 0; bj < 2; ++bj)
; #define SBE() __builtin_amdgcn_sched_barrier(0)
;     ...
;         if constexpr (!Epi::AFTER_DRAIN) { E(acc, cur, wr, wc, fr, fq); S.done(cur); }
;         if (!has_next) break;
; #pragma unroll
;         for (int a = 0; a < 2; ++a)
; #pragma unroll
;             for (int b = 0; b < 2; ++b)
; #pragma unroll
;                 for (int m = 0; m < 4; ++m)
; #pragma unroll
;                     for (int n = 0; n < 2; ++n) acc[a][b][m][n] = (f32x4){0.f, 0.f, 0.f, 0.f};
;         cur = nxt; cA = nA; cB = nB; ++ui;
;         if constexpr (ALIGN_EPI) { if (wr == 1) PG8_BAR; }
;     DI void operator()(const AccT& acc, const pg8::Unit& u, int wr, int wc, int fr_in, int fq_in) const {
;     ...
;             ITLOOP { BJLOOP { float v[8]; ACC8(v, IT_AI, bj, IT_M, rs[it]);
; #pragma unroll
;                 for (int e = 0; e < 8; ++e) { const float t = fmaxf(v[e], 0.f); v[e] = t * t; }
;                 st8(b.hdn + IT_ROW * 4096 + tc0 + bj * 128, v); } SBE(); }
	v_pk_mul_f32 v[46:47], v[46:47], v[152:153] op_sel_hi:[1,0]
	v_pk_mul_f32 v[44:45], v[44:45], v[152:153] op_sel_hi:[1,0]
	v_pk_mul_f32 v[42:43], v[42:43], v[152:153] op_sel_hi:[1,0]
	v_max_f32_e32 v40, 0, v40
	v_max_f32_e32 v41, 0, v41
	v_lshlrev_b64 v[48:49], 13, v[48:49]
	v_max_f32_e32 v44, 0, v44
	v_max_f32_e32 v45, 0, v45
	v_max_f32_e32 v46, 0, v46
	v_max_f32_e32 v47, 0, v47
	v_pk_mul_f32 v[50:51], v[40:41], v[40:41]
	v_max_f32_e32 v40, 0, v42
	v_max_f32_e32 v41, 0, v43
	v_pk_mul_f32 v[44:45], v[44:45], v[44:45]
	v_pk_mul_f32 v[46:47], v[46:47], v[46:47]
	v_pk_mul_f32 v[52:53], v[40:41], v[40:41]
	v_lshl_add_u64 v[40:41], s[8:9], 0, v[48:49]
	v_pk_mul_f32 v[32:33], v[32:33], v[152:153] op_sel_hi:[1,0]
	v_lshl_add_u64 v[48:49], v[40:41], 0, v[146:147]
	v_cvt_pk_bf16_f32 v40, v44, v45
	v_cvt_pk_bf16_f32 v41, v46, v47
	v_cvt_pk_bf16_f32 v42, v50, v51
	v_cvt_pk_bf16_f32 v43, v52, v53
	v_pk_mul_f32 v[38:39], v[38:39], v[152:153] op_sel_hi:[1,0]
	v_pk_mul_f32 v[36:37], v[36:37], v[152:153] op_sel_hi:[1,0]
	v_pk_mul_f32 v[34:35], v[34:35], v[152:153] op_sel_hi:[1,0]
	v_max_f32_e32 v32, 0, v32
	v_max_f32_e32 v33, 0, v33
	global_store_dwordx4 v[48:49], v[40:43], off
	v_max_f32_e32 v36, 0, v36
	v_max_f32_e32 v37, 0, v37
	v_max_f32_e32 v38, 0, v38
	v_max_f32_e32 v39, 0, v39
	v_pk_mul_f32 v[40:41], v[32:33], v[32:33]
	v_max_f32_e32 v32, 0, v34
	v_max_f32_e32 v33, 0, v35
	v_pk_mul_f32 v[36:37], v[36:37], v[36:37]
	v_pk_mul_f32 v[38:39], v[38:39], v[38:39]
	v_pk_mul_f32 v[42:43], v[32:33], v[32:33]
	v_cvt_pk_bf16_f32 v32, v36, v37
	v_cvt_pk_bf16_f32 v33, v38, v39
	v_cvt_pk_bf16_f32 v34, v40, v41
	v_cvt_pk_bf16_f32 v35, v42, v43
	global_store_dwordx4 v[48:49], v[32:35], off offset:256
	s_nop 1
	v_add_u32_e32 v32, 0xa0, v144
	v_pk_mul_f32 v[24:25], v[24:25], v[150:151] op_sel_hi:[1,0]
	v_ashrrev_i32_e32 v33, 31, v32
	v_pk_mul_f32 v[30:31], v[30:31], v[150:151] op_sel_hi:[1,0]
	v_pk_mul_f32 v[28:29], v[28:29], v[150:151] op_sel_hi:[1,0]
	v_pk_mul_f32 v[26:27], v[26:27], v[150:151] op_sel_hi:[1,0]
	v_max_f32_e32 v24, 0, v24
	v_max_f32_e32 v25, 0, v25
	v_lshlrev_b64 v[32:33], 13, v[32:33]
	v_max_f32_e32 v28, 0, v28
	v_max_f32_e32 v29, 0, v29
	v_max_f32_e32 v30, 0, v30
	v_max_f32_e32 v31, 0, v31
	v_pk_mul_f32 v[34:35], v[24:25], v[24:25]
	v_max_f32_e32 v24, 0, v26
	v_max_f32_e32 v25, 0, v27
	v_pk_mul_f32 v[28:29], v[28:29], v[28:29]
	v_pk_mul_f32 v[30:31], v[30:31], v[30:31]
	v_pk_mul_f32 v[36:37], v[24:25], v[24:25]
	v_lshl_add_u64 v[24:25], s[8:9], 0, v[32:33]
	v_pk_mul_f32 v[16:17], v[16:17], v[150:151] op_sel_hi:[1,0]
	v_lshl_add_u64 v[32:33], v[24:25], 0, v[146:147]
	v_cvt_pk_bf16_f32 v24, v28, v29
	v_cvt_pk_bf16_f32 v25, v30, v31
	v_cvt_pk_bf16_f32 v26, v34, v35
	v_cvt_pk_bf16_f32 v27, v36, v37
	v_pk_mul_f32 v[22:23], v[22:23], v[150:151] op_sel_hi:[1,0]
	v_pk_mul_f32 v[20:21], v[20:21], v[150:151] op_sel_hi:[1,0]
	v_pk_mul_f32 v[18:19], v[18:19], v[150:151] op_sel_hi:[1,0]
	v_max_f32_e32 v16, 0, v16
	v_max_f32_e32 v17, 0, v17
	global_store_dwordx4 v[32:33], v[24:27], off
	v_max_f32_e32 v20, 0, v20
	v_max_f32_e32 v21, 0, v21
	v_max_f32_e32 v22, 0, v22
	v_max_f32_e32 v23, 0, v23
	v_pk_mul_f32 v[24:25], v[16:17], v[16:17]
	v_max_f32_e32 v16, 0, v18
	v_max_f32_e32 v17, 0, v19
	v_pk_mul_f32 v[20:21], v[20:21], v[20:21]
	v_pk_mul_f32 v[22:23], v[22:23], v[22:23]
	v_pk_mul_f32 v[26:27], v[16:17], v[16:17]
	v_cvt_pk_bf16_f32 v16, v20, v21
	v_cvt_pk_bf16_f32 v17, v22, v23
	v_cvt_pk_bf16_f32 v18, v24, v25
	v_cvt_pk_bf16_f32 v19, v26, v27
	global_store_dwordx4 v[32:33], v[16:19], off offset:256
	s_nop 1
	v_add_u32_e32 v16, 0xb0, v144
	v_pk_mul_f32 v[8:9], v[8:9], v[148:149] op_sel_hi:[1,0]
	v_ashrrev_i32_e32 v17, 31, v16
	v_pk_mul_f32 v[14:15], v[14:15], v[148:149] op_sel_hi:[1,0]
	v_pk_mul_f32 v[12:13], v[12:13], v[148:149] op_sel_hi:[1,0]
	v_pk_mul_f32 v[10:11], v[10:11], v[148:149] op_sel_hi:[1,0]
	v_max_f32_e32 v8, 0, v8
	v_max_f32_e32 v9, 0, v9
	v_lshlrev_b64 v[16:17], 13, v[16:17]
	v_max_f32_e32 v12, 0, v12
	v_max_f32_e32 v13, 0, v13
	v_max_f32_e32 v14, 0, v14
	v_max_f32_e32 v15, 0, v15
	v_pk_mul_f32 v[18:19], v[8:9], v[8:9]
	v_max_f32_e32 v8, 0, v10
	v_max_f32_e32 v9, 0, v11
	v_pk_mul_f32 v[12:13], v[12:13], v[12:13]
	v_pk_mul_f32 v[14:15], v[14:15], v[14:15]
	v_pk_mul_f32 v[20:21], v[8:9], v[8:9]
	v_lshl_add_u64 v[8:9], s[8:9], 0, v[16:17]
	v_pk_mul_f32 v[0:1], v[0:1], v[148:149] op_sel_hi:[1,0]
	v_lshl_add_u64 v[16:17], v[8:9], 0, v[146:147]
	v_cvt_pk_bf16_f32 v8, v12, v13
	v_cvt_pk_bf16_f32 v9, v14, v15
	v_cvt_pk_bf16_f32 v10, v18, v19
	v_cvt_pk_bf16_f32 v11, v20, v21
	v_pk_mul_f32 v[6:7], v[6:7], v[148:149] op_sel_hi:[1,0]
	v_pk_mul_f32 v[4:5], v[4:5], v[148:149] op_sel_hi:[1,0]
	v_pk_mul_f32 v[2:3], v[2:3], v[148:149] op_sel_hi:[1,0]
	v_max_f32_e32 v0, 0, v0
	v_max_f32_e32 v1, 0, v1
	global_store_dwordx4 v[16:17], v[8:11], off
	v_max_f32_e32 v4, 0, v4
	v_max_f32_e32 v5, 0, v5
	v_max_f32_e32 v6, 0, v6
	v_max_f32_e32 v7, 0, v7
	v_pk_mul_f32 v[8:9], v[0:1], v[0:1]
	v_max_f32_e32 v0, 0, v2
	v_max_f32_e32 v1, 0, v3
	v_pk_mul_f32 v[4:5], v[4:5], v[4:5]
	v_pk_mul_f32 v[6:7], v[6:7], v[6:7]
	v_pk_mul_f32 v[10:11], v[0:1], v[0:1]
	v_cvt_pk_bf16_f32 v0, v4, v5
	v_cvt_pk_bf16_f32 v1, v6, v7
	v_cvt_pk_bf16_f32 v2, v8, v9
	v_cvt_pk_bf16_f32 v3, v10, v11
	global_store_dwordx4 v[16:17], v[0:3], off offset:256
	s_andn2_b64 vcc, exec, s[0:1]
	s_mov_b64 s[0:1], -1
	s_cbranch_vccnz .LBB0_1333
	s_andn2_b64 vcc, exec, s[4:5]
	s_cbranch_vccnz .LBB0_1332
	s_branch .LBB0_1332

; #define PG8_STAGE(bufoff, gbase, voff) do { _Pragma("unroll") for (int _i = 0; _i < 2; ++_i) \
;         __builtin_amdgcn_global_load_lds((const unsigned*)((const char*)(gbase) + (voff)[_i]), (PG8_LAS unsigned*)(lds + (bufoff) + ldsw + _i * 8192), 16, 0, 0); } while (0)
; #define PG8_WAIT_V(n) asm volatile("s_waitcnt vmcnt(" #n ")" ::: "memory")
; #define PG8_BAR __builtin_amdgcn_s_barrier()
;     ...
;     for (int i = 0; i < 2; ++i) { int R, C; stage_rc(tid * 16 + i * 8192, R, C); const int Rb = Epi::PERM ? ((R & ~31) + perm32(R & 31)) : R;
;         voffA[i] = (unsigned)(R * lda_ + C) * 2u; voffB[i] = (unsigned)(Rb * K + C) * 2u; }
;     const size_t kstep = (size_t)(BK * 2);
;     const size_t hstepA = (size_t)HALF * lda_ * 2, hstepB = (size_t)HALF * K * 2;
;     const size_t tstepA = 2 * hstepA, tstepB = 2 * hstepB;
;     const unsigned ldsw = (unsigned)wid * 1024u;
;     const int aoff = lds_byte(wr * 64 + fr, fq * 8), boff = lds_byte(wc * 32 + fr, fq * 8);
;     ...
;         PG8_STAGE(PG8_SB(1, 0), cB + kstep, voffB); PG8_STAGE(PG8_SA(1, 0), cA + kstep, voffA); PG8_STAGE(PG8_SB(1, 1), cB + hstepB + kstep, voffB);
;         PG8_WAIT_V(6); PG8_BAR;
.LBB0_1404:
	s_add_u32 s6, s6, 0x4800000
	s_addc_u32 s7, s7, 0
	s_lshl_b32 s42, s15, 6
	s_lshl_b32 s18, s15, 13
	s_lshl_b32 s1, s1, 5
	s_mov_b64 s[14:15], 0x80
	s_and_b32 s43, s1, 0x60
	s_add_i32 m0, s8, 0x18000
	v_lshl_add_u64 v[6:7], v[6:7], 0, s[14:15]
	s_lshl_b32 s1, s43, 7
	s_waitcnt vmcnt(2)
	s_barrier
	global_load_lds_dwordx4 v[6:7], off
	v_lshl_add_u64 v[4:5], v[4:5], 0, s[14:15]
	s_add_i32 m0, s8, 0x1a000
	s_add_i32 s44, s8, 0x8000
	s_add_i32 s45, s8, 0xa000
	global_load_lds_dwordx4 v[4:5], off
	v_lshl_add_u64 v[0:1], v[0:1], 0, s[14:15]
	s_mov_b32 m0, s44
	s_add_u32 s16, s28, 0x100080
	global_load_lds_dwordx4 v[0:1], off
	v_lshl_add_u64 v[0:1], v[2:3], 0, s[14:15]
	s_mov_b32 m0, s45
	s_addc_u32 s17, s29, 0
	global_load_lds_dwordx4 v[0:1], off
	s_add_i32 m0, s8, 0x1c000
	v_lshl_add_u64 v[0:1], s[16:17], 0, v[140:141]
	global_load_lds_dwordx4 v[0:1], off
	v_lshl_add_u64 v[0:1], s[16:17], 0, v[136:137]
	s_add_i32 m0, s8, 0x1e000
	s_movk_i32 s16, 0x3c0
	global_load_lds_dwordx4 v[0:1], off
	v_and_b32_e32 v0, 48, v232
	v_lshlrev_b32_e32 v1, 6, v232
	v_and_or_b32 v0, v1, s16, v0
	v_lshlrev_b32_e32 v1, 2, v232
	v_and_b32_e32 v1, 32, v1
	v_bitop3_b32 v2, v0, s18, v1 bitop3:0xde
	v_bitop3_b32 v162, s1, v0, v1 bitop3:0xf6
	v_lshlrev_b32_e32 v0, 16, v12
	v_and_b32_e32 v0, 0xfffe0000, v0
	v_lshl_add_u32 v0, v11, 13, v0
	v_and_b32_e32 v1, 1, v12
	v_lshl_or_b32 v0, v1, 6, v0
	v_lshl_add_u32 v144, v13, 1, v0
	v_lshlrev_b32_e32 v0, 16, v8
	v_and_b32_e32 v0, 0xfffe0000, v0
	s_waitcnt vmcnt(6)
	s_cmpk_lt_u32 s0, 0x100
	v_lshl_add_u32 v0, v9, 13, v0
	v_and_b32_e32 v1, 1, v8
	s_cselect_b64 s[16:17], -1, 0
	v_lshl_or_b32 v0, v1, 6, v0
	s_add_i32 s46, 0, 0x10000
	s_add_i32 s47, 0, 0x14000
	v_mov_b32_e32 v145, v141
	v_lshl_add_u32 v146, v10, 1, v0
	v_mov_b32_e32 v147, v141
	v_mov_b64_e32 v[148:149], 0x400
	v_mov_b64_e32 v[150:151], 0x3ff
	v_add_u32_e32 v163, s46, v162
	v_add_u32_e32 v164, s47, v162
	v_add_u32_e32 v165, 0, v2
	s_cmp_lg_u32 s98, 0
	s_cbranch_scc1 .Lpg_x2_81
	s_barrier
.Lpg_x2_81:
	s_branch .LBB0_1407
.LBB0_1405:
	s_mov_b64 s[0:1], 0

; #define PG8_STAGE(bufoff, gbase, voff) do { _Pragma("unroll") for (int _i = 0; _i < 2; ++_i) \
;         __builtin_amdgcn_global_load_lds((const unsigned*)((const char*)(gbase) + (voff)[_i]), (PG8_LAS unsigned*)(lds + (bufoff) + ldsw + _i * 8192), 16, 0, 0); } while (0)
; #define PG8_LDA(dst, b, h) do { _Pragma("unroll") for (int m = 0; m < 4; ++m) _Pragma("unroll") for (int k = 0; k < 2; ++k) dst[m][k] = *(const PG8_LAS bf16x8*)(lds + PG8_SA(b, h) + aoff + m * 2048 + k * 1024); } while (0)
; #define PG8_LDB(dst, b, h) do { _Pragma("unroll") for (int n = 0; n < 2; ++n) _Pragma("unroll") for (int k = 0; k < 2; ++k) dst[n][k] = *(const PG8_LAS bf16x8*)(lds + PG8_SB(b, h) + boff + n * 2048 + k * 1024); } while (0)
; #define PG8_MMA(ai, bj, At, Bt) do { __builtin_amdgcn_s_setprio(1); _Pragma("unroll") for (int m = 0; m < 4; ++m) _Pragma("unroll") for (int n = 0; n < 2; ++n) _Pragma("unroll") for (int k = 0; k < 2; ++k) \
;         acc[ai][bj][m][n] = __builtin_amdgcn_mfma_f32_16x16x32_bf16(Bt[n][k], At[m][k], acc[ai][bj][m][n], 0, 0, 0); __builtin_amdgcn_s_setprio(0); } while (0)
; #define PG8_WAIT_V(n) asm volatile("s_waitcnt vmcnt(" #n ")" ::: "memory")
; #define PG8_WAIT_L(n) asm volatile("s_waitcnt lgkmcnt(" #n ")" ::: "memory")
; #define PG8_BAR __builtin_amdgcn_s_barrier()
; #define PG8_SCHED __builtin_amdgcn_sched_barrier(0)
;     ...
;             PG8_LDB(B0, 0, 0); PG8_LDB(B1, 0, 1); PG8_SCHED; PG8_LDA(At, 0, 0); PG8_STAGE(PG8_SA(1, 1), a1 + hstepA, voffA);
;             PG8_WAIT_V(8); PG8_WAIT_L(0); PG8_BAR; PG8_MMA(0, 0, At, B0); PG8_MMA(0, 1, At, B1); PG8_BAR; PG8_SCHED;
.LBB0_1414:
	ds_read_b128 v[128:131], v163
	ds_read_b128 v[132:135], v163 offset:1024
	ds_read_b128 v[152:155], v163 offset:2048
	ds_read_b128 v[156:159], v163 offset:3072
	ds_read_b128 v[166:169], v164
	ds_read_b128 v[170:173], v164 offset:1024
	ds_read_b128 v[174:177], v164 offset:2048
	ds_read_b128 v[178:181], v164 offset:3072
	s_add_u32 s28, s26, 0xfff00080
	s_addc_u32 s29, s27, -1
	s_cmp_eq_u32 s52, 60
	s_cselect_b32 s35, s21, s29
	s_cselect_b32 s34, s48, s28
	s_cselect_b32 s29, s19, s51
	s_cselect_b32 s28, s49, s50
	v_lshl_add_u64 v[160:161], s[26:27], 0, v[144:145]
	s_add_i32 m0, s8, 0xc000
	ds_read_b128 v[182:185], v165
	ds_read_b128 v[186:189], v165 offset:1024
	ds_read_b128 v[190:193], v165 offset:2048
	ds_read_b128 v[194:197], v165 offset:3072
	ds_read_b128 v[198:201], v165 offset:4096
	ds_read_b128 v[202:205], v165 offset:5120
	ds_read_b128 v[206:209], v165 offset:6144
	ds_read_b128 v[210:213], v165 offset:7168
	global_load_lds_dwordx4 v[160:161], off
	v_lshl_add_u64 v[160:161], s[26:27], 0, v[146:147]
	s_add_i32 m0, s8, 0xe000
	s_nop 0
	global_load_lds_dwordx4 v[160:161], off
	s_waitcnt vmcnt(8)
	s_waitcnt lgkmcnt(0)
	s_setprio 1
	s_cmp_lg_u32 s98, 0
	s_cbranch_scc0 .Lpg_b1_73
	s_barrier
	s_setprio 2
.Lpg_b1_73:
	s_waitcnt lgkmcnt(0)
	v_mfma_f32_16x16x32_bf16 v[124:127], v[128:131], v[182:185], v[124:127]
	v_mfma_f32_16x16x32_bf16 v[120:123], v[152:155], v[182:185], v[120:123]
	v_mfma_f32_16x16x32_bf16 v[108:111], v[128:131], v[190:193], v[108:111]
	v_mfma_f32_16x16x32_bf16 v[104:107], v[152:155], v[190:193], v[104:107]
	v_mfma_f32_16x16x32_bf16 v[92:95], v[128:131], v[198:201], v[92:95]
	v_mfma_f32_16x16x32_bf16 v[88:91], v[152:155], v[198:201], v[88:91]
	v_mfma_f32_16x16x32_bf16 v[76:79], v[128:131], v[206:209], v[76:79]
	v_mfma_f32_16x16x32_bf16 v[72:75], v[152:155], v[206:209], v[72:75]
	v_mfma_f32_16x16x32_bf16 v[124:127], v[132:135], v[186:189], v[124:127]
	v_mfma_f32_16x16x32_bf16 v[120:123], v[156:159], v[186:189], v[120:123]
	v_mfma_f32_16x16x32_bf16 v[108:111], v[132:135], v[194:197], v[108:111]
	v_mfma_f32_16x16x32_bf16 v[104:107], v[156:159], v[194:197], v[104:107]
	v_mfma_f32_16x16x32_bf16 v[92:95], v[132:135], v[202:205], v[92:95]
	v_mfma_f32_16x16x32_bf16 v[88:91], v[156:159], v[202:205], v[88:91]
	v_mfma_f32_16x16x32_bf16 v[76:79], v[132:135], v[210:213], v[76:79]
	v_mfma_f32_16x16x32_bf16 v[72:75], v[156:159], v[210:213], v[72:75]
	v_mfma_f32_16x16x32_bf16 v[116:119], v[166:169], v[182:185], v[116:119]
	v_mfma_f32_16x16x32_bf16 v[112:115], v[174:177], v[182:185], v[112:115]
	v_mfma_f32_16x16x32_bf16 v[100:103], v[166:169], v[190:193], v[100:103]
	v_mfma_f32_16x16x32_bf16 v[96:99], v[174:177], v[190:193], v[96:99]
	v_mfma_f32_16x16x32_bf16 v[84:87], v[166:169], v[198:201], v[84:87]
	v_mfma_f32_16x16x32_bf16 v[80:83], v[174:177], v[198:201], v[80:83]
	v_mfma_f32_16x16x32_bf16 v[68:71], v[166:169], v[206:209], v[68:71]
	v_mfma_f32_16x16x32_bf16 v[64:67], v[174:177], v[206:209], v[64:67]
	v_mfma_f32_16x16x32_bf16 v[116:119], v[170:173], v[186:189], v[116:119]
	v_mfma_f32_16x16x32_bf16 v[112:115], v[178:181], v[186:189], v[112:115]
	v_mfma_f32_16x16x32_bf16 v[100:103], v[170:173], v[194:197], v[100:103]
	v_mfma_f32_16x16x32_bf16 v[96:99], v[178:181], v[194:197], v[96:99]
	v_mfma_f32_16x16x32_bf16 v[84:87], v[170:173], v[202:205], v[84:87]
	v_mfma_f32_16x16x32_bf16 v[80:83], v[178:181], v[202:205], v[80:83]
	v_mfma_f32_16x16x32_bf16 v[68:71], v[170:173], v[210:213], v[68:71]
	v_mfma_f32_16x16x32_bf16 v[64:67], v[178:181], v[210:213], v[64:67]
	s_setprio 0
	s_cmp_lg_u32 s98, 0
	s_cbranch_scc1 .Lpg_b2_74
	s_barrier
; #define PG8_STAGE(bufoff, gbase, voff) do { _Pragma("unroll") for (int _i = 0; _i < 2; ++_i) \
;         __builtin_amdgcn_global_load_lds((const unsigned*)((const char*)(gbase) + (voff)[_i]), (PG8_LAS unsigned*)(lds + (bufoff) + ldsw + _i * 8192), 16, 0, 0); } while (0)
; #define PG8_LDA(dst, b, h) do { _Pragma("unroll") for (int m = 0; m < 4; ++m) _Pragma("unroll") for (int k = 0; k < 2; ++k) dst[m][k] = *(const PG8_LAS bf16x8*)(lds + PG8_SA(b, h) + aoff + m * 2048 + k * 1024); } while (0)
; #define PG8_LDB(dst, b, h) do { _Pragma("unroll") for (int n = 0; n < 2; ++n) _Pragma("unroll") for (int k = 0; k < 2; ++k) dst[n][k] = *(const PG8_LAS bf16x8*)(lds + PG8_SB(b, h) + boff + n * 2048 + k * 1024); } while (0)
; #define PG8_MMA(ai, bj, At, Bt) do { __builtin_amdgcn_s_setprio(1); _Pragma("unroll") for (int m = 0; m < 4; ++m) _Pragma("unroll") for (int n = 0; n < 2; ++n) _Pragma("unroll") for (int k = 0; k < 2; ++k) \
;         acc[ai][bj][m][n] = __builtin_amdgcn_mfma_f32_16x16x32_bf16(Bt[n][k], At[m][k], acc[ai][bj][m][n], 0, 0, 0); __builtin_amdgcn_s_setprio(0); } while (0)
; #define PG8_WAIT_V(n) asm volatile("s_waitcnt vmcnt(" #n ")" ::: "memory")
; #define PG8_WAIT_L(n) asm volatile("s_waitcnt lgkmcnt(" #n ")" ::: "memory")
; #define PG8_BAR __builtin_amdgcn_s_barrier()
; #define PG8_SCHED __builtin_amdgcn_sched_barrier(0)
;     ...
;             PG8_LDA(At, 0, 1); PG8_STAGE(PG8_SB(0, 0), b2, voffB); PG8_STAGE(PG8_SB(0, 1), b2 + hstepB, voffB); PG8_STAGE(PG8_SA(0, 0), a2, voffA);
;             PG8_WAIT_V(8); PG8_WAIT_L(0); PG8_BAR; PG8_MMA(1, 0, At, B0); PG8_MMA(1, 1, At, B1); PG8_BAR; PG8_SCHED;
;             PG8_LDB(B0, 1, 0); PG8_LDB(B1, 1, 1); PG8_SCHED; PG8_LDA(At, 1, 0); PG8_STAGE(PG8_SA(0, 1), a2 + hstepA, voffA);
;             PG8_WAIT_V(8); PG8_WAIT_L(0); PG8_BAR; PG8_MMA(0, 0, At, B0); PG8_MMA(0, 1, At, B1); PG8_BAR; PG8_SCHED;
.Lpg_b2_74:
	s_add_i32 s53, s46, s39
	v_lshl_add_u64 v[160:161], s[28:29], 0, v[140:141]
	s_mov_b32 m0, s53
	ds_read_b128 v[182:185], v165 offset:16384
	ds_read_b128 v[186:189], v165 offset:17408
	ds_read_b128 v[190:193], v165 offset:18432
	ds_read_b128 v[194:197], v165 offset:19456
	ds_read_b128 v[198:201], v165 offset:20480
	ds_read_b128 v[202:205], v165 offset:21504
	ds_read_b128 v[206:209], v165 offset:22528
	ds_read_b128 v[210:213], v165 offset:23552
	global_load_lds_dwordx4 v[160:161], off
	s_add_i32 m0, s53, 0x2000
	s_add_u32 s54, s28, 0x100000
	v_lshl_add_u64 v[214:215], s[28:29], 0, v[136:137]
	s_addc_u32 s55, s29, 0
	s_add_i32 s53, s47, s39
	global_load_lds_dwordx4 v[214:215], off
	v_lshl_add_u64 v[216:217], s[54:55], 0, v[140:141]
	s_mov_b32 m0, s53
	v_lshl_add_u64 v[218:219], s[34:35], 0, v[138:139]
	global_load_lds_dwordx4 v[216:217], off
	v_lshl_add_u64 v[216:217], s[54:55], 0, v[136:137]
	s_add_i32 m0, s53, 0x2000
	s_nop 0
	global_load_lds_dwordx4 v[216:217], off
	v_lshl_add_u64 v[216:217], s[34:35], 0, v[142:143]
	s_mov_b32 m0, s8
	s_nop 0
	global_load_lds_dwordx4 v[216:217], off
	s_mov_b32 m0, s13
	s_nop 0
	global_load_lds_dwordx4 v[218:219], off
	s_waitcnt vmcnt(8)
	s_waitcnt lgkmcnt(0)
	s_setprio 1
	s_cmp_lg_u32 s98, 0
	s_cbranch_scc0 .Lpg_b1_75
	s_barrier
	s_setprio 2
.Lpg_b1_75:
	s_waitcnt lgkmcnt(0)
	v_mfma_f32_16x16x32_bf16 v[60:63], v[128:131], v[182:185], v[60:63]
	v_mfma_f32_16x16x32_bf16 v[56:59], v[152:155], v[182:185], v[56:59]
	v_mfma_f32_16x16x32_bf16 v[48:51], v[128:131], v[190:193], v[48:51]
	v_mfma_f32_16x16x32_bf16 v[40:43], v[152:155], v[190:193], v[40:43]
	v_mfma_f32_16x16x32_bf16 v[32:35], v[128:131], v[198:201], v[32:35]
	v_mfma_f32_16x16x32_bf16 v[24:27], v[152:155], v[198:201], v[24:27]
	v_mfma_f32_16x16x32_bf16 v[16:19], v[128:131], v[206:209], v[16:19]
	v_mfma_f32_16x16x32_bf16 v[8:11], v[152:155], v[206:209], v[8:11]
	v_mfma_f32_16x16x32_bf16 v[60:63], v[132:135], v[186:189], v[60:63]
	v_mfma_f32_16x16x32_bf16 v[56:59], v[156:159], v[186:189], v[56:59]
	v_mfma_f32_16x16x32_bf16 v[48:51], v[132:135], v[194:197], v[48:51]
	v_mfma_f32_16x16x32_bf16 v[40:43], v[156:159], v[194:197], v[40:43]
	v_mfma_f32_16x16x32_bf16 v[32:35], v[132:135], v[202:205], v[32:35]
	v_mfma_f32_16x16x32_bf16 v[24:27], v[156:159], v[202:205], v[24:27]
	v_mfma_f32_16x16x32_bf16 v[16:19], v[132:135], v[210:213], v[16:19]
	v_mfma_f32_16x16x32_bf16 v[8:11], v[156:159], v[210:213], v[8:11]
	v_mfma_f32_16x16x32_bf16 v[52:55], v[166:169], v[182:185], v[52:55]
	v_mfma_f32_16x16x32_bf16 v[44:47], v[174:177], v[182:185], v[44:47]
	v_mfma_f32_16x16x32_bf16 v[36:39], v[166:169], v[190:193], v[36:39]
	v_mfma_f32_16x16x32_bf16 v[28:31], v[174:177], v[190:193], v[28:31]
	v_mfma_f32_16x16x32_bf16 v[20:23], v[166:169], v[198:201], v[20:23]
	v_mfma_f32_16x16x32_bf16 v[12:15], v[174:177], v[198:201], v[12:15]
	v_mfma_f32_16x16x32_bf16 v[4:7], v[166:169], v[206:209], v[4:7]
	v_mfma_f32_16x16x32_bf16 v[0:3], v[174:177], v[206:209], v[0:3]
	v_mfma_f32_16x16x32_bf16 v[52:55], v[170:173], v[186:189], v[52:55]
	v_mfma_f32_16x16x32_bf16 v[44:47], v[178:181], v[186:189], v[44:47]
	v_mfma_f32_16x16x32_bf16 v[36:39], v[170:173], v[194:197], v[36:39]
	v_mfma_f32_16x16x32_bf16 v[28:31], v[178:181], v[194:197], v[28:31]
	v_mfma_f32_16x16x32_bf16 v[20:23], v[170:173], v[202:205], v[20:23]
	v_mfma_f32_16x16x32_bf16 v[12:15], v[178:181], v[202:205], v[12:15]
	v_mfma_f32_16x16x32_bf16 v[4:7], v[170:173], v[210:213], v[4:7]
	v_mfma_f32_16x16x32_bf16 v[0:3], v[178:181], v[210:213], v[0:3]
	s_setprio 0
	s_cmp_lg_u32 s98, 0
	s_cbranch_scc1 .Lpg_b2_76
	s_barrier
.Lpg_b2_76:
	s_add_i32 s53, 0, 0x18000
	s_add_i32 s54, 0, 0x1c000
	v_add_u32_e32 v156, s53, v162
	v_add_u32_e32 v178, s54, v162
	ds_read_b128 v[128:131], v156
	ds_read_b128 v[132:135], v156 offset:1024
	ds_read_b128 v[152:155], v156 offset:2048
	ds_read_b128 v[156:159], v156 offset:3072
	ds_read_b128 v[166:169], v178
	ds_read_b128 v[170:173], v178 offset:1024
	ds_read_b128 v[174:177], v178 offset:2048
	ds_read_b128 v[178:181], v178 offset:3072
	s_add_u32 s34, s34, 0x100000
	s_addc_u32 s35, s35, 0
	s_mov_b32 m0, s40
	v_lshl_add_u64 v[220:221], s[34:35], 0, v[142:143]
	ds_read_b128 v[182:185], v165 offset:32768
	ds_read_b128 v[186:189], v165 offset:33792
	ds_read_b128 v[190:193], v165 offset:34816
	ds_read_b128 v[194:197], v165 offset:35840
	ds_read_b128 v[198:201], v165 offset:36864
	ds_read_b128 v[202:205], v165 offset:37888
	ds_read_b128 v[206:209], v165 offset:38912
	ds_read_b128 v[210:213], v165 offset:39936
	global_load_lds_dwordx4 v[220:221], off
	v_lshl_add_u64 v[220:221], s[34:35], 0, v[138:139]
	s_mov_b32 m0, s41
	s_nop 0
	global_load_lds_dwordx4 v[220:221], off
	s_waitcnt vmcnt(8)
	s_waitcnt lgkmcnt(0)
	s_setprio 1
	s_cmp_lg_u32 s98, 0
	s_cbranch_scc0 .Lpg_b1_77
	s_barrier
	s_setprio 2

; #define PG8_STAGE(bufoff, gbase, voff) do { _Pragma("unroll") for (int _i = 0; _i < 2; ++_i) \
;         __builtin_amdgcn_global_load_lds((const unsigned*)((const char*)(gbase) + (voff)[_i]), (PG8_LAS unsigned*)(lds + (bufoff) + ldsw + _i * 8192), 16, 0, 0); } while (0)
; #define PG8_LDA(dst, b, h) do { _Pragma("unroll") for (int m = 0; m < 4; ++m) _Pragma("unroll") for (int k = 0; k < 2; ++k) dst[m][k] = *(const PG8_LAS bf16x8*)(lds + PG8_SA(b, h) + aoff + m * 2048 + k * 1024); } while (0)
; #define PG8_MMA(ai, bj, At, Bt) do { __builtin_amdgcn_s_setprio(1); _Pragma("unroll") for (int m = 0; m < 4; ++m) _Pragma("unroll") for (int n = 0; n < 2; ++n) _Pragma("unroll") for (int k = 0; k < 2; ++k) \
;         acc[ai][bj][m][n] = __builtin_amdgcn_mfma_f32_16x16x32_bf16(Bt[n][k], At[m][k], acc[ai][bj][m][n], 0, 0, 0); __builtin_amdgcn_s_setprio(0); } while (0)
; #define PG8_WAIT_V(n) asm volatile("s_waitcnt vmcnt(" #n ")" ::: "memory")
; #define PG8_WAIT_L(n) asm volatile("s_waitcnt lgkmcnt(" #n ")" ::: "memory")
; #define PG8_BAR __builtin_amdgcn_s_barrier()
; #define PG8_SCHED __builtin_amdgcn_sched_barrier(0)
;     ...
;             PG8_LDA(At, 1, 1); PG8_STAGE(PG8_SB(1, 0), b3, voffB); PG8_STAGE(PG8_SB(1, 1), b3 + hstepB, voffB); PG8_STAGE(PG8_SA(1, 0), a3, voffA);
;             PG8_WAIT_V(8); PG8_WAIT_L(0); PG8_BAR; PG8_MMA(1, 0, At, B0); PG8_MMA(1, 1, At, B1); PG8_BAR; PG8_SCHED;
.Lpg_b2_78:
	s_add_i32 s34, s53, s39
	v_lshl_add_u64 v[160:161], v[160:161], 0, s[14:15]
	s_mov_b32 m0, s34
	ds_read_b128 v[182:185], v165 offset:49152
	ds_read_b128 v[186:189], v165 offset:50176
	ds_read_b128 v[190:193], v165 offset:51200
	ds_read_b128 v[194:197], v165 offset:52224
	ds_read_b128 v[198:201], v165 offset:53248
	ds_read_b128 v[202:205], v165 offset:54272
	ds_read_b128 v[206:209], v165 offset:55296
	ds_read_b128 v[210:213], v165 offset:56320
	global_load_lds_dwordx4 v[160:161], off
	s_add_i32 m0, s34, 0x2000
	s_add_u32 s28, s28, 0x100080
	v_lshl_add_u64 v[160:161], v[214:215], 0, s[14:15]
	s_addc_u32 s29, s29, 0
	s_add_i32 s34, s54, s39
	global_load_lds_dwordx4 v[160:161], off
	v_lshl_add_u64 v[160:161], s[28:29], 0, v[140:141]
	s_mov_b32 m0, s34
	s_nop 0
	global_load_lds_dwordx4 v[160:161], off
	v_lshl_add_u64 v[160:161], s[28:29], 0, v[136:137]
	s_add_i32 m0, s34, 0x2000
	s_nop 0
	global_load_lds_dwordx4 v[160:161], off
	v_lshl_add_u64 v[160:161], v[216:217], 0, s[14:15]
	s_mov_b32 m0, s44
	s_nop 0
	global_load_lds_dwordx4 v[160:161], off
	v_lshl_add_u64 v[160:161], v[218:219], 0, s[14:15]
	s_mov_b32 m0, s45
	s_nop 0
	global_load_lds_dwordx4 v[160:161], off
	s_waitcnt vmcnt(8)
	s_waitcnt lgkmcnt(0)
	s_setprio 1
	s_cmp_lg_u32 s98, 0
	s_cbranch_scc0 .Lpg_b1_79
	s_barrier
	s_setprio 2

; #define PG8_BAR __builtin_amdgcn_s_barrier()
; DI float bflo(unsigned w) { return __uint_as_float(w << 16); }
; DI float bfhi(unsigned w) { return __uint_as_float(w & 0xffff0000u); }
; #define ACC8(v, ai, bj, m, s) do { const f32x4 a_ = acc[ai][bj][m][0] * (s), b_ = acc[ai][bj][m][1] * (s); v[0] = a_[0]; v[1] = a_[1]; v[2] = a_[2]; v[3] = a_[3]; v[4] = b_[0]; v[5] = b_[1]; v[6] = b_[2]; v[7] = b_[3]; } while (0)
; #define ITLOOP _Pragma("unroll") for (int it = 0; it < 8; ++it)
; #define BJLOOP _Pragma("unroll") for (int bj = 0; bj < 2; ++bj)
; #define SBE() __builtin_amdgcn_sched_barrier(0)
; #define RES_LOAD(itn, buf) do { const float* p_ = b.x + (size_t)(grow0 + ((itn) >> 2) * 128 + ((itn) & 3) * 16) * 1024 + tc0; BJLOOP { px[buf][bj][0] = *(const f32x4*)(p_ + bj * 128); px[buf][bj][1] = *(const f32x4*)(p_ + bj * 128 + 4); } } while (0)
; #define RES_LOAD(itn, buf) do { const bf16_t* p_ = b.x1b + (size_t)(grow0 + ((itn) >> 2) * 128 + ((itn) & 3) * 16) * 1024 + tc0; BJLOOP { px[buf][bj] = *(const u32x4*)(p_ + bj * 128); } } while (0)
;     ...
;         }
;         if constexpr (ALIGN_EPI) { if (wr == 0) PG8_BAR; }
;     DI void operator()(const AccT& acc, const pg8::Unit& u, int wr, int wc, int fr_in, int fq_in) const {
;     ...
;         if (KIND == K_FF2) {
;             u32x4 px[4][2];
;     ...
;             RES_LOAD(0, 0); RES_LOAD(1, 1); RES_LOAD(2, 2); RES_LOAD(3, 3); SBE();
;             ITLOOP {
;                 BJLOOP { float v[8]; ACC8(v, IT_AI, bj, IT_M, 1.0f); const u32x4 w = px[it & 3][bj];
;                     float* op = b.out + IT_ROW * 1024 + tc0 + bj * 128;
;                     *(f32x4*)op = (f32x4){v[0] + bflo(w.x), v[1] + bfhi(w.x), v[2] + bflo(w.y), v[3] + bfhi(w.y)}; *(f32x4*)(op + 4) = (f32x4){v[4] + bflo(w.z), v[5] + bfhi(w.z), v[6] + bflo(w.w), v[7] + bfhi(w.w)}; }
;                 SBE(); if (it + 4 < 8) RES_LOAD(it + 4, it & 3); SBE(); }
.Lpg_b2_80:
	s_add_i32 s52, s52, 2
	s_add_u32 s26, s26, 0x100
	s_addc_u32 s27, s27, 0
	s_add_u32 s50, s50, 0x100
	s_addc_u32 s51, s51, 0
	s_cmp_gt_u32 s52, 61
	s_cbranch_scc0 .LBB0_1414
	s_and_b64 vcc, exec, s[16:17]
	s_cbranch_vccz .LBB0_1417
.LBB0_1417:
	s_lshl_b32 s12, s12, 8
	v_mbcnt_lo_u32_b32 v128, -1, 0
	v_mbcnt_hi_u32_b32 v128, -1, v128
	s_add_i32 s12, s12, s42
	v_and_or_b32 v154, v128, 15, s12
	v_ashrrev_i32_e32 v128, 1, v128
	s_lshl_b32 s2, s2, 8
	v_and_b32_e32 v128, -8, v128
	s_or_b32 s2, s2, s43
	v_add_u32_e32 v152, s2, v128
	v_ashrrev_i32_e32 v155, 31, v154
	v_lshlrev_b64 v[128:129], 11, v[154:155]
	v_ashrrev_i32_e32 v153, 31, v152
	v_lshl_add_u64 v[128:129], s[6:7], 0, v[128:129]
	v_lshlrev_b64 v[156:157], 1, v[152:153]
	v_or_b32_e32 v190, 16, v154
	v_lshl_add_u64 v[128:129], v[128:129], 0, v[156:157]
	v_ashrrev_i32_e32 v191, 31, v190
	global_load_dwordx4 v[166:169], v[128:129], off
	global_load_dwordx4 v[170:173], v[128:129], off offset:256
	v_lshlrev_b64 v[128:129], 11, v[190:191]
	v_lshl_add_u64 v[128:129], s[6:7], 0, v[128:129]
	v_or_b32_e32 v192, 32, v154
	v_lshl_add_u64 v[128:129], v[128:129], 0, v[156:157]
	v_ashrrev_i32_e32 v193, 31, v192
	global_load_dwordx4 v[174:177], v[128:129], off
	global_load_dwordx4 v[178:181], v[128:129], off offset:256
	v_lshlrev_b64 v[128:129], 11, v[192:193]
	v_lshl_add_u64 v[128:129], s[6:7], 0, v[128:129]
	v_or_b32_e32 v160, 48, v154
	v_lshl_add_u64 v[128:129], v[128:129], 0, v[156:157]
	v_ashrrev_i32_e32 v161, 31, v160
	global_load_dwordx4 v[182:185], v[128:129], off
	global_load_dwordx4 v[186:189], v[128:129], off offset:256
	v_lshlrev_b64 v[128:129], 11, v[160:161]
	v_lshl_add_u64 v[128:129], s[6:7], 0, v[128:129]
	v_lshl_add_u64 v[128:129], v[128:129], 0, v[156:157]
	global_load_dwordx4 v[132:135], v[128:129], off
	s_nop 0
	global_load_dwordx4 v[128:131], v[128:129], off offset:256
	v_lshlrev_b64 v[194:195], 12, v[154:155]
	v_lshl_add_u64 v[194:195], s[4:5], 0, v[194:195]
	v_lshlrev_b64 v[152:153], 2, v[152:153]
	s_waitcnt vmcnt(0)
	v_lshlrev_b32_e32 v196, 16, v166
	v_and_b32_e32 v197, 0xffff0000, v166
	v_lshlrev_b32_e32 v166, 16, v167
	v_and_b32_e32 v167, 0xffff0000, v167
	v_lshl_add_u64 v[194:195], v[194:195], 0, v[152:153]
	v_pk_add_f32 v[124:125], v[124:125], v[196:197]
	v_pk_add_f32 v[126:127], v[126:127], v[166:167]
	global_store_dwordx4 v[194:195], v[124:127], off
	v_add_u32_e32 v158, 0x80, v154
	s_nop 0
	v_lshlrev_b32_e32 v124, 16, v168
	v_and_b32_e32 v125, 0xffff0000, v168
	v_pk_add_f32 v[120:121], v[120:121], v[124:125]
	v_lshlrev_b32_e32 v124, 16, v169
	v_and_b32_e32 v125, 0xffff0000, v169
	v_pk_add_f32 v[122:123], v[122:123], v[124:125]
	global_store_dwordx4 v[194:195], v[120:123], off offset:16
	s_nop 1
	v_lshlrev_b32_e32 v120, 16, v170
	v_and_b32_e32 v121, 0xffff0000, v170
	v_pk_add_f32 v[116:117], v[116:117], v[120:121]
	v_lshlrev_b32_e32 v120, 16, v171
	v_and_b32_e32 v121, 0xffff0000, v171
	v_pk_add_f32 v[118:119], v[118:119], v[120:121]
	global_store_dwordx4 v[194:195], v[116:119], off offset:512
	s_nop 1
	v_lshlrev_b32_e32 v116, 16, v172
	v_and_b32_e32 v117, 0xffff0000, v172
	v_pk_add_f32 v[112:113], v[112:113], v[116:117]
	v_lshlrev_b32_e32 v116, 16, v173
	v_and_b32_e32 v117, 0xffff0000, v173
	v_pk_add_f32 v[114:115], v[114:115], v[116:117]
	global_store_dwordx4 v[194:195], v[112:115], off offset:528
	v_ashrrev_i32_e32 v159, 31, v158
	s_nop 0
	v_lshlrev_b64 v[112:113], 11, v[158:159]
	v_lshl_add_u64 v[112:113], s[6:7], 0, v[112:113]
	v_lshl_add_u64 v[112:113], v[112:113], 0, v[156:157]
	global_load_dwordx4 v[116:119], v[112:113], off
	s_nop 0
	global_load_dwordx4 v[112:115], v[112:113], off offset:256
	v_lshlrev_b64 v[120:121], 12, v[190:191]
	v_lshlrev_b32_e32 v122, 16, v174
	v_and_b32_e32 v123, 0xffff0000, v174
	v_lshl_add_u64 v[120:121], s[4:5], 0, v[120:121]
	v_pk_add_f32 v[108:109], v[108:109], v[122:123]
	v_lshlrev_b32_e32 v122, 16, v175
	v_and_b32_e32 v123, 0xffff0000, v175
	v_lshl_add_u64 v[120:121], v[120:121], 0, v[152:153]
	v_pk_add_f32 v[110:111], v[110:111], v[122:123]
	global_store_dwordx4 v[120:121], v[108:111], off
	s_nop 1
	v_lshlrev_b32_e32 v108, 16, v176
	v_and_b32_e32 v109, 0xffff0000, v176
	v_pk_add_f32 v[104:105], v[104:105], v[108:109]
	v_lshlrev_b32_e32 v108, 16, v177
	v_and_b32_e32 v109, 0xffff0000, v177
	v_pk_add_f32 v[106:107], v[106:107], v[108:109]
	global_store_dwordx4 v[120:121], v[104:107], off offset:16
	s_nop 1
	v_lshlrev_b32_e32 v104, 16, v178
	v_and_b32_e32 v105, 0xffff0000, v178
	v_pk_add_f32 v[100:101], v[100:101], v[104:105]
	v_lshlrev_b32_e32 v104, 16, v179
	v_and_b32_e32 v105, 0xffff0000, v179
	v_pk_add_f32 v[102:103], v[102:103], v[104:105]
	global_store_dwordx4 v[120:121], v[100:103], off offset:512
	s_nop 1
	v_lshlrev_b32_e32 v100, 16, v180
	v_and_b32_e32 v101, 0xffff0000, v180
	v_pk_add_f32 v[96:97], v[96:97], v[100:101]
	v_lshlrev_b32_e32 v100, 16, v181
	v_and_b32_e32 v101, 0xffff0000, v181
	v_pk_add_f32 v[98:99], v[98:99], v[100:101]
	global_store_dwordx4 v[120:121], v[96:99], off offset:528
	v_add_u32_e32 v104, 0x90, v154
	v_ashrrev_i32_e32 v105, 31, v104
	v_lshlrev_b64 v[96:97], 11, v[104:105]
	v_lshl_add_u64 v[96:97], s[6:7], 0, v[96:97]
	v_lshl_add_u64 v[96:97], v[96:97], 0, v[156:157]
	global_load_dwordx4 v[100:103], v[96:97], off
	s_nop 0
	global_load_dwordx4 v[96:99], v[96:97], off offset:256
	v_lshlrev_b64 v[106:107], 12, v[192:193]
	v_lshlrev_b32_e32 v108, 16, v182
	v_and_b32_e32 v109, 0xffff0000, v182
	v_lshl_add_u64 v[106:107], s[4:5], 0, v[106:107]
	v_pk_add_f32 v[92:93], v[92:93], v[108:109]
	v_lshlrev_b32_e32 v108, 16, v183
	v_and_b32_e32 v109, 0xffff0000, v183
	v_lshl_add_u64 v[106:107], v[106:107], 0, v[152:153]
; DI float bflo(unsigned w) { return __uint_as_float(w << 16); }
; DI float bfhi(unsigned w) { return __uint_as_float(w & 0xffff0000u); }
; #define ACC8(v, ai, bj, m, s) do { const f32x4 a_ = acc[ai][bj][m][0] * (s), b_ = acc[ai][bj][m][1] * (s); v[0] = a_[0]; v[1] = a_[1]; v[2] = a_[2]; v[3] = a_[3]; v[4] = b_[0]; v[5] = b_[1]; v[6] = b_[2]; v[7] = b_[3]; } while (0)
; #define ITLOOP _Pragma("unroll") for (int it = 0; it < 8; ++it)
; #define BJLOOP _Pragma("unroll") for (int bj = 0; bj < 2; ++bj)
; #define SBE() __builtin_amdgcn_sched_barrier(0)
; #define RES_LOAD(itn, buf) do { const float* p_ = b.x + (size_t)(grow0 + ((itn) >> 2) * 128 + ((itn) & 3) * 16) * 1024 + tc0; BJLOOP { px[buf][bj][0] = *(const f32x4*)(p_ + bj * 128); px[buf][bj][1] = *(const f32x4*)(p_ + bj * 128 + 4); } } while (0)
; #define RES_LOAD(itn, buf) do { const bf16_t* p_ = b.x1b + (size_t)(grow0 + ((itn) >> 2) * 128 + ((itn) & 3) * 16) * 1024 + tc0; BJLOOP { px[buf][bj] = *(const u32x4*)(p_ + bj * 128); } } while (0)
;     DI void operator()(const AccT& acc, const pg8::Unit& u, int wr, int wc, int fr_in, int fq_in) const {
;     ...
;         if (KIND == K_FF2) {
;             u32x4 px[4][2];
;     ...
;             RES_LOAD(0, 0); RES_LOAD(1, 1); RES_LOAD(2, 2); RES_LOAD(3, 3); SBE();
;             ITLOOP {
;                 BJLOOP { float v[8]; ACC8(v, IT_AI, bj, IT_M, 1.0f); const u32x4 w = px[it & 3][bj];
;                     float* op = b.out + IT_ROW * 1024 + tc0 + bj * 128;
;                     *(f32x4*)op = (f32x4){v[0] + bflo(w.x), v[1] + bfhi(w.x), v[2] + bflo(w.y), v[3] + bfhi(w.y)}; *(f32x4*)(op + 4) = (f32x4){v[4] + bflo(w.z), v[5] + bfhi(w.z), v[6] + bflo(w.w), v[7] + bfhi(w.w)}; }
;                 SBE(); if (it + 4 < 8) RES_LOAD(it + 4, it & 3); SBE(); }
	v_pk_add_f32 v[94:95], v[94:95], v[108:109]
	global_store_dwordx4 v[106:107], v[92:95], off
	s_nop 1
	v_lshlrev_b32_e32 v92, 16, v184
	v_and_b32_e32 v93, 0xffff0000, v184
	v_pk_add_f32 v[88:89], v[88:89], v[92:93]
	v_lshlrev_b32_e32 v92, 16, v185
	v_and_b32_e32 v93, 0xffff0000, v185
	v_pk_add_f32 v[90:91], v[90:91], v[92:93]
	global_store_dwordx4 v[106:107], v[88:91], off offset:16
	s_nop 1
	v_lshlrev_b32_e32 v88, 16, v186
	v_and_b32_e32 v89, 0xffff0000, v186
	v_pk_add_f32 v[84:85], v[84:85], v[88:89]
	v_lshlrev_b32_e32 v88, 16, v187
	v_and_b32_e32 v89, 0xffff0000, v187
	v_pk_add_f32 v[86:87], v[86:87], v[88:89]
	global_store_dwordx4 v[106:107], v[84:87], off offset:512
	s_nop 1
	v_lshlrev_b32_e32 v84, 16, v188
	v_and_b32_e32 v85, 0xffff0000, v188
	v_pk_add_f32 v[80:81], v[80:81], v[84:85]
	v_lshlrev_b32_e32 v84, 16, v189
	v_and_b32_e32 v85, 0xffff0000, v189
	v_pk_add_f32 v[82:83], v[82:83], v[84:85]
	global_store_dwordx4 v[106:107], v[80:83], off offset:528
	v_add_u32_e32 v88, 0xa0, v154
	v_ashrrev_i32_e32 v89, 31, v88
	v_lshlrev_b64 v[80:81], 11, v[88:89]
	v_lshl_add_u64 v[80:81], s[6:7], 0, v[80:81]
	v_lshl_add_u64 v[80:81], v[80:81], 0, v[156:157]
	global_load_dwordx4 v[84:87], v[80:81], off
	s_nop 0
	global_load_dwordx4 v[80:83], v[80:81], off offset:256
	v_lshlrev_b64 v[90:91], 12, v[160:161]
	v_lshlrev_b32_e32 v92, 16, v132
	v_and_b32_e32 v93, 0xffff0000, v132
	v_lshl_add_u64 v[90:91], s[4:5], 0, v[90:91]
	v_pk_add_f32 v[76:77], v[76:77], v[92:93]
	v_lshlrev_b32_e32 v92, 16, v133
	v_and_b32_e32 v93, 0xffff0000, v133
	v_lshl_add_u64 v[90:91], v[90:91], 0, v[152:153]
	v_pk_add_f32 v[78:79], v[78:79], v[92:93]
	global_store_dwordx4 v[90:91], v[76:79], off
	s_nop 1
	v_lshlrev_b32_e32 v76, 16, v134
	v_and_b32_e32 v77, 0xffff0000, v134
	v_pk_add_f32 v[72:73], v[72:73], v[76:77]
	v_lshlrev_b32_e32 v76, 16, v135
	v_and_b32_e32 v77, 0xffff0000, v135
	v_pk_add_f32 v[74:75], v[74:75], v[76:77]
	global_store_dwordx4 v[90:91], v[72:75], off offset:16
	s_nop 1
	v_lshlrev_b32_e32 v72, 16, v128
	v_and_b32_e32 v73, 0xffff0000, v128
	v_pk_add_f32 v[68:69], v[68:69], v[72:73]
	v_lshlrev_b32_e32 v72, 16, v129
	v_and_b32_e32 v73, 0xffff0000, v129
	v_pk_add_f32 v[70:71], v[70:71], v[72:73]
	global_store_dwordx4 v[90:91], v[68:71], off offset:512
	s_nop 1
	v_lshlrev_b32_e32 v68, 16, v130
	v_and_b32_e32 v69, 0xffff0000, v130
	v_pk_add_f32 v[64:65], v[64:65], v[68:69]
	v_lshlrev_b32_e32 v68, 16, v131
	v_and_b32_e32 v69, 0xffff0000, v131
	v_pk_add_f32 v[66:67], v[66:67], v[68:69]
	global_store_dwordx4 v[90:91], v[64:67], off offset:528
	v_add_u32_e32 v72, 0xb0, v154
	v_ashrrev_i32_e32 v73, 31, v72
	v_lshlrev_b64 v[64:65], 11, v[72:73]
	v_lshl_add_u64 v[64:65], s[6:7], 0, v[64:65]
	v_lshl_add_u64 v[64:65], v[64:65], 0, v[156:157]
	global_load_dwordx4 v[68:71], v[64:65], off
	s_nop 0
	global_load_dwordx4 v[64:67], v[64:65], off offset:256
	v_lshlrev_b64 v[74:75], 12, v[158:159]
	s_waitcnt vmcnt(19)
	v_lshlrev_b32_e32 v76, 16, v116
	v_and_b32_e32 v77, 0xffff0000, v116
	v_lshl_add_u64 v[74:75], s[4:5], 0, v[74:75]
	v_pk_add_f32 v[60:61], v[60:61], v[76:77]
	v_lshlrev_b32_e32 v76, 16, v117
	v_and_b32_e32 v77, 0xffff0000, v117
	v_lshl_add_u64 v[74:75], v[74:75], 0, v[152:153]
	v_pk_add_f32 v[62:63], v[62:63], v[76:77]
	global_store_dwordx4 v[74:75], v[60:63], off
	s_nop 1
	v_lshlrev_b32_e32 v60, 16, v118
	v_and_b32_e32 v61, 0xffff0000, v118
	v_pk_add_f32 v[56:57], v[56:57], v[60:61]
	v_lshlrev_b32_e32 v60, 16, v119
	v_and_b32_e32 v61, 0xffff0000, v119
	v_pk_add_f32 v[58:59], v[58:59], v[60:61]
	global_store_dwordx4 v[74:75], v[56:59], off offset:16
	s_waitcnt vmcnt(20)
	s_nop 0
	v_lshlrev_b32_e32 v56, 16, v112
	v_and_b32_e32 v57, 0xffff0000, v112
	v_pk_add_f32 v[52:53], v[52:53], v[56:57]
	v_lshlrev_b32_e32 v56, 16, v113
	v_and_b32_e32 v57, 0xffff0000, v113
	v_pk_add_f32 v[54:55], v[54:55], v[56:57]
	global_store_dwordx4 v[74:75], v[52:55], off offset:512
	s_nop 1
	v_lshlrev_b32_e32 v52, 16, v114
	v_and_b32_e32 v53, 0xffff0000, v114
	v_pk_add_f32 v[44:45], v[44:45], v[52:53]
	v_lshlrev_b32_e32 v52, 16, v115
	v_and_b32_e32 v53, 0xffff0000, v115
	v_pk_add_f32 v[46:47], v[46:47], v[52:53]
	global_store_dwordx4 v[74:75], v[44:47], off offset:528
	s_nop 1
	v_lshlrev_b64 v[44:45], 12, v[104:105]
	v_lshl_add_u64 v[44:45], s[4:5], 0, v[44:45]
	v_lshl_add_u64 v[52:53], v[44:45], 0, v[152:153]
	s_waitcnt vmcnt(17)
; #define PG8_BAR __builtin_amdgcn_s_barrier()
; DI float bflo(unsigned w) { return __uint_as_float(w << 16); }
; DI float bfhi(unsigned w) { return __uint_as_float(w & 0xffff0000u); }
; #define ACC8(v, ai, bj, m, s) do { const f32x4 a_ = acc[ai][bj][m][0] * (s), b_ = acc[ai][bj][m][1] * (s); v[0] = a_[0]; v[1] = a_[1]; v[2] = a_[2]; v[3] = a_[3]; v[4] = b_[0]; v[5] = b_[1]; v[6] = b_[2]; v[7] = b_[3]; } while (0)
; #define ITLOOP _Pragma("unroll") for (int it = 0; it < 8; ++it)
; #define BJLOOP _Pragma("unroll") for (int bj = 0; bj < 2; ++bj)
; #define SBE() __builtin_amdgcn_sched_barrier(0)
; #define RES_LOAD(itn, buf) do { const float* p_ = b.x + (size_t)(grow0 + ((itn) >> 2) * 128 + ((itn) & 3) * 16) * 1024 + tc0; BJLOOP { px[buf][bj][0] = *(const f32x4*)(p_ + bj * 128); px[buf][bj][1] = *(const f32x4*)(p_ + bj * 128 + 4); } } while (0)
; #define RES_LOAD(itn, buf) do { const bf16_t* p_ = b.x1b + (size_t)(grow0 + ((itn) >> 2) * 128 + ((itn) & 3) * 16) * 1024 + tc0; BJLOOP { px[buf][bj] = *(const u32x4*)(p_ + bj * 128); } } while (0)
;     ...
;         if (!has_next) break;
; #pragma unroll
;         for (int a = 0; a < 2; ++a)
; #pragma unroll
;             for (int b = 0; b < 2; ++b)
; #pragma unroll
;                 for (int m = 0; m < 4; ++m)
; #pragma unroll
;                     for (int n = 0; n < 2; ++n) acc[a][b][m][n] = (f32x4){0.f, 0.f, 0.f, 0.f};
;         cur = nxt; cA = nA; cB = nB; ++ui;
;         if constexpr (ALIGN_EPI) { if (wr == 1) PG8_BAR; }
;     DI void operator()(const AccT& acc, const pg8::Unit& u, int wr, int wc, int fr_in, int fq_in) const {
;     ...
;         if (KIND == K_FF2) {
;             u32x4 px[4][2];
;     ...
;             RES_LOAD(0, 0); RES_LOAD(1, 1); RES_LOAD(2, 2); RES_LOAD(3, 3); SBE();
;             ITLOOP {
;                 BJLOOP { float v[8]; ACC8(v, IT_AI, bj, IT_M, 1.0f); const u32x4 w = px[it & 3][bj];
;                     float* op = b.out + IT_ROW * 1024 + tc0 + bj * 128;
;                     *(f32x4*)op = (f32x4){v[0] + bflo(w.x), v[1] + bfhi(w.x), v[2] + bflo(w.y), v[3] + bfhi(w.y)}; *(f32x4*)(op + 4) = (f32x4){v[4] + bflo(w.z), v[5] + bfhi(w.z), v[6] + bflo(w.w), v[7] + bfhi(w.w)}; }
;                 SBE(); if (it + 4 < 8) RES_LOAD(it + 4, it & 3); SBE(); }
	v_lshlrev_b32_e32 v44, 16, v100
	v_and_b32_e32 v45, 0xffff0000, v100
	v_lshlrev_b32_e32 v46, 16, v101
	v_and_b32_e32 v47, 0xffff0000, v101
	v_pk_add_f32 v[44:45], v[48:49], v[44:45]
	v_pk_add_f32 v[46:47], v[50:51], v[46:47]
	global_store_dwordx4 v[52:53], v[44:47], off
	s_nop 1
	v_lshlrev_b32_e32 v44, 16, v102
	v_and_b32_e32 v45, 0xffff0000, v102
	v_pk_add_f32 v[40:41], v[40:41], v[44:45]
	v_lshlrev_b32_e32 v44, 16, v103
	v_and_b32_e32 v45, 0xffff0000, v103
	v_pk_add_f32 v[42:43], v[42:43], v[44:45]
	global_store_dwordx4 v[52:53], v[40:43], off offset:16
	s_waitcnt vmcnt(18)
	s_nop 0
	v_lshlrev_b32_e32 v40, 16, v96
	v_and_b32_e32 v41, 0xffff0000, v96
	v_pk_add_f32 v[36:37], v[36:37], v[40:41]
	v_lshlrev_b32_e32 v40, 16, v97
	v_and_b32_e32 v41, 0xffff0000, v97
	v_pk_add_f32 v[38:39], v[38:39], v[40:41]
	global_store_dwordx4 v[52:53], v[36:39], off offset:512
	s_nop 1
	v_lshlrev_b32_e32 v36, 16, v98
	v_and_b32_e32 v37, 0xffff0000, v98
	v_pk_add_f32 v[28:29], v[28:29], v[36:37]
	v_lshlrev_b32_e32 v36, 16, v99
	v_and_b32_e32 v37, 0xffff0000, v99
	v_pk_add_f32 v[30:31], v[30:31], v[36:37]
	global_store_dwordx4 v[52:53], v[28:31], off offset:528
	s_nop 1
	v_lshlrev_b64 v[28:29], 12, v[88:89]
	v_lshl_add_u64 v[28:29], s[4:5], 0, v[28:29]
	v_lshl_add_u64 v[36:37], v[28:29], 0, v[152:153]
	s_waitcnt vmcnt(15)
	v_lshlrev_b32_e32 v28, 16, v84
	v_and_b32_e32 v29, 0xffff0000, v84
	v_lshlrev_b32_e32 v30, 16, v85
	v_and_b32_e32 v31, 0xffff0000, v85
	v_pk_add_f32 v[28:29], v[32:33], v[28:29]
	v_pk_add_f32 v[30:31], v[34:35], v[30:31]
	global_store_dwordx4 v[36:37], v[28:31], off
	s_nop 1
	v_lshlrev_b32_e32 v28, 16, v86
	v_and_b32_e32 v29, 0xffff0000, v86
	v_pk_add_f32 v[24:25], v[24:25], v[28:29]
	v_lshlrev_b32_e32 v28, 16, v87
	v_and_b32_e32 v29, 0xffff0000, v87
	v_pk_add_f32 v[26:27], v[26:27], v[28:29]
	global_store_dwordx4 v[36:37], v[24:27], off offset:16
	s_waitcnt vmcnt(16)
	s_nop 0
	v_lshlrev_b32_e32 v24, 16, v80
	v_and_b32_e32 v25, 0xffff0000, v80
	v_pk_add_f32 v[20:21], v[20:21], v[24:25]
	v_lshlrev_b32_e32 v24, 16, v81
	v_and_b32_e32 v25, 0xffff0000, v81
	v_pk_add_f32 v[22:23], v[22:23], v[24:25]
	global_store_dwordx4 v[36:37], v[20:23], off offset:512
	s_nop 1
	v_lshlrev_b32_e32 v20, 16, v82
	v_and_b32_e32 v21, 0xffff0000, v82
	v_pk_add_f32 v[12:13], v[12:13], v[20:21]
	v_lshlrev_b32_e32 v20, 16, v83
	v_and_b32_e32 v21, 0xffff0000, v83
	v_pk_add_f32 v[14:15], v[14:15], v[20:21]
	global_store_dwordx4 v[36:37], v[12:15], off offset:528
	s_nop 1
	v_lshlrev_b64 v[12:13], 12, v[72:73]
	v_lshl_add_u64 v[12:13], s[4:5], 0, v[12:13]
	v_lshl_add_u64 v[20:21], v[12:13], 0, v[152:153]
	s_waitcnt vmcnt(13)
	v_lshlrev_b32_e32 v12, 16, v68
	v_and_b32_e32 v13, 0xffff0000, v68
	v_lshlrev_b32_e32 v14, 16, v69
	v_and_b32_e32 v15, 0xffff0000, v69
	v_pk_add_f32 v[12:13], v[16:17], v[12:13]
	v_pk_add_f32 v[14:15], v[18:19], v[14:15]
	global_store_dwordx4 v[20:21], v[12:15], off
	s_nop 1
	v_lshlrev_b32_e32 v12, 16, v70
	v_and_b32_e32 v13, 0xffff0000, v70
	v_pk_add_f32 v[8:9], v[8:9], v[12:13]
	v_lshlrev_b32_e32 v12, 16, v71
	v_and_b32_e32 v13, 0xffff0000, v71
	v_pk_add_f32 v[10:11], v[10:11], v[12:13]
	global_store_dwordx4 v[20:21], v[8:11], off offset:16
	s_waitcnt vmcnt(14)
	s_nop 0
	v_lshlrev_b32_e32 v8, 16, v64
	v_and_b32_e32 v9, 0xffff0000, v64
	v_pk_add_f32 v[4:5], v[4:5], v[8:9]
	v_lshlrev_b32_e32 v8, 16, v65
	v_and_b32_e32 v9, 0xffff0000, v65
	v_pk_add_f32 v[6:7], v[6:7], v[8:9]
	global_store_dwordx4 v[20:21], v[4:7], off offset:512
	s_nop 1
	v_lshlrev_b32_e32 v4, 16, v66
	v_and_b32_e32 v5, 0xffff0000, v66
	v_pk_add_f32 v[0:1], v[0:1], v[4:5]
	v_lshlrev_b32_e32 v4, 16, v67
	v_and_b32_e32 v5, 0xffff0000, v67
	v_pk_add_f32 v[2:3], v[2:3], v[4:5]
	global_store_dwordx4 v[20:21], v[0:3], off offset:528
	s_andn2_b64 vcc, exec, s[0:1]
	s_mov_b64 s[0:1], -1
	s_cbranch_vccnz .LBB0_1406
	s_andn2_b64 vcc, exec, s[10:11]
	s_cbranch_vccnz .LBB0_1405
	s_branch .LBB0_1405

; __global__ void __launch_bounds__(512) mega_fwd(Args a_unused) {
	.amdhsa_kernel _Z8mega_fwd4Args
		.amdhsa_group_segment_fixed_size 0
		.amdhsa_private_segment_fixed_size 0
		.amdhsa_kernarg_size 496
		.amdhsa_user_sgpr_count 2
		.amdhsa_user_sgpr_dispatch_ptr 0
		.amdhsa_user_sgpr_queue_ptr 0
		.amdhsa_user_sgpr_kernarg_segment_ptr 1
		.amdhsa_user_sgpr_dispatch_id 0
		.amdhsa_user_sgpr_kernarg_preload_length 0
		.amdhsa_user_sgpr_kernarg_preload_offset 0
		.amdhsa_user_sgpr_private_segment_size 0
		.amdhsa_uses_dynamic_stack 0
		.amdhsa_enable_private_segment 0
		.amdhsa_system_sgpr_workgroup_id_x 1
		.amdhsa_system_sgpr_workgroup_id_y 0
		.amdhsa_system_sgpr_workgroup_id_z 0
		.amdhsa_system_sgpr_workgroup_info 0
		.amdhsa_system_vgpr_workitem_id 2
		.amdhsa_next_free_vgpr 254
		.amdhsa_next_free_sgpr 99
		.amdhsa_accum_offset 256
		.amdhsa_reserve_vcc 1
		.amdhsa_float_round_mode_32 0
		.amdhsa_float_round_mode_16_64 0
		.amdhsa_float_denorm_mode_32 3
		.amdhsa_float_denorm_mode_16_64 3
		.amdhsa_dx10_clamp 1
		.amdhsa_ieee_mode 1
		.amdhsa_fp16_overflow 0
		.amdhsa_tg_split 0
		.amdhsa_exception_fp_ieee_invalid_op 0
		.amdhsa_exception_fp_denorm_src 0
		.amdhsa_exception_fp_ieee_div_zero 0
		.amdhsa_exception_fp_ieee_overflow 0
		.amdhsa_exception_fp_ieee_underflow 0
		.amdhsa_exception_fp_ieee_inexact 0
		.amdhsa_exception_int_div_zero 0
	.end_amdhsa_kernel

; __global__ void __launch_bounds__(512) mega_fwd(Args a_unused) {
amdhsa.kernels:
  - .agpr_count:     0
    .args:
      - .offset:         0
        .size:           240
        .value_kind:     by_value
      - .offset:         240
        .size:           4
        .value_kind:     hidden_block_count_x
      - .offset:         244
        .size:           4
        .value_kind:     hidden_block_count_y
      - .offset:         248
        .size:           4
        .value_kind:     hidden_block_count_z
      - .offset:         252
        .size:           2
        .value_kind:     hidden_group_size_x
      - .offset:         254
        .size:           2
        .value_kind:     hidden_group_size_y
      - .offset:         256
        .size:           2
        .value_kind:     hidden_group_size_z
      - .offset:         258
        .size:           2
        .value_kind:     hidden_remainder_x
      - .offset:         260
        .size:           2
        .value_kind:     hidden_remainder_y
      - .offset:         262
        .size:           2
        .value_kind:     hidden_remainder_z
      - .offset:         280
        .size:           8
        .value_kind:     hidden_global_offset_x
      - .offset:         288
        .size:           8
        .value_kind:     hidden_global_offset_y
      - .offset:         296
        .size:           8
        .value_kind:     hidden_global_offset_z
      - .offset:         304
        .size:           2
        .value_kind:     hidden_grid_dims
      - .offset:         328
        .size:           8
        .value_kind:     hidden_multigrid_sync_arg
      - .offset:         360
        .size:           4
        .value_kind:     hidden_dynamic_lds_size
    .group_segment_fixed_size: 0
    .kernarg_segment_align: 8
    .kernarg_segment_size: 496
    .language:       OpenCL C
    .language_version:
      - 2
      - 0
    .max_flat_workgroup_size: 512
    .name:           _Z8mega_fwd4Args
    .private_segment_fixed_size: 0
    .sgpr_count:     105
    .sgpr_spill_count: 45
    .symbol:         _Z8mega_fwd4Args.kd
    .uniform_work_group_size: 1
    .uses_dynamic_stack: false
    .vgpr_count:     254
    .vgpr_spill_count: 0
    .wavefront_size: 64
